# merge GEMM epilogues: gate / partial-sum operand loads issued ahead (16 up front in MergeA, groups of 7 in MergeB) instead of one load+full wait per row group
# speedup vs baseline: 1.0300x; 1.0183x over previous
; #define PG8_STAGE(bufoff, gbase, voff) do { const char* _gb = (const char*)(gbase); asm volatile("" : "+s"(_gb)); _Pragma("unroll") for (int _i = 0; _i < 2; ++_i) \
;         __builtin_amdgcn_global_load_lds((const unsigned*)(_gb + (voff)[_i]), (LAS unsigned*)(lds + (bufoff) + ldsw + _i * 8192), 16, 0, 0); } while (0)
; #define PG8_STAGEA(bufoff, gbase, h_, usenext) do { if (GATHER) { unsigned go_[2] = {(usenext) ? gnxt[h_][0] : gcur[h_][0], (usenext) ? gnxt[h_][1] : gcur[h_][1]}; PG8_STAGE(bufoff, gbase, go_); } else PG8_STAGE(bufoff, (gbase) + (h_) * hstepA, voffA); } while (0)
; #define PG8_LDA(dst, b, h) do { _Pragma("unroll") for (int m = 0; m < 4; ++m) _Pragma("unroll") for (int k = 0; k < 2; ++k) dst[m][k] = *(const LAS bf16x8*)(lds + PG8_SA(b, h) + aoff + m * 2048 + k * 1024); } while (0)
; #define PG8_LDB(dst, b, h) do { _Pragma("unroll") for (int n = 0; n < 2; ++n) _Pragma("unroll") for (int k = 0; k < 2; ++k) dst[n][k] = *(const LAS bf16x8*)(lds + PG8_SB(b, h) + boff + n * 2048 + k * 1024); } while (0)
; #define PG8_WAIT_L(n) asm volatile("s_waitcnt lgkmcnt(" #n ")" ::: "memory")
; #define PG8_BAR __builtin_amdgcn_s_barrier()
; #define PG8_SCHED __builtin_amdgcn_sched_barrier(0)
; template <class Epi, class Sched, bool GATHER = false>
; __device__ __forceinline__ void gemm_phase(LAS unsigned char* lds, const int K, const int lda, const Sched& S, const Epi& E, const int wid_s, const LAS int* rowoff = nullptr) {
;     ...
;             const bool last = (t == nt - 2);
;             const char* a1 = cA + (size_t)(t + 1) * kstep;
;             const char* a2 = last ? nA : cA + (size_t)(t + 2) * kstep; const char* b2 = last ? nB : cB + (size_t)(t + 2) * kstep;
;             const char* a3 = a2 + kstep; const char* b3 = b2 + kstep;
;             PG8_LDB(B0, 0, 0); PG8_SCHED; PG8_LDA(At, 0, 0); PG8_STAGEA(PG8_SA(1, 1), a1, 1, false);
;             PG8_WAIT_L(8); PG8_BAR; PG8_WAIT_L(0); PG8_MMA(0, 0, At, B0); PG8_BAR; PG8_SCHED;
;             PG8_LDB(B1, 0, 1); PG8_STAGE(PG8_SB(0, 0), b2, voffB);
;             PG8_BAR; PG8_WAIT_L(0); PG8_MMA(0, 1, At, B1); PG8_BAR;
;             PG8_LDA(At, 0, 1); PG8_STAGEA(PG8_SA(0, 0), a2, 0, last);
;             PG8_BAR; PG8_WAIT_L(0); PG8_MMA(1, 0, At, B0); PG8_BAR; PG8_SCHED;
.LBB0_480:
	s_add_u32 s20, s18, 0x100
	s_addc_u32 s21, s19, 0
	s_cmp_eq_u32 s41, 4
	s_cselect_b32 s24, s12, s20
	s_cselect_b32 s25, s13, s21
	s_cselect_b32 s2, s14, s7
	s_cselect_b32 s3, s15, s40
	s_add_u32 s22, s24, 0x80
	s_addc_u32 s23, s25, 0
	s_add_i32 s42, 0, 0x10000
	v_add_u32_e32 v138, s42, v141
	ds_read_b128 v[134:137], v138
	ds_read_b128 v[144:147], v138 offset:1024
	ds_read_b128 v[148:151], v138 offset:2048
	ds_read_b128 v[152:155], v138 offset:3072
	s_add_u32 s18, s18, 0x40080
	s_addc_u32 s19, s19, 0
	ds_read_b128 v[156:159], v143
	ds_read_b128 v[160:163], v143 offset:1024
	ds_read_b128 v[164:167], v143 offset:2048
	ds_read_b128 v[168:171], v143 offset:3072
	ds_read_b128 v[172:175], v143 offset:4096
	ds_read_b128 v[176:179], v143 offset:5120
	ds_read_b128 v[180:183], v143 offset:6144
	ds_read_b128 v[184:187], v143 offset:7168
	s_add_i32 m0, s17, 0xc000
	v_lshl_add_u64 v[138:139], s[18:19], 0, v[132:133]
	global_load_lds_dwordx4 v[138:139], off
	v_lshl_add_u64 v[138:139], s[18:19], 0, v[130:131]
	s_add_i32 m0, s17, 0xe000
	s_nop 0
	global_load_lds_dwordx4 v[138:139], off
	s_waitcnt lgkmcnt(8)
	s_barrier
	s_waitcnt lgkmcnt(0)
	s_setprio 1
	s_waitcnt lgkmcnt(0)
	v_mfma_f32_16x16x32_bf16 v[124:127], v[134:137], v[156:159], v[124:127]
	v_mfma_f32_16x16x32_bf16 v[120:123], v[148:151], v[156:159], v[120:123]
	v_mfma_f32_16x16x32_bf16 v[116:119], v[134:137], v[164:167], v[116:119]
	v_mfma_f32_16x16x32_bf16 v[112:115], v[148:151], v[164:167], v[112:115]
	v_mfma_f32_16x16x32_bf16 v[108:111], v[134:137], v[172:175], v[108:111]
	v_mfma_f32_16x16x32_bf16 v[104:107], v[148:151], v[172:175], v[104:107]
	v_mfma_f32_16x16x32_bf16 v[100:103], v[134:137], v[180:183], v[100:103]
	v_mfma_f32_16x16x32_bf16 v[96:99], v[148:151], v[180:183], v[96:99]
	v_mfma_f32_16x16x32_bf16 v[124:127], v[144:147], v[160:163], v[124:127]
	v_mfma_f32_16x16x32_bf16 v[120:123], v[152:155], v[160:163], v[120:123]
	v_mfma_f32_16x16x32_bf16 v[116:119], v[144:147], v[168:171], v[116:119]
	v_mfma_f32_16x16x32_bf16 v[112:115], v[152:155], v[168:171], v[112:115]
	v_mfma_f32_16x16x32_bf16 v[108:111], v[144:147], v[176:179], v[108:111]
	v_mfma_f32_16x16x32_bf16 v[104:107], v[152:155], v[176:179], v[104:107]
	v_mfma_f32_16x16x32_bf16 v[100:103], v[144:147], v[184:187], v[100:103]
	v_mfma_f32_16x16x32_bf16 v[96:99], v[152:155], v[184:187], v[96:99]
	s_setprio 0
	s_barrier
	s_add_i32 s43, 0, 0x14000
	v_add_u32_e32 v138, s43, v141
	s_mov_b64 s[18:19], s[2:3]
	s_add_i32 s42, s42, s33
	ds_read_b128 v[188:191], v138
	ds_read_b128 v[192:195], v138 offset:1024
	ds_read_b128 v[196:199], v138 offset:2048
	ds_read_b128 v[206:209], v138 offset:3072
	s_mov_b32 m0, s42
	v_lshl_add_u64 v[138:139], s[18:19], 0, v[200:201]
	global_load_lds_dwordx4 v[138:139], off
	v_lshl_add_u64 v[138:139], s[18:19], 0, v[128:129]
	s_add_i32 m0, s42, 0x2000
	s_nop 0
	global_load_lds_dwordx4 v[138:139], off
	s_barrier
	s_waitcnt lgkmcnt(0)
	s_setprio 1
	s_waitcnt lgkmcnt(0)
	v_mfma_f32_16x16x32_bf16 v[60:63], v[188:191], v[156:159], v[60:63]
	v_mfma_f32_16x16x32_bf16 v[56:59], v[196:199], v[156:159], v[56:59]
	v_mfma_f32_16x16x32_bf16 v[52:55], v[188:191], v[164:167], v[52:55]
	v_mfma_f32_16x16x32_bf16 v[48:51], v[196:199], v[164:167], v[48:51]
	v_mfma_f32_16x16x32_bf16 v[44:47], v[188:191], v[172:175], v[44:47]
	v_mfma_f32_16x16x32_bf16 v[40:43], v[196:199], v[172:175], v[40:43]
	v_mfma_f32_16x16x32_bf16 v[36:39], v[188:191], v[180:183], v[36:39]
	v_mfma_f32_16x16x32_bf16 v[32:35], v[196:199], v[180:183], v[32:35]
	v_mfma_f32_16x16x32_bf16 v[60:63], v[192:195], v[160:163], v[60:63]
	v_mfma_f32_16x16x32_bf16 v[56:59], v[206:209], v[160:163], v[56:59]
	v_mfma_f32_16x16x32_bf16 v[52:55], v[192:195], v[168:171], v[52:55]
	v_mfma_f32_16x16x32_bf16 v[48:51], v[206:209], v[168:171], v[48:51]
	v_mfma_f32_16x16x32_bf16 v[44:47], v[192:195], v[176:179], v[44:47]
	v_mfma_f32_16x16x32_bf16 v[40:43], v[206:209], v[176:179], v[40:43]
	v_mfma_f32_16x16x32_bf16 v[36:39], v[192:195], v[184:187], v[36:39]
	v_mfma_f32_16x16x32_bf16 v[32:35], v[206:209], v[184:187], v[32:35]
	s_setprio 0
	s_mov_b64 s[18:19], s[24:25]
	s_mov_b32 m0, s17
	s_barrier
	ds_read_b128 v[156:159], v143 offset:16384
	ds_read_b128 v[160:163], v143 offset:17408
	ds_read_b128 v[164:167], v143 offset:18432
	ds_read_b128 v[168:171], v143 offset:19456
	ds_read_b128 v[172:175], v143 offset:20480
	ds_read_b128 v[176:179], v143 offset:21504
	ds_read_b128 v[180:183], v143 offset:22528
	ds_read_b128 v[184:187], v143 offset:23552
	s_nop 0
	v_lshl_add_u64 v[138:139], s[18:19], 0, v[132:133]
	global_load_lds_dwordx4 v[138:139], off
	v_lshl_add_u64 v[138:139], s[18:19], 0, v[130:131]
	s_mov_b32 m0, s31
	s_nop 0
	global_load_lds_dwordx4 v[138:139], off
	s_barrier
	s_waitcnt lgkmcnt(0)
	s_setprio 1
	s_waitcnt lgkmcnt(0)
	v_mfma_f32_16x16x32_bf16 v[92:95], v[134:137], v[156:159], v[92:95]
	v_mfma_f32_16x16x32_bf16 v[88:91], v[148:151], v[156:159], v[88:91]
	v_mfma_f32_16x16x32_bf16 v[84:87], v[134:137], v[164:167], v[84:87]
	v_mfma_f32_16x16x32_bf16 v[80:83], v[148:151], v[164:167], v[80:83]
	v_mfma_f32_16x16x32_bf16 v[76:79], v[134:137], v[172:175], v[76:79]
	v_mfma_f32_16x16x32_bf16 v[72:75], v[148:151], v[172:175], v[72:75]
	v_mfma_f32_16x16x32_bf16 v[68:71], v[134:137], v[180:183], v[68:71]
	v_mfma_f32_16x16x32_bf16 v[64:67], v[148:151], v[180:183], v[64:67]
	v_mfma_f32_16x16x32_bf16 v[92:95], v[144:147], v[160:163], v[92:95]
	v_mfma_f32_16x16x32_bf16 v[88:91], v[152:155], v[160:163], v[88:91]
	v_mfma_f32_16x16x32_bf16 v[84:87], v[144:147], v[168:171], v[84:87]
	v_mfma_f32_16x16x32_bf16 v[80:83], v[152:155], v[168:171], v[80:83]
	v_mfma_f32_16x16x32_bf16 v[76:79], v[144:147], v[176:179], v[76:79]
	v_mfma_f32_16x16x32_bf16 v[72:75], v[152:155], v[176:179], v[72:75]
	v_mfma_f32_16x16x32_bf16 v[68:71], v[144:147], v[184:187], v[68:71]
	v_mfma_f32_16x16x32_bf16 v[64:67], v[152:155], v[184:187], v[64:67]
	s_setprio 0
	s_barrier
; #define PG8_STAGE(bufoff, gbase, voff) do { const char* _gb = (const char*)(gbase); asm volatile("" : "+s"(_gb)); _Pragma("unroll") for (int _i = 0; _i < 2; ++_i) \
;         __builtin_amdgcn_global_load_lds((const unsigned*)(_gb + (voff)[_i]), (LAS unsigned*)(lds + (bufoff) + ldsw + _i * 8192), 16, 0, 0); } while (0)
; #define PG8_STAGEA(bufoff, gbase, h_, usenext) do { if (GATHER) { unsigned go_[2] = {(usenext) ? gnxt[h_][0] : gcur[h_][0], (usenext) ? gnxt[h_][1] : gcur[h_][1]}; PG8_STAGE(bufoff, gbase, go_); } else PG8_STAGE(bufoff, (gbase) + (h_) * hstepA, voffA); } while (0)
; #define PG8_LDA(dst, b, h) do { _Pragma("unroll") for (int m = 0; m < 4; ++m) _Pragma("unroll") for (int k = 0; k < 2; ++k) dst[m][k] = *(const LAS bf16x8*)(lds + PG8_SA(b, h) + aoff + m * 2048 + k * 1024); } while (0)
; #define PG8_LDB(dst, b, h) do { _Pragma("unroll") for (int n = 0; n < 2; ++n) _Pragma("unroll") for (int k = 0; k < 2; ++k) dst[n][k] = *(const LAS bf16x8*)(lds + PG8_SB(b, h) + boff + n * 2048 + k * 1024); } while (0)
; #define PG8_MMA(ai, bj, At, Bt) do { __builtin_amdgcn_s_setprio(1); _Pragma("unroll") for (int m = 0; m < 4; ++m) _Pragma("unroll") for (int n = 0; n < 2; ++n) _Pragma("unroll") for (int k = 0; k < 2; ++k) \
;         acc[ai][bj][m][n] = __builtin_amdgcn_mfma_f32_16x16x32_bf16(Bt[n][k], At[m][k], acc[ai][bj][m][n], 0, 0, 0); __builtin_amdgcn_s_setprio(0); } while (0)
; #define PG8_WAIT_V(n) asm volatile("s_waitcnt vmcnt(" #n ")" ::: "memory")
; #define PG8_WAIT_L(n) asm volatile("s_waitcnt lgkmcnt(" #n ")" ::: "memory")
; #define PG8_BAR __builtin_amdgcn_s_barrier()
; #define PG8_SCHED __builtin_amdgcn_sched_barrier(0)
; template <class Epi, class Sched, bool GATHER = false>
; __device__ __forceinline__ void gemm_phase(LAS unsigned char* lds, const int K, const int lda, const Sched& S, const Epi& E, const int wid_s, const LAS int* rowoff = nullptr) {
;     ...
;             PG8_STAGE(PG8_SB(0, 1), b2 + hstepB, voffB);
;             PG8_WAIT_V(6); PG8_BAR; PG8_MMA(1, 1, At, B1); PG8_BAR;
;             PG8_LDB(B0, 1, 0); PG8_SCHED; PG8_LDA(At, 1, 0); PG8_STAGEA(PG8_SA(0, 1), a2, 1, last);
;             PG8_WAIT_L(8); PG8_BAR; PG8_WAIT_L(0); PG8_MMA(0, 0, At, B0); PG8_BAR; PG8_SCHED;
;             PG8_LDB(B1, 1, 1); PG8_STAGE(PG8_SB(1, 0), b3, voffB);
;             PG8_BAR; PG8_WAIT_L(0); PG8_MMA(0, 1, At, B1); PG8_BAR;
	s_add_u32 s18, s2, 0x20000
	s_addc_u32 s19, s3, 0
	s_add_i32 s42, s43, s33
	s_mov_b32 m0, s42
	v_lshl_add_u64 v[134:135], s[18:19], 0, v[200:201]
	global_load_lds_dwordx4 v[134:135], off
	v_lshl_add_u64 v[134:135], s[18:19], 0, v[128:129]
	s_add_i32 m0, s42, 0x2000
	s_nop 0
	global_load_lds_dwordx4 v[134:135], off
	s_waitcnt vmcnt(6)
	s_barrier
	s_setprio 1
	v_mfma_f32_16x16x32_bf16 v[28:31], v[188:191], v[156:159], v[28:31]
	v_mfma_f32_16x16x32_bf16 v[24:27], v[196:199], v[156:159], v[24:27]
	v_mfma_f32_16x16x32_bf16 v[20:23], v[188:191], v[164:167], v[20:23]
	v_mfma_f32_16x16x32_bf16 v[16:19], v[196:199], v[164:167], v[16:19]
	v_mfma_f32_16x16x32_bf16 v[12:15], v[188:191], v[172:175], v[12:15]
	v_mfma_f32_16x16x32_bf16 v[8:11], v[196:199], v[172:175], v[8:11]
	v_mfma_f32_16x16x32_bf16 v[4:7], v[188:191], v[180:183], v[4:7]
	v_mfma_f32_16x16x32_bf16 v[0:3], v[196:199], v[180:183], v[0:3]
	v_mfma_f32_16x16x32_bf16 v[28:31], v[192:195], v[160:163], v[28:31]
	v_mfma_f32_16x16x32_bf16 v[24:27], v[206:209], v[160:163], v[24:27]
	v_mfma_f32_16x16x32_bf16 v[20:23], v[192:195], v[168:171], v[20:23]
	v_mfma_f32_16x16x32_bf16 v[16:19], v[206:209], v[168:171], v[16:19]
	v_mfma_f32_16x16x32_bf16 v[12:15], v[192:195], v[176:179], v[12:15]
	v_mfma_f32_16x16x32_bf16 v[8:11], v[206:209], v[176:179], v[8:11]
	v_mfma_f32_16x16x32_bf16 v[4:7], v[192:195], v[184:187], v[4:7]
	v_mfma_f32_16x16x32_bf16 v[0:3], v[206:209], v[184:187], v[0:3]
	s_setprio 0
	s_add_i32 s42, 0, 0x18000
	v_add_u32_e32 v138, s42, v141
	s_barrier
	ds_read_b128 v[134:137], v138
	ds_read_b128 v[144:147], v138 offset:1024
	ds_read_b128 v[148:151], v138 offset:2048
	ds_read_b128 v[152:155], v138 offset:3072
	s_add_u32 s18, s24, 0x40000
	s_addc_u32 s19, s25, 0
	s_mov_b32 m0, s34
	ds_read_b128 v[156:159], v143 offset:32768
	ds_read_b128 v[160:163], v143 offset:33792
	ds_read_b128 v[164:167], v143 offset:34816
	ds_read_b128 v[168:171], v143 offset:35840
	ds_read_b128 v[172:175], v143 offset:36864
	ds_read_b128 v[176:179], v143 offset:37888
	ds_read_b128 v[180:183], v143 offset:38912
	ds_read_b128 v[184:187], v143 offset:39936
	s_nop 0
	v_lshl_add_u64 v[138:139], s[18:19], 0, v[132:133]
	global_load_lds_dwordx4 v[138:139], off
	v_lshl_add_u64 v[138:139], s[18:19], 0, v[130:131]
	s_mov_b32 m0, s35
	s_nop 0
	global_load_lds_dwordx4 v[138:139], off
	s_waitcnt lgkmcnt(8)
	s_barrier
	s_waitcnt lgkmcnt(0)
	s_setprio 1
	s_waitcnt lgkmcnt(0)
	v_mfma_f32_16x16x32_bf16 v[124:127], v[134:137], v[156:159], v[124:127]
	v_mfma_f32_16x16x32_bf16 v[120:123], v[148:151], v[156:159], v[120:123]
	v_mfma_f32_16x16x32_bf16 v[116:119], v[134:137], v[164:167], v[116:119]
	v_mfma_f32_16x16x32_bf16 v[112:115], v[148:151], v[164:167], v[112:115]
	v_mfma_f32_16x16x32_bf16 v[108:111], v[134:137], v[172:175], v[108:111]
	v_mfma_f32_16x16x32_bf16 v[104:107], v[148:151], v[172:175], v[104:107]
	v_mfma_f32_16x16x32_bf16 v[100:103], v[134:137], v[180:183], v[100:103]
	v_mfma_f32_16x16x32_bf16 v[96:99], v[148:151], v[180:183], v[96:99]
	v_mfma_f32_16x16x32_bf16 v[124:127], v[144:147], v[160:163], v[124:127]
	v_mfma_f32_16x16x32_bf16 v[120:123], v[152:155], v[160:163], v[120:123]
	v_mfma_f32_16x16x32_bf16 v[116:119], v[144:147], v[168:171], v[116:119]
	v_mfma_f32_16x16x32_bf16 v[112:115], v[152:155], v[168:171], v[112:115]
	v_mfma_f32_16x16x32_bf16 v[108:111], v[144:147], v[176:179], v[108:111]
	v_mfma_f32_16x16x32_bf16 v[104:107], v[152:155], v[176:179], v[104:107]
	v_mfma_f32_16x16x32_bf16 v[100:103], v[144:147], v[184:187], v[100:103]
	v_mfma_f32_16x16x32_bf16 v[96:99], v[152:155], v[184:187], v[96:99]
	s_setprio 0
	s_barrier
	s_add_i32 s24, 0, 0x1c000
	s_add_u32 s18, s2, 0x80
	v_add_u32_e32 v138, s24, v141
	s_addc_u32 s19, s3, 0
	s_add_i32 s25, s42, s33
	ds_read_b128 v[188:191], v138
	ds_read_b128 v[192:195], v138 offset:1024
	ds_read_b128 v[196:199], v138 offset:2048
	ds_read_b128 v[206:209], v138 offset:3072
	s_mov_b32 m0, s25
	v_lshl_add_u64 v[138:139], s[18:19], 0, v[200:201]
	global_load_lds_dwordx4 v[138:139], off
	v_lshl_add_u64 v[138:139], s[18:19], 0, v[128:129]
	s_add_i32 m0, s25, 0x2000
	s_nop 0
	global_load_lds_dwordx4 v[138:139], off
	s_barrier
	s_waitcnt lgkmcnt(0)
	s_setprio 1
	s_waitcnt lgkmcnt(0)
	v_mfma_f32_16x16x32_bf16 v[60:63], v[188:191], v[156:159], v[60:63]
	v_mfma_f32_16x16x32_bf16 v[56:59], v[196:199], v[156:159], v[56:59]
	v_mfma_f32_16x16x32_bf16 v[52:55], v[188:191], v[164:167], v[52:55]
	v_mfma_f32_16x16x32_bf16 v[48:51], v[196:199], v[164:167], v[48:51]
	v_mfma_f32_16x16x32_bf16 v[44:47], v[188:191], v[172:175], v[44:47]
	v_mfma_f32_16x16x32_bf16 v[40:43], v[196:199], v[172:175], v[40:43]
	v_mfma_f32_16x16x32_bf16 v[36:39], v[188:191], v[180:183], v[36:39]
	v_mfma_f32_16x16x32_bf16 v[32:35], v[196:199], v[180:183], v[32:35]
	v_mfma_f32_16x16x32_bf16 v[60:63], v[192:195], v[160:163], v[60:63]
	v_mfma_f32_16x16x32_bf16 v[56:59], v[206:209], v[160:163], v[56:59]
	v_mfma_f32_16x16x32_bf16 v[52:55], v[192:195], v[168:171], v[52:55]
	v_mfma_f32_16x16x32_bf16 v[48:51], v[206:209], v[168:171], v[48:51]
	v_mfma_f32_16x16x32_bf16 v[44:47], v[192:195], v[176:179], v[44:47]
	v_mfma_f32_16x16x32_bf16 v[40:43], v[206:209], v[176:179], v[40:43]
	v_mfma_f32_16x16x32_bf16 v[36:39], v[192:195], v[184:187], v[36:39]
	v_mfma_f32_16x16x32_bf16 v[32:35], v[206:209], v[184:187], v[32:35]
	s_setprio 0
	s_mov_b32 m0, s36
	s_barrier
; __device__ __forceinline__ float bf_lo(unsigned u) { return __uint_as_float(u << 16); }
; __device__ __forceinline__ float bf_hi(unsigned u) { return __uint_as_float(u & 0xffff0000u); }
; __device__ __forceinline__ float sigmoidf_(float x) { return frcp(1.0f + fexp2(-1.4426950408889634f * x)); }
; #define PG8_STAGE(bufoff, gbase, voff) do { const char* _gb = (const char*)(gbase); asm volatile("" : "+s"(_gb)); _Pragma("unroll") for (int _i = 0; _i < 2; ++_i) \
;         __builtin_amdgcn_global_load_lds((const unsigned*)(_gb + (voff)[_i]), (LAS unsigned*)(lds + (bufoff) + ldsw + _i * 8192), 16, 0, 0); } while (0)
; #define PG8_STAGEA(bufoff, gbase, h_, usenext) do { if (GATHER) { unsigned go_[2] = {(usenext) ? gnxt[h_][0] : gcur[h_][0], (usenext) ? gnxt[h_][1] : gcur[h_][1]}; PG8_STAGE(bufoff, gbase, go_); } else PG8_STAGE(bufoff, (gbase) + (h_) * hstepA, voffA); } while (0)
; #define PG8_LDA(dst, b, h) do { _Pragma("unroll") for (int m = 0; m < 4; ++m) _Pragma("unroll") for (int k = 0; k < 2; ++k) dst[m][k] = *(const LAS bf16x8*)(lds + PG8_SA(b, h) + aoff + m * 2048 + k * 1024); } while (0)
; #define PG8_WAIT_V(n) asm volatile("s_waitcnt vmcnt(" #n ")" ::: "memory")
; #define PG8_WAIT_L(n) asm volatile("s_waitcnt lgkmcnt(" #n ")" ::: "memory")
; #define PG8_BAR __builtin_amdgcn_s_barrier()
; #define PG8_SCHED __builtin_amdgcn_sched_barrier(0)
; template <class Epi, class Sched, bool GATHER = false>
; __device__ __forceinline__ void gemm_phase(LAS unsigned char* lds, const int K, const int lda, const Sched& S, const Epi& E, const int wid_s, const LAS int* rowoff = nullptr) {
;     ...
;             PG8_LDA(At, 1, 1); PG8_STAGEA(PG8_SA(1, 0), a3, 0, last);
;             PG8_BAR; PG8_WAIT_L(0); PG8_MMA(1, 0, At, B0); PG8_BAR; PG8_SCHED;
;             PG8_STAGE(PG8_SB(1, 1), b3 + hstepB, voffB);
;             PG8_WAIT_V(6); PG8_BAR; PG8_MMA(1, 1, At, B1); PG8_BAR;
;     __device__ __forceinline__ void operator()(Acc& acc, const Unit& u, int wr, int wc, int fr, int fq) const {
;         EPI_FOR_BJ { const int c0 = EPI_COL(u, bj);
;             EPI_FOR_AM { int r = EPI_ROW(u, ai, m); EPI_PIN(r);
;                 const u32x4 ga = *(const u32x4*)(P + (size_t)r * INWP + OFF_GA + c0);
; #pragma unroll
;                 for (int e = 0; e < 8; ++e) acc[ai][bj][m][e >> 2][e & 3] *= sigmoidf_((e & 1) ? bf_hi(ga[e >> 1]) : bf_lo(ga[e >> 1]));
	ds_read_b128 v[156:159], v143 offset:49152
	ds_read_b128 v[160:163], v143 offset:50176
	ds_read_b128 v[164:167], v143 offset:51200
	ds_read_b128 v[168:171], v143 offset:52224
	ds_read_b128 v[172:175], v143 offset:53248
	ds_read_b128 v[176:179], v143 offset:54272
	ds_read_b128 v[180:183], v143 offset:55296
	ds_read_b128 v[184:187], v143 offset:56320
	s_nop 0
	v_lshl_add_u64 v[138:139], s[22:23], 0, v[132:133]
	global_load_lds_dwordx4 v[138:139], off
	v_lshl_add_u64 v[138:139], s[22:23], 0, v[130:131]
	s_mov_b32 m0, s37
	s_nop 0
	global_load_lds_dwordx4 v[138:139], off
	s_barrier
	s_waitcnt lgkmcnt(0)
	s_setprio 1
	s_waitcnt lgkmcnt(0)
	v_mfma_f32_16x16x32_bf16 v[92:95], v[134:137], v[156:159], v[92:95]
	v_mfma_f32_16x16x32_bf16 v[88:91], v[148:151], v[156:159], v[88:91]
	v_mfma_f32_16x16x32_bf16 v[84:87], v[134:137], v[164:167], v[84:87]
	v_mfma_f32_16x16x32_bf16 v[80:83], v[148:151], v[164:167], v[80:83]
	v_mfma_f32_16x16x32_bf16 v[76:79], v[134:137], v[172:175], v[76:79]
	v_mfma_f32_16x16x32_bf16 v[72:75], v[148:151], v[172:175], v[72:75]
	v_mfma_f32_16x16x32_bf16 v[68:71], v[134:137], v[180:183], v[68:71]
	v_mfma_f32_16x16x32_bf16 v[64:67], v[148:151], v[180:183], v[64:67]
	v_mfma_f32_16x16x32_bf16 v[92:95], v[144:147], v[160:163], v[92:95]
	v_mfma_f32_16x16x32_bf16 v[88:91], v[152:155], v[160:163], v[88:91]
	v_mfma_f32_16x16x32_bf16 v[84:87], v[144:147], v[168:171], v[84:87]
	v_mfma_f32_16x16x32_bf16 v[80:83], v[152:155], v[168:171], v[80:83]
	v_mfma_f32_16x16x32_bf16 v[76:79], v[144:147], v[176:179], v[76:79]
	v_mfma_f32_16x16x32_bf16 v[72:75], v[152:155], v[176:179], v[72:75]
	v_mfma_f32_16x16x32_bf16 v[68:71], v[144:147], v[184:187], v[68:71]
	v_mfma_f32_16x16x32_bf16 v[64:67], v[152:155], v[184:187], v[64:67]
	s_setprio 0
	s_barrier
	s_add_u32 s2, s2, 0x20080
	s_addc_u32 s3, s3, 0
	s_add_i32 s18, s24, s33
	s_mov_b32 m0, s18
	v_lshl_add_u64 v[134:135], s[2:3], 0, v[200:201]
	global_load_lds_dwordx4 v[134:135], off
	v_lshl_add_u64 v[134:135], s[2:3], 0, v[128:129]
	s_add_i32 m0, s18, 0x2000
	s_nop 0
	global_load_lds_dwordx4 v[134:135], off
	s_waitcnt vmcnt(6)
	s_barrier
	s_setprio 1
	v_mfma_f32_16x16x32_bf16 v[28:31], v[188:191], v[156:159], v[28:31]
	v_mfma_f32_16x16x32_bf16 v[24:27], v[196:199], v[156:159], v[24:27]
	v_mfma_f32_16x16x32_bf16 v[20:23], v[188:191], v[164:167], v[20:23]
	v_mfma_f32_16x16x32_bf16 v[16:19], v[196:199], v[164:167], v[16:19]
	v_mfma_f32_16x16x32_bf16 v[12:15], v[188:191], v[172:175], v[12:15]
	v_mfma_f32_16x16x32_bf16 v[8:11], v[196:199], v[172:175], v[8:11]
	v_mfma_f32_16x16x32_bf16 v[4:7], v[188:191], v[180:183], v[4:7]
	v_mfma_f32_16x16x32_bf16 v[0:3], v[196:199], v[180:183], v[0:3]
	v_mfma_f32_16x16x32_bf16 v[28:31], v[192:195], v[160:163], v[28:31]
	v_mfma_f32_16x16x32_bf16 v[24:27], v[206:209], v[160:163], v[24:27]
	v_mfma_f32_16x16x32_bf16 v[20:23], v[192:195], v[168:171], v[20:23]
	v_mfma_f32_16x16x32_bf16 v[16:19], v[206:209], v[168:171], v[16:19]
	v_mfma_f32_16x16x32_bf16 v[12:15], v[192:195], v[176:179], v[12:15]
	v_mfma_f32_16x16x32_bf16 v[8:11], v[206:209], v[176:179], v[8:11]
	v_mfma_f32_16x16x32_bf16 v[4:7], v[192:195], v[184:187], v[4:7]
	v_mfma_f32_16x16x32_bf16 v[0:3], v[206:209], v[184:187], v[0:3]
	s_setprio 0
	s_add_i32 s41, s41, 2
	s_add_u32 s7, s7, 0x100
	s_addc_u32 s40, s40, 0
	s_cmp_gt_u32 s41, 5
	s_mov_b64 s[18:19], s[20:21]
	s_barrier
	s_cbranch_scc0 .LBB0_480
	v_lshl_add_u32 v136, s16, 8, v140
	v_mov_b32_e32 v134, v136
	v_lshl_or_b32 v138, s39, 8, v142
	v_readlane_b32 s2, v249, 34
	v_ashrrev_i32_e32 v135, 31, v134
	v_ashrrev_i32_e32 v139, 31, v138
	v_lshlrev_b64 v[134:135], 13, v[134:135]
	v_readlane_b32 s3, v249, 35
	s_nop 1
	v_lshl_add_u64 v[144:145], s[2:3], 0, v[134:135]
	v_lshlrev_b64 v[134:135], 1, v[138:139]
	v_lshl_add_u64 v[144:145], v[144:145], 0, v[134:135]
	v_mov_b32_e32 v198, v144
	v_mov_b32_e32 v199, v145
	s_mov_b32 s87, 0
	s_mov_b32 s86, 0x0
	v_lshl_add_u64 v[196:197], v[198:199], 0, s[86:87]
	global_load_dwordx4 v[156:159], v[196:197], off offset:3904
	s_mov_b32 s86, 0x20000
	v_lshl_add_u64 v[196:197], v[198:199], 0, s[86:87]
	global_load_dwordx4 v[160:163], v[196:197], off offset:3904
	s_mov_b32 s86, 0x40000
	v_lshl_add_u64 v[196:197], v[198:199], 0, s[86:87]
	global_load_dwordx4 v[164:167], v[196:197], off offset:3904
	s_mov_b32 s86, 0x60000
	v_lshl_add_u64 v[196:197], v[198:199], 0, s[86:87]
	global_load_dwordx4 v[168:171], v[196:197], off offset:3904
	s_mov_b32 s86, 0x100000
	v_lshl_add_u64 v[196:197], v[198:199], 0, s[86:87]
	global_load_dwordx4 v[172:175], v[196:197], off offset:3904
	s_mov_b32 s86, 0x120000
	v_lshl_add_u64 v[196:197], v[198:199], 0, s[86:87]
	global_load_dwordx4 v[176:179], v[196:197], off offset:3904
	s_mov_b32 s86, 0x140000
	v_lshl_add_u64 v[196:197], v[198:199], 0, s[86:87]
	global_load_dwordx4 v[180:183], v[196:197], off offset:3904
	s_mov_b32 s86, 0x160000
	v_lshl_add_u64 v[196:197], v[198:199], 0, s[86:87]
	global_load_dwordx4 v[184:187], v[196:197], off offset:3904
	s_mov_b32 s86, 0x100
	v_lshl_add_u64 v[196:197], v[198:199], 0, s[86:87]
	global_load_dwordx4 v[188:191], v[196:197], off offset:3904
	s_mov_b32 s86, 0x20100
	v_lshl_add_u64 v[196:197], v[198:199], 0, s[86:87]
	global_load_dwordx4 v[192:195], v[196:197], off offset:3904
	s_mov_b32 s86, 0x40100
	v_lshl_add_u64 v[196:197], v[198:199], 0, s[86:87]
	global_load_dwordx4 v[206:209], v[196:197], off offset:3904
	s_mov_b32 s86, 0x60100
	v_lshl_add_u64 v[196:197], v[198:199], 0, s[86:87]
	global_load_dwordx4 v[210:213], v[196:197], off offset:3904
	s_mov_b32 s86, 0x100100
	v_lshl_add_u64 v[196:197], v[198:199], 0, s[86:87]
	global_load_dwordx4 v[214:217], v[196:197], off offset:3904
	s_mov_b32 s86, 0x120100
	v_lshl_add_u64 v[196:197], v[198:199], 0, s[86:87]
	global_load_dwordx4 v[218:221], v[196:197], off offset:3904
	s_mov_b32 s86, 0x140100
	v_lshl_add_u64 v[196:197], v[198:199], 0, s[86:87]
	global_load_dwordx4 v[222:225], v[196:197], off offset:3904
	s_mov_b32 s86, 0x160100
	v_lshl_add_u64 v[196:197], v[198:199], 0, s[86:87]
	global_load_dwordx4 v[226:229], v[196:197], off offset:3904
	s_waitcnt vmcnt(15)
; __device__ __forceinline__ float bf_lo(unsigned u) { return __uint_as_float(u << 16); }
; __device__ __forceinline__ float bf_hi(unsigned u) { return __uint_as_float(u & 0xffff0000u); }
; __device__ __forceinline__ float sigmoidf_(float x) { return frcp(1.0f + fexp2(-1.4426950408889634f * x)); }
; #define EPI_PIN(r) asm volatile("" : "+v"(r))
; #define EPI_FOR_BJ _Pragma("unroll") for (int bj = 0; bj < 2; ++bj)
; #define EPI_FOR_AM _Pragma("unroll") for (int ai = 0; ai < 2; ++ai) _Pragma("unroll") for (int m = 0; m < 4; ++m)
;     __device__ __forceinline__ void operator()(Acc& acc, const Unit& u, int wr, int wc, int fr, int fq) const {
;         EPI_FOR_BJ { const int c0 = EPI_COL(u, bj);
;             EPI_FOR_AM { int r = EPI_ROW(u, ai, m); EPI_PIN(r);
;                 const u32x4 ga = *(const u32x4*)(P + (size_t)r * INWP + OFF_GA + c0);
; #pragma unroll
;                 for (int e = 0; e < 8; ++e) acc[ai][bj][m][e >> 2][e & 3] *= sigmoidf_((e & 1) ? bf_hi(ga[e >> 1]) : bf_lo(ga[e >> 1]));
;                 __builtin_amdgcn_sched_barrier(0); } }
	v_mov_b32_e32 v144, v156
	v_mov_b32_e32 v145, v157
	v_mov_b32_e32 v146, v158
	v_mov_b32_e32 v147, v159
	v_lshlrev_b32_e32 v137, 16, v144
	v_mul_f32_e32 v137, 0xbfb8aa3b, v137
	v_exp_f32_e32 v137, v137
	s_nop 0
	v_add_f32_e32 v137, 1.0, v137
	v_rcp_f32_e32 v137, v137
	s_nop 0
	v_mul_f32_e32 v124, v124, v137
	v_and_b32_e32 v137, 0xffff0000, v144
	v_mul_f32_e32 v137, 0xbfb8aa3b, v137
	v_exp_f32_e32 v137, v137
	s_nop 0
	v_add_f32_e32 v137, 1.0, v137
	v_rcp_f32_e32 v137, v137
	s_nop 0
	v_mul_f32_e32 v125, v125, v137
	v_lshlrev_b32_e32 v137, 16, v145
	v_mul_f32_e32 v137, 0xbfb8aa3b, v137
	v_exp_f32_e32 v137, v137
	s_nop 0
	v_add_f32_e32 v137, 1.0, v137
	v_rcp_f32_e32 v137, v137
	s_nop 0
	v_mul_f32_e32 v126, v126, v137
	v_and_b32_e32 v137, 0xffff0000, v145
	v_mul_f32_e32 v137, 0xbfb8aa3b, v137
	v_exp_f32_e32 v137, v137
	s_nop 0
	v_add_f32_e32 v137, 1.0, v137
	v_rcp_f32_e32 v137, v137
	s_nop 0
	v_mul_f32_e32 v127, v127, v137
	v_lshlrev_b32_e32 v137, 16, v146
	v_mul_f32_e32 v137, 0xbfb8aa3b, v137
	v_exp_f32_e32 v137, v137
	s_nop 0
	v_add_f32_e32 v137, 1.0, v137
	v_rcp_f32_e32 v137, v137
	s_nop 0
	v_mul_f32_e32 v137, v120, v137
	v_and_b32_e32 v120, 0xffff0000, v146
	v_mul_f32_e32 v120, 0xbfb8aa3b, v120
	v_exp_f32_e32 v120, v120
	s_nop 0
	v_add_f32_e32 v120, 1.0, v120
	v_rcp_f32_e32 v120, v120
	s_nop 0
	v_mul_f32_e32 v121, v121, v120
	v_lshlrev_b32_e32 v120, 16, v147
	v_mul_f32_e32 v120, 0xbfb8aa3b, v120
	v_exp_f32_e32 v120, v120
	s_nop 0
	v_add_f32_e32 v120, 1.0, v120
	v_rcp_f32_e32 v120, v120
	s_nop 0
	v_mul_f32_e32 v122, v122, v120
	v_and_b32_e32 v120, 0xffff0000, v147
	v_mul_f32_e32 v120, 0xbfb8aa3b, v120
	v_exp_f32_e32 v120, v120
	s_nop 0
	v_add_f32_e32 v120, 1.0, v120
	v_rcp_f32_e32 v120, v120
	s_nop 0
	v_mul_f32_e32 v123, v123, v120
	v_or_b32_e32 v120, 16, v136
	v_mov_b32_e32 v144, v120
	s_nop 0
	v_ashrrev_i32_e32 v145, 31, v144
	v_lshlrev_b64 v[144:145], 13, v[144:145]
	v_lshl_add_u64 v[144:145], s[2:3], 0, v[144:145]
	v_lshl_add_u64 v[144:145], v[144:145], 0, v[134:135]
	s_waitcnt vmcnt(14)
	v_mov_b32_e32 v144, v160
	v_mov_b32_e32 v145, v161
	v_mov_b32_e32 v146, v162
	v_mov_b32_e32 v147, v163
	v_lshlrev_b32_e32 v139, 16, v144
	v_mul_f32_e32 v139, 0xbfb8aa3b, v139
	v_exp_f32_e32 v139, v139
	s_nop 0
	v_add_f32_e32 v139, 1.0, v139
	v_rcp_f32_e32 v139, v139
	s_nop 0
	v_mul_f32_e32 v116, v116, v139
	v_and_b32_e32 v139, 0xffff0000, v144
	v_mul_f32_e32 v139, 0xbfb8aa3b, v139
	v_exp_f32_e32 v139, v139
	s_nop 0
	v_add_f32_e32 v139, 1.0, v139
	v_rcp_f32_e32 v139, v139
	s_nop 0
	v_mul_f32_e32 v117, v117, v139
	v_lshlrev_b32_e32 v139, 16, v145
	v_mul_f32_e32 v139, 0xbfb8aa3b, v139
	v_exp_f32_e32 v139, v139
	s_nop 0
	v_add_f32_e32 v139, 1.0, v139
	v_rcp_f32_e32 v139, v139
	s_nop 0
	v_mul_f32_e32 v118, v118, v139
	v_and_b32_e32 v139, 0xffff0000, v145
	v_mul_f32_e32 v139, 0xbfb8aa3b, v139
	v_exp_f32_e32 v139, v139
	s_nop 0
	v_add_f32_e32 v139, 1.0, v139
	v_rcp_f32_e32 v139, v139
	s_nop 0
	v_mul_f32_e32 v119, v119, v139
	v_lshlrev_b32_e32 v139, 16, v146
	v_mul_f32_e32 v139, 0xbfb8aa3b, v139
	v_exp_f32_e32 v139, v139
	s_nop 0
	v_add_f32_e32 v139, 1.0, v139
	v_rcp_f32_e32 v139, v139
	s_nop 0
	v_mul_f32_e32 v139, v112, v139
	v_and_b32_e32 v112, 0xffff0000, v146
	v_mul_f32_e32 v112, 0xbfb8aa3b, v112
	v_exp_f32_e32 v112, v112
	s_nop 0
	v_add_f32_e32 v112, 1.0, v112
	v_rcp_f32_e32 v112, v112
	s_nop 0
	v_mul_f32_e32 v113, v113, v112
	v_lshlrev_b32_e32 v112, 16, v147
	v_mul_f32_e32 v112, 0xbfb8aa3b, v112
	v_exp_f32_e32 v112, v112
	s_nop 0
	v_add_f32_e32 v112, 1.0, v112
	v_rcp_f32_e32 v112, v112
	s_nop 0
	v_mul_f32_e32 v114, v114, v112
	v_and_b32_e32 v112, 0xffff0000, v147
	v_mul_f32_e32 v112, 0xbfb8aa3b, v112
	v_exp_f32_e32 v112, v112
	s_nop 0
	v_add_f32_e32 v112, 1.0, v112
	v_rcp_f32_e32 v112, v112
	s_nop 0
	v_mul_f32_e32 v115, v115, v112
	v_or_b32_e32 v112, 32, v136
	v_mov_b32_e32 v144, v112
	s_nop 0
	v_ashrrev_i32_e32 v145, 31, v144
	v_lshlrev_b64 v[144:145], 13, v[144:145]
	v_lshl_add_u64 v[144:145], s[2:3], 0, v[144:145]
	v_lshl_add_u64 v[144:145], v[144:145], 0, v[134:135]
	s_waitcnt vmcnt(13)
	v_mov_b32_e32 v144, v164
	v_mov_b32_e32 v145, v165
	v_mov_b32_e32 v146, v166
	v_mov_b32_e32 v147, v167
	v_lshlrev_b32_e32 v148, 16, v144
	v_and_b32_e32 v144, 0xffff0000, v144
	v_mul_f32_e32 v144, 0xbfb8aa3b, v144
	v_exp_f32_e32 v144, v144
	v_mul_f32_e32 v148, 0xbfb8aa3b, v148
	v_exp_f32_e32 v148, v148
	v_add_f32_e32 v144, 1.0, v144
	v_rcp_f32_e32 v144, v144
	v_add_f32_e32 v148, 1.0, v148
	v_rcp_f32_e32 v148, v148
	v_mul_f32_e32 v109, v109, v144
	v_lshlrev_b32_e32 v144, 16, v145
	v_mul_f32_e32 v144, 0xbfb8aa3b, v144
	v_exp_f32_e32 v144, v144
	v_mul_f32_e32 v108, v108, v148
	v_add_f32_e32 v144, 1.0, v144
	v_rcp_f32_e32 v144, v144
	s_nop 0
	v_mul_f32_e32 v110, v110, v144
	v_and_b32_e32 v144, 0xffff0000, v145
	v_mul_f32_e32 v144, 0xbfb8aa3b, v144
	v_exp_f32_e32 v144, v144
	s_nop 0
	v_add_f32_e32 v144, 1.0, v144
	v_rcp_f32_e32 v144, v144
	s_nop 0
	v_mul_f32_e32 v111, v111, v144
	v_lshlrev_b32_e32 v144, 16, v146
	v_mul_f32_e32 v144, 0xbfb8aa3b, v144
	v_exp_f32_e32 v144, v144
	s_nop 0
	v_add_f32_e32 v144, 1.0, v144
	v_rcp_f32_e32 v144, v144
	s_nop 0
	v_mul_f32_e32 v144, v104, v144
	v_and_b32_e32 v104, 0xffff0000, v146
	v_mul_f32_e32 v104, 0xbfb8aa3b, v104
	v_exp_f32_e32 v104, v104
	s_nop 0
	v_add_f32_e32 v104, 1.0, v104
	v_rcp_f32_e32 v104, v104
	s_nop 0
	v_mul_f32_e32 v105, v105, v104
	v_lshlrev_b32_e32 v104, 16, v147
	v_mul_f32_e32 v104, 0xbfb8aa3b, v104
	v_exp_f32_e32 v104, v104
	s_nop 0
	v_add_f32_e32 v104, 1.0, v104
	v_rcp_f32_e32 v104, v104
	s_nop 0
	v_mul_f32_e32 v106, v106, v104
	v_and_b32_e32 v104, 0xffff0000, v147
	v_mul_f32_e32 v104, 0xbfb8aa3b, v104
	v_exp_f32_e32 v104, v104
	s_nop 0
	v_add_f32_e32 v104, 1.0, v104
	v_rcp_f32_e32 v104, v104
	s_nop 0
	v_mul_f32_e32 v107, v107, v104
	v_or_b32_e32 v104, 48, v136
	v_mov_b32_e32 v146, v104
	s_nop 0
	v_ashrrev_i32_e32 v147, 31, v146
	v_lshlrev_b64 v[146:147], 13, v[146:147]
	v_lshl_add_u64 v[146:147], s[2:3], 0, v[146:147]
	v_lshl_add_u64 v[146:147], v[146:147], 0, v[134:135]
	s_waitcnt vmcnt(12)
; __device__ __forceinline__ float bf_lo(unsigned u) { return __uint_as_float(u << 16); }
; __device__ __forceinline__ float bf_hi(unsigned u) { return __uint_as_float(u & 0xffff0000u); }
; __device__ __forceinline__ float sigmoidf_(float x) { return frcp(1.0f + fexp2(-1.4426950408889634f * x)); }
; #define EPI_PIN(r) asm volatile("" : "+v"(r))
; #define EPI_FOR_BJ _Pragma("unroll") for (int bj = 0; bj < 2; ++bj)
; #define EPI_FOR_AM _Pragma("unroll") for (int ai = 0; ai < 2; ++ai) _Pragma("unroll") for (int m = 0; m < 4; ++m)
;     __device__ __forceinline__ void operator()(Acc& acc, const Unit& u, int wr, int wc, int fr, int fq) const {
;         EPI_FOR_BJ { const int c0 = EPI_COL(u, bj);
;             EPI_FOR_AM { int r = EPI_ROW(u, ai, m); EPI_PIN(r);
;                 const u32x4 ga = *(const u32x4*)(P + (size_t)r * INWP + OFF_GA + c0);
; #pragma unroll
;                 for (int e = 0; e < 8; ++e) acc[ai][bj][m][e >> 2][e & 3] *= sigmoidf_((e & 1) ? bf_hi(ga[e >> 1]) : bf_lo(ga[e >> 1]));
;                 __builtin_amdgcn_sched_barrier(0); } }
	v_mov_b32_e32 v146, v168
	v_mov_b32_e32 v147, v169
	v_mov_b32_e32 v148, v170
	v_mov_b32_e32 v149, v171
	v_lshlrev_b32_e32 v145, 16, v146
	v_mul_f32_e32 v145, 0xbfb8aa3b, v145
	v_exp_f32_e32 v145, v145
	s_nop 0
	v_add_f32_e32 v145, 1.0, v145
	v_rcp_f32_e32 v145, v145
	s_nop 0
	v_mul_f32_e32 v100, v100, v145
	v_and_b32_e32 v145, 0xffff0000, v146
	v_mul_f32_e32 v145, 0xbfb8aa3b, v145
	v_exp_f32_e32 v145, v145
	s_nop 0
	v_add_f32_e32 v145, 1.0, v145
	v_rcp_f32_e32 v145, v145
	s_nop 0
	v_mul_f32_e32 v101, v101, v145
	v_lshlrev_b32_e32 v145, 16, v147
	v_mul_f32_e32 v145, 0xbfb8aa3b, v145
	v_exp_f32_e32 v145, v145
	s_nop 0
	v_add_f32_e32 v145, 1.0, v145
	v_rcp_f32_e32 v145, v145
	s_nop 0
	v_mul_f32_e32 v102, v102, v145
	v_and_b32_e32 v145, 0xffff0000, v147
	v_mul_f32_e32 v145, 0xbfb8aa3b, v145
	v_exp_f32_e32 v145, v145
	s_nop 0
	v_add_f32_e32 v145, 1.0, v145
	v_rcp_f32_e32 v145, v145
	s_nop 0
	v_mul_f32_e32 v103, v103, v145
	v_lshlrev_b32_e32 v145, 16, v148
	v_mul_f32_e32 v145, 0xbfb8aa3b, v145
	v_exp_f32_e32 v145, v145
	s_nop 0
	v_add_f32_e32 v145, 1.0, v145
	v_rcp_f32_e32 v145, v145
	s_nop 0
	v_mul_f32_e32 v145, v96, v145
	v_and_b32_e32 v96, 0xffff0000, v148
	v_mul_f32_e32 v96, 0xbfb8aa3b, v96
	v_exp_f32_e32 v96, v96
	s_nop 0
	v_add_f32_e32 v96, 1.0, v96
	v_rcp_f32_e32 v96, v96
	s_nop 0
	v_mul_f32_e32 v97, v97, v96
	v_lshlrev_b32_e32 v96, 16, v149
	v_mul_f32_e32 v96, 0xbfb8aa3b, v96
	v_exp_f32_e32 v96, v96
	s_nop 0
	v_add_f32_e32 v96, 1.0, v96
	v_rcp_f32_e32 v96, v96
	s_nop 0
	v_mul_f32_e32 v98, v98, v96
	v_and_b32_e32 v96, 0xffff0000, v149
	v_mul_f32_e32 v96, 0xbfb8aa3b, v96
	v_exp_f32_e32 v96, v96
	s_nop 0
	v_add_f32_e32 v96, 1.0, v96
	v_rcp_f32_e32 v96, v96
	s_nop 0
	v_mul_f32_e32 v99, v99, v96
	v_add_u32_e32 v96, 0x80, v136
	v_mov_b32_e32 v146, v96
	s_nop 0
	v_ashrrev_i32_e32 v147, 31, v146
	v_lshlrev_b64 v[146:147], 13, v[146:147]
	v_lshl_add_u64 v[146:147], s[2:3], 0, v[146:147]
	v_lshl_add_u64 v[146:147], v[146:147], 0, v[134:135]
	s_waitcnt vmcnt(11)
	v_mov_b32_e32 v146, v172
	v_mov_b32_e32 v147, v173
	v_mov_b32_e32 v148, v174
	v_mov_b32_e32 v149, v175
	v_lshlrev_b32_e32 v150, 16, v146
	v_and_b32_e32 v146, 0xffff0000, v146
	v_mul_f32_e32 v146, 0xbfb8aa3b, v146
	v_exp_f32_e32 v146, v146
	v_mul_f32_e32 v150, 0xbfb8aa3b, v150
	v_exp_f32_e32 v150, v150
	v_add_f32_e32 v146, 1.0, v146
	v_rcp_f32_e32 v146, v146
	v_add_f32_e32 v150, 1.0, v150
	v_rcp_f32_e32 v150, v150
	v_mul_f32_e32 v93, v93, v146
	v_lshlrev_b32_e32 v146, 16, v147
	v_mul_f32_e32 v146, 0xbfb8aa3b, v146
	v_exp_f32_e32 v146, v146
	v_mul_f32_e32 v92, v92, v150
	v_add_f32_e32 v146, 1.0, v146
	v_rcp_f32_e32 v146, v146
	s_nop 0
	v_mul_f32_e32 v94, v94, v146
	v_and_b32_e32 v146, 0xffff0000, v147
	v_mul_f32_e32 v146, 0xbfb8aa3b, v146
	v_exp_f32_e32 v146, v146
	s_nop 0
	v_add_f32_e32 v146, 1.0, v146
	v_rcp_f32_e32 v146, v146
	s_nop 0
	v_mul_f32_e32 v95, v95, v146
	v_lshlrev_b32_e32 v146, 16, v148
	v_mul_f32_e32 v146, 0xbfb8aa3b, v146
	v_exp_f32_e32 v146, v146
	s_nop 0
	v_add_f32_e32 v146, 1.0, v146
	v_rcp_f32_e32 v146, v146
	s_nop 0
	v_mul_f32_e32 v146, v88, v146
	v_and_b32_e32 v88, 0xffff0000, v148
	v_mul_f32_e32 v88, 0xbfb8aa3b, v88
	v_exp_f32_e32 v88, v88
	s_nop 0
	v_add_f32_e32 v88, 1.0, v88
	v_rcp_f32_e32 v88, v88
	s_nop 0
	v_mul_f32_e32 v89, v89, v88
	v_lshlrev_b32_e32 v88, 16, v149
	v_mul_f32_e32 v88, 0xbfb8aa3b, v88
	v_exp_f32_e32 v88, v88
	s_nop 0
	v_add_f32_e32 v88, 1.0, v88
	v_rcp_f32_e32 v88, v88
	s_nop 0
	v_mul_f32_e32 v90, v90, v88
	v_and_b32_e32 v88, 0xffff0000, v149
	v_mul_f32_e32 v88, 0xbfb8aa3b, v88
	v_exp_f32_e32 v88, v88
	s_nop 0
	v_add_f32_e32 v88, 1.0, v88
	v_rcp_f32_e32 v88, v88
	s_nop 0
	v_mul_f32_e32 v91, v91, v88
	v_add_u32_e32 v88, 0x90, v136
	v_mov_b32_e32 v148, v88
	s_nop 0
	v_ashrrev_i32_e32 v149, 31, v148
	v_lshlrev_b64 v[148:149], 13, v[148:149]
	v_lshl_add_u64 v[148:149], s[2:3], 0, v[148:149]
	v_lshl_add_u64 v[148:149], v[148:149], 0, v[134:135]
	s_waitcnt vmcnt(10)
	v_mov_b32_e32 v148, v176
	v_mov_b32_e32 v149, v177
	v_mov_b32_e32 v150, v178
	v_mov_b32_e32 v151, v179
	v_lshlrev_b32_e32 v147, 16, v148
	v_mul_f32_e32 v147, 0xbfb8aa3b, v147
	v_exp_f32_e32 v147, v147
	s_nop 0
	v_add_f32_e32 v147, 1.0, v147
	v_rcp_f32_e32 v147, v147
	s_nop 0
	v_mul_f32_e32 v84, v84, v147
	v_and_b32_e32 v147, 0xffff0000, v148
	v_mul_f32_e32 v147, 0xbfb8aa3b, v147
	v_exp_f32_e32 v147, v147
	s_nop 0
	v_add_f32_e32 v147, 1.0, v147
	v_rcp_f32_e32 v147, v147
	s_nop 0
	v_mul_f32_e32 v85, v85, v147
	v_lshlrev_b32_e32 v147, 16, v149
	v_mul_f32_e32 v147, 0xbfb8aa3b, v147
	v_exp_f32_e32 v147, v147
	s_nop 0
	v_add_f32_e32 v147, 1.0, v147
	v_rcp_f32_e32 v147, v147
	s_nop 0
	v_mul_f32_e32 v86, v86, v147
	v_and_b32_e32 v147, 0xffff0000, v149
	v_mul_f32_e32 v147, 0xbfb8aa3b, v147
	v_exp_f32_e32 v147, v147
	s_nop 0
	v_add_f32_e32 v147, 1.0, v147
	v_rcp_f32_e32 v147, v147
	s_nop 0
	v_mul_f32_e32 v87, v87, v147
	v_lshlrev_b32_e32 v147, 16, v150
	v_mul_f32_e32 v147, 0xbfb8aa3b, v147
	v_exp_f32_e32 v147, v147
	s_nop 0
	v_add_f32_e32 v147, 1.0, v147
	v_rcp_f32_e32 v147, v147
	s_nop 0
	v_mul_f32_e32 v147, v80, v147
	v_and_b32_e32 v80, 0xffff0000, v150
	v_mul_f32_e32 v80, 0xbfb8aa3b, v80
	v_exp_f32_e32 v80, v80
	s_nop 0
	v_add_f32_e32 v80, 1.0, v80
	v_rcp_f32_e32 v80, v80
	s_nop 0
	v_mul_f32_e32 v81, v81, v80
	v_lshlrev_b32_e32 v80, 16, v151
	v_mul_f32_e32 v80, 0xbfb8aa3b, v80
	v_exp_f32_e32 v80, v80
	s_nop 0
	v_add_f32_e32 v80, 1.0, v80
	v_rcp_f32_e32 v80, v80
	s_nop 0
	v_mul_f32_e32 v82, v82, v80
	v_and_b32_e32 v80, 0xffff0000, v151
	v_mul_f32_e32 v80, 0xbfb8aa3b, v80
	v_exp_f32_e32 v80, v80
	s_nop 0
	v_add_f32_e32 v80, 1.0, v80
	v_rcp_f32_e32 v80, v80
	s_nop 0
	v_mul_f32_e32 v83, v83, v80
	v_add_u32_e32 v80, 0xa0, v136
	v_mov_b32_e32 v148, v80
	s_nop 0
	v_ashrrev_i32_e32 v149, 31, v148
	v_lshlrev_b64 v[148:149], 13, v[148:149]
	v_lshl_add_u64 v[148:149], s[2:3], 0, v[148:149]
	v_lshl_add_u64 v[148:149], v[148:149], 0, v[134:135]
	s_waitcnt vmcnt(9)
; __device__ __forceinline__ float bf_lo(unsigned u) { return __uint_as_float(u << 16); }
; __device__ __forceinline__ float bf_hi(unsigned u) { return __uint_as_float(u & 0xffff0000u); }
; __device__ __forceinline__ float sigmoidf_(float x) { return frcp(1.0f + fexp2(-1.4426950408889634f * x)); }
; #define EPI_PIN(r) asm volatile("" : "+v"(r))
; #define EPI_FOR_BJ _Pragma("unroll") for (int bj = 0; bj < 2; ++bj)
; #define EPI_FOR_AM _Pragma("unroll") for (int ai = 0; ai < 2; ++ai) _Pragma("unroll") for (int m = 0; m < 4; ++m)
;     __device__ __forceinline__ void operator()(Acc& acc, const Unit& u, int wr, int wc, int fr, int fq) const {
;         EPI_FOR_BJ { const int c0 = EPI_COL(u, bj);
;             EPI_FOR_AM { int r = EPI_ROW(u, ai, m); EPI_PIN(r);
;                 const u32x4 ga = *(const u32x4*)(P + (size_t)r * INWP + OFF_GA + c0);
; #pragma unroll
;                 for (int e = 0; e < 8; ++e) acc[ai][bj][m][e >> 2][e & 3] *= sigmoidf_((e & 1) ? bf_hi(ga[e >> 1]) : bf_lo(ga[e >> 1]));
;                 __builtin_amdgcn_sched_barrier(0); } }
	v_mov_b32_e32 v148, v180
	v_mov_b32_e32 v149, v181
	v_mov_b32_e32 v150, v182
	v_mov_b32_e32 v151, v183
	v_lshlrev_b32_e32 v152, 16, v148
	v_and_b32_e32 v148, 0xffff0000, v148
	v_mul_f32_e32 v148, 0xbfb8aa3b, v148
	v_exp_f32_e32 v148, v148
	v_mul_f32_e32 v152, 0xbfb8aa3b, v152
	v_exp_f32_e32 v152, v152
	v_add_f32_e32 v148, 1.0, v148
	v_rcp_f32_e32 v148, v148
	v_add_f32_e32 v152, 1.0, v152
	v_rcp_f32_e32 v152, v152
	v_mul_f32_e32 v77, v77, v148
	v_lshlrev_b32_e32 v148, 16, v149
	v_mul_f32_e32 v148, 0xbfb8aa3b, v148
	v_exp_f32_e32 v148, v148
	v_mul_f32_e32 v76, v76, v152
	v_add_f32_e32 v148, 1.0, v148
	v_rcp_f32_e32 v148, v148
	s_nop 0
	v_mul_f32_e32 v78, v78, v148
	v_and_b32_e32 v148, 0xffff0000, v149
	v_mul_f32_e32 v148, 0xbfb8aa3b, v148
	v_exp_f32_e32 v148, v148
	s_nop 0
	v_add_f32_e32 v148, 1.0, v148
	v_rcp_f32_e32 v148, v148
	s_nop 0
	v_mul_f32_e32 v79, v79, v148
	v_lshlrev_b32_e32 v148, 16, v150
	v_mul_f32_e32 v148, 0xbfb8aa3b, v148
	v_exp_f32_e32 v148, v148
	s_nop 0
	v_add_f32_e32 v148, 1.0, v148
	v_rcp_f32_e32 v148, v148
	s_nop 0
	v_mul_f32_e32 v148, v72, v148
	v_and_b32_e32 v72, 0xffff0000, v150
	v_mul_f32_e32 v72, 0xbfb8aa3b, v72
	v_exp_f32_e32 v72, v72
	s_nop 0
	v_add_f32_e32 v72, 1.0, v72
	v_rcp_f32_e32 v72, v72
	s_nop 0
	v_mul_f32_e32 v73, v73, v72
	v_lshlrev_b32_e32 v72, 16, v151
	v_mul_f32_e32 v72, 0xbfb8aa3b, v72
	v_exp_f32_e32 v72, v72
	s_nop 0
	v_add_f32_e32 v72, 1.0, v72
	v_rcp_f32_e32 v72, v72
	s_nop 0
	v_mul_f32_e32 v74, v74, v72
	v_and_b32_e32 v72, 0xffff0000, v151
	v_mul_f32_e32 v72, 0xbfb8aa3b, v72
	v_exp_f32_e32 v72, v72
	s_nop 0
	v_add_f32_e32 v72, 1.0, v72
	v_rcp_f32_e32 v72, v72
	s_nop 0
	v_mul_f32_e32 v75, v75, v72
	v_add_u32_e32 v72, 0xb0, v136
	v_mov_b32_e32 v150, v72
	s_nop 0
	v_ashrrev_i32_e32 v151, 31, v150
	v_lshlrev_b64 v[150:151], 13, v[150:151]
	v_lshl_add_u64 v[150:151], s[2:3], 0, v[150:151]
	v_lshl_add_u64 v[150:151], v[150:151], 0, v[134:135]
	s_waitcnt vmcnt(8)
	v_mov_b32_e32 v150, v184
	v_mov_b32_e32 v151, v185
	v_mov_b32_e32 v152, v186
	v_mov_b32_e32 v153, v187
	v_lshlrev_b32_e32 v149, 16, v150
	v_mul_f32_e32 v149, 0xbfb8aa3b, v149
	v_exp_f32_e32 v149, v149
	s_nop 0
	v_add_f32_e32 v149, 1.0, v149
	v_rcp_f32_e32 v149, v149
	s_nop 0
	v_mul_f32_e32 v68, v68, v149
	v_and_b32_e32 v149, 0xffff0000, v150
	v_mul_f32_e32 v149, 0xbfb8aa3b, v149
	v_exp_f32_e32 v149, v149
	s_nop 0
	v_add_f32_e32 v149, 1.0, v149
	v_rcp_f32_e32 v149, v149
	s_nop 0
	v_mul_f32_e32 v69, v69, v149
	v_lshlrev_b32_e32 v149, 16, v151
	v_mul_f32_e32 v149, 0xbfb8aa3b, v149
	v_exp_f32_e32 v149, v149
	s_nop 0
	v_add_f32_e32 v149, 1.0, v149
	v_rcp_f32_e32 v149, v149
	s_nop 0
	v_mul_f32_e32 v70, v70, v149
	v_and_b32_e32 v149, 0xffff0000, v151
	v_mul_f32_e32 v149, 0xbfb8aa3b, v149
	v_exp_f32_e32 v149, v149
	s_nop 0
	v_add_f32_e32 v149, 1.0, v149
	v_rcp_f32_e32 v149, v149
	s_nop 0
	v_mul_f32_e32 v71, v71, v149
	v_lshlrev_b32_e32 v149, 16, v152
	v_mul_f32_e32 v149, 0xbfb8aa3b, v149
	v_exp_f32_e32 v149, v149
	s_nop 0
	v_add_f32_e32 v149, 1.0, v149
	v_rcp_f32_e32 v149, v149
	s_nop 0
	v_mul_f32_e32 v149, v64, v149
	v_and_b32_e32 v64, 0xffff0000, v152
	v_mul_f32_e32 v64, 0xbfb8aa3b, v64
	v_exp_f32_e32 v64, v64
	s_nop 0
	v_add_f32_e32 v64, 1.0, v64
	v_rcp_f32_e32 v64, v64
	s_nop 0
	v_mul_f32_e32 v150, v65, v64
	v_lshlrev_b32_e32 v64, 16, v153
	v_mul_f32_e32 v64, 0xbfb8aa3b, v64
	v_exp_f32_e32 v64, v64
	s_nop 0
	v_add_f32_e32 v64, 1.0, v64
	v_rcp_f32_e32 v64, v64
	s_nop 0
	v_mul_f32_e32 v66, v66, v64
	v_and_b32_e32 v64, 0xffff0000, v153
	v_mul_f32_e32 v64, 0xbfb8aa3b, v64
	v_exp_f32_e32 v64, v64
	s_nop 0
	v_add_f32_e32 v64, 1.0, v64
	v_rcp_f32_e32 v64, v64
	s_nop 0
	v_mul_f32_e32 v67, v67, v64
	v_mov_b32_e32 v152, v136
	v_or_b32_e32 v64, 0x80, v138
	v_ashrrev_i32_e32 v65, 31, v64
	v_ashrrev_i32_e32 v153, 31, v152
	v_lshlrev_b64 v[152:153], 13, v[152:153]
	v_lshl_add_u64 v[152:153], s[2:3], 0, v[152:153]
	v_lshlrev_b64 v[64:65], 1, v[64:65]
	v_lshl_add_u64 v[152:153], v[152:153], 0, v[64:65]
	s_waitcnt vmcnt(7)
	v_mov_b32_e32 v152, v188
	v_mov_b32_e32 v153, v189
	v_mov_b32_e32 v154, v190
	v_mov_b32_e32 v155, v191
	v_lshlrev_b32_e32 v138, 16, v152
	v_mul_f32_e32 v138, 0xbfb8aa3b, v138
	v_exp_f32_e32 v138, v138
	s_nop 0
	v_add_f32_e32 v138, 1.0, v138
	v_rcp_f32_e32 v138, v138
	s_nop 0
	v_mul_f32_e32 v60, v60, v138
	v_and_b32_e32 v138, 0xffff0000, v152
	v_mul_f32_e32 v138, 0xbfb8aa3b, v138
	v_exp_f32_e32 v138, v138
	s_nop 0
	v_add_f32_e32 v138, 1.0, v138
	v_rcp_f32_e32 v138, v138
	s_nop 0
	v_mul_f32_e32 v61, v61, v138
	v_lshlrev_b32_e32 v138, 16, v153
	v_mul_f32_e32 v138, 0xbfb8aa3b, v138
	v_exp_f32_e32 v138, v138
	s_nop 0
	v_add_f32_e32 v138, 1.0, v138
	v_rcp_f32_e32 v138, v138
	s_nop 0
	v_mul_f32_e32 v62, v62, v138
	v_and_b32_e32 v138, 0xffff0000, v153
	v_mul_f32_e32 v138, 0xbfb8aa3b, v138
	v_exp_f32_e32 v138, v138
	s_nop 0
	v_add_f32_e32 v138, 1.0, v138
	v_rcp_f32_e32 v138, v138
	s_nop 0
	v_mul_f32_e32 v63, v63, v138
	v_lshlrev_b32_e32 v138, 16, v154
	v_mul_f32_e32 v138, 0xbfb8aa3b, v138
	v_exp_f32_e32 v138, v138
	s_nop 0
	v_add_f32_e32 v138, 1.0, v138
	v_rcp_f32_e32 v138, v138
	s_nop 0
	v_mul_f32_e32 v56, v56, v138
	v_and_b32_e32 v138, 0xffff0000, v154
	v_mul_f32_e32 v138, 0xbfb8aa3b, v138
	v_exp_f32_e32 v138, v138
	s_nop 0
	v_add_f32_e32 v138, 1.0, v138
	v_rcp_f32_e32 v138, v138
	s_nop 0
	v_mul_f32_e32 v57, v57, v138
	v_lshlrev_b32_e32 v138, 16, v155
	v_mul_f32_e32 v138, 0xbfb8aa3b, v138
	v_exp_f32_e32 v138, v138
	s_nop 0
	v_add_f32_e32 v138, 1.0, v138
	v_rcp_f32_e32 v138, v138
	s_nop 0
	v_mul_f32_e32 v58, v58, v138
	v_and_b32_e32 v138, 0xffff0000, v155
	v_mul_f32_e32 v138, 0xbfb8aa3b, v138
	v_exp_f32_e32 v138, v138
	s_nop 0
	v_add_f32_e32 v138, 1.0, v138
	v_rcp_f32_e32 v138, v138
	s_nop 0
	v_mul_f32_e32 v59, v59, v138
	v_mov_b32_e32 v152, v120
	s_nop 0
	v_ashrrev_i32_e32 v153, 31, v152
	v_lshlrev_b64 v[152:153], 13, v[152:153]
	v_lshl_add_u64 v[152:153], s[2:3], 0, v[152:153]
	v_lshl_add_u64 v[152:153], v[152:153], 0, v[64:65]
	s_waitcnt vmcnt(6)
; __device__ __forceinline__ float bf_lo(unsigned u) { return __uint_as_float(u << 16); }
; __device__ __forceinline__ float bf_hi(unsigned u) { return __uint_as_float(u & 0xffff0000u); }
; __device__ __forceinline__ float sigmoidf_(float x) { return frcp(1.0f + fexp2(-1.4426950408889634f * x)); }
; #define EPI_PIN(r) asm volatile("" : "+v"(r))
; #define EPI_FOR_BJ _Pragma("unroll") for (int bj = 0; bj < 2; ++bj)
; #define EPI_FOR_AM _Pragma("unroll") for (int ai = 0; ai < 2; ++ai) _Pragma("unroll") for (int m = 0; m < 4; ++m)
;     __device__ __forceinline__ void operator()(Acc& acc, const Unit& u, int wr, int wc, int fr, int fq) const {
;         EPI_FOR_BJ { const int c0 = EPI_COL(u, bj);
;             EPI_FOR_AM { int r = EPI_ROW(u, ai, m); EPI_PIN(r);
;                 const u32x4 ga = *(const u32x4*)(P + (size_t)r * INWP + OFF_GA + c0);
; #pragma unroll
;                 for (int e = 0; e < 8; ++e) acc[ai][bj][m][e >> 2][e & 3] *= sigmoidf_((e & 1) ? bf_hi(ga[e >> 1]) : bf_lo(ga[e >> 1]));
;                 __builtin_amdgcn_sched_barrier(0); } }
	v_mov_b32_e32 v152, v192
	v_mov_b32_e32 v153, v193
	v_mov_b32_e32 v154, v194
	v_mov_b32_e32 v155, v195
	v_lshlrev_b32_e32 v138, 16, v152
	v_mul_f32_e32 v138, 0xbfb8aa3b, v138
	v_exp_f32_e32 v138, v138
	s_nop 0
	v_add_f32_e32 v138, 1.0, v138
	v_rcp_f32_e32 v138, v138
	s_nop 0
	v_mul_f32_e32 v52, v52, v138
	v_and_b32_e32 v138, 0xffff0000, v152
	v_mul_f32_e32 v138, 0xbfb8aa3b, v138
	v_exp_f32_e32 v138, v138
	s_nop 0
	v_add_f32_e32 v138, 1.0, v138
	v_rcp_f32_e32 v138, v138
	s_nop 0
	v_mul_f32_e32 v53, v53, v138
	v_lshlrev_b32_e32 v138, 16, v153
	v_mul_f32_e32 v138, 0xbfb8aa3b, v138
	v_exp_f32_e32 v138, v138
	s_nop 0
	v_add_f32_e32 v138, 1.0, v138
	v_rcp_f32_e32 v138, v138
	s_nop 0
	v_mul_f32_e32 v54, v54, v138
	v_and_b32_e32 v138, 0xffff0000, v153
	v_mul_f32_e32 v138, 0xbfb8aa3b, v138
	v_exp_f32_e32 v138, v138
	s_nop 0
	v_add_f32_e32 v138, 1.0, v138
	v_rcp_f32_e32 v138, v138
	s_nop 0
	v_mul_f32_e32 v55, v55, v138
	v_lshlrev_b32_e32 v138, 16, v154
	v_mul_f32_e32 v138, 0xbfb8aa3b, v138
	v_exp_f32_e32 v138, v138
	s_nop 0
	v_add_f32_e32 v138, 1.0, v138
	v_rcp_f32_e32 v138, v138
	s_nop 0
	v_mul_f32_e32 v48, v48, v138
	v_and_b32_e32 v138, 0xffff0000, v154
	v_mul_f32_e32 v138, 0xbfb8aa3b, v138
	v_exp_f32_e32 v138, v138
	s_nop 0
	v_add_f32_e32 v138, 1.0, v138
	v_rcp_f32_e32 v138, v138
	s_nop 0
	v_mul_f32_e32 v49, v49, v138
	v_lshlrev_b32_e32 v138, 16, v155
	v_mul_f32_e32 v138, 0xbfb8aa3b, v138
	v_exp_f32_e32 v138, v138
	s_nop 0
	v_add_f32_e32 v138, 1.0, v138
	v_rcp_f32_e32 v138, v138
	s_nop 0
	v_mul_f32_e32 v50, v50, v138
	v_and_b32_e32 v138, 0xffff0000, v155
	v_mul_f32_e32 v138, 0xbfb8aa3b, v138
	v_exp_f32_e32 v138, v138
	s_nop 0
	v_add_f32_e32 v138, 1.0, v138
	v_rcp_f32_e32 v138, v138
	s_nop 0
	v_mul_f32_e32 v51, v51, v138
	v_mov_b32_e32 v152, v112
	s_nop 0
	v_ashrrev_i32_e32 v153, 31, v152
	v_lshlrev_b64 v[152:153], 13, v[152:153]
	v_lshl_add_u64 v[152:153], s[2:3], 0, v[152:153]
	v_lshl_add_u64 v[152:153], v[152:153], 0, v[64:65]
	s_waitcnt vmcnt(5)
	v_mov_b32_e32 v152, v206
	v_mov_b32_e32 v153, v207
	v_mov_b32_e32 v154, v208
	v_mov_b32_e32 v155, v209
	v_lshlrev_b32_e32 v138, 16, v152
	v_mul_f32_e32 v138, 0xbfb8aa3b, v138
	v_exp_f32_e32 v138, v138
	s_nop 0
	v_add_f32_e32 v138, 1.0, v138
	v_rcp_f32_e32 v138, v138
	s_nop 0
	v_mul_f32_e32 v44, v44, v138
	v_and_b32_e32 v138, 0xffff0000, v152
	v_mul_f32_e32 v138, 0xbfb8aa3b, v138
	v_exp_f32_e32 v138, v138
	s_nop 0
	v_add_f32_e32 v138, 1.0, v138
	v_rcp_f32_e32 v138, v138
	s_nop 0
	v_mul_f32_e32 v45, v45, v138
	v_lshlrev_b32_e32 v138, 16, v153
	v_mul_f32_e32 v138, 0xbfb8aa3b, v138
	v_exp_f32_e32 v138, v138
	s_nop 0
	v_add_f32_e32 v138, 1.0, v138
	v_rcp_f32_e32 v138, v138
	s_nop 0
	v_mul_f32_e32 v46, v46, v138
	v_and_b32_e32 v138, 0xffff0000, v153
	v_mul_f32_e32 v138, 0xbfb8aa3b, v138
	v_exp_f32_e32 v138, v138
	s_nop 0
	v_add_f32_e32 v138, 1.0, v138
	v_rcp_f32_e32 v138, v138
	s_nop 0
	v_mul_f32_e32 v47, v47, v138
	v_lshlrev_b32_e32 v138, 16, v154
	v_mul_f32_e32 v138, 0xbfb8aa3b, v138
	v_exp_f32_e32 v138, v138
	s_nop 0
	v_add_f32_e32 v138, 1.0, v138
	v_rcp_f32_e32 v138, v138
	s_nop 0
	v_mul_f32_e32 v40, v40, v138
	v_and_b32_e32 v138, 0xffff0000, v154
	v_mul_f32_e32 v138, 0xbfb8aa3b, v138
	v_exp_f32_e32 v138, v138
	s_nop 0
	v_add_f32_e32 v138, 1.0, v138
	v_rcp_f32_e32 v138, v138
	s_nop 0
	v_mul_f32_e32 v41, v41, v138
	v_lshlrev_b32_e32 v138, 16, v155
	v_mul_f32_e32 v138, 0xbfb8aa3b, v138
	v_exp_f32_e32 v138, v138
	s_nop 0
	v_add_f32_e32 v138, 1.0, v138
	v_rcp_f32_e32 v138, v138
	s_nop 0
	v_mul_f32_e32 v42, v42, v138
	v_and_b32_e32 v138, 0xffff0000, v155
	v_mul_f32_e32 v138, 0xbfb8aa3b, v138
	v_exp_f32_e32 v138, v138
	s_nop 0
	v_add_f32_e32 v138, 1.0, v138
	v_rcp_f32_e32 v138, v138
	s_nop 0
	v_mul_f32_e32 v43, v43, v138
	v_mov_b32_e32 v152, v104
	s_nop 0
	v_ashrrev_i32_e32 v153, 31, v152
	v_lshlrev_b64 v[152:153], 13, v[152:153]
	v_lshl_add_u64 v[152:153], s[2:3], 0, v[152:153]
	v_lshl_add_u64 v[152:153], v[152:153], 0, v[64:65]
	s_waitcnt vmcnt(4)
	v_mov_b32_e32 v152, v210
	v_mov_b32_e32 v153, v211
	v_mov_b32_e32 v154, v212
	v_mov_b32_e32 v155, v213
	v_lshlrev_b32_e32 v138, 16, v152
	v_mul_f32_e32 v138, 0xbfb8aa3b, v138
	v_exp_f32_e32 v138, v138
	s_nop 0
	v_add_f32_e32 v138, 1.0, v138
	v_rcp_f32_e32 v138, v138
	s_nop 0
	v_mul_f32_e32 v36, v36, v138
	v_and_b32_e32 v138, 0xffff0000, v152
	v_mul_f32_e32 v138, 0xbfb8aa3b, v138
	v_exp_f32_e32 v138, v138
	s_nop 0
	v_add_f32_e32 v138, 1.0, v138
	v_rcp_f32_e32 v138, v138
	s_nop 0
	v_mul_f32_e32 v37, v37, v138
	v_lshlrev_b32_e32 v138, 16, v153
	v_mul_f32_e32 v138, 0xbfb8aa3b, v138
	v_exp_f32_e32 v138, v138
	s_nop 0
	v_add_f32_e32 v138, 1.0, v138
	v_rcp_f32_e32 v138, v138
	s_nop 0
	v_mul_f32_e32 v38, v38, v138
	v_and_b32_e32 v138, 0xffff0000, v153
	v_mul_f32_e32 v138, 0xbfb8aa3b, v138
	v_exp_f32_e32 v138, v138
	s_nop 0
	v_add_f32_e32 v138, 1.0, v138
	v_rcp_f32_e32 v138, v138
	s_nop 0
	v_mul_f32_e32 v39, v39, v138
	v_lshlrev_b32_e32 v138, 16, v154
	v_mul_f32_e32 v138, 0xbfb8aa3b, v138
	v_exp_f32_e32 v138, v138
	s_nop 0
	v_add_f32_e32 v138, 1.0, v138
	v_rcp_f32_e32 v138, v138
	s_nop 0
	v_mul_f32_e32 v32, v32, v138
	v_and_b32_e32 v138, 0xffff0000, v154
	v_mul_f32_e32 v138, 0xbfb8aa3b, v138
	v_exp_f32_e32 v138, v138
	s_nop 0
	v_add_f32_e32 v138, 1.0, v138
	v_rcp_f32_e32 v138, v138
	s_nop 0
	v_mul_f32_e32 v33, v33, v138
	v_lshlrev_b32_e32 v138, 16, v155
	v_mul_f32_e32 v138, 0xbfb8aa3b, v138
	v_exp_f32_e32 v138, v138
	s_nop 0
	v_add_f32_e32 v138, 1.0, v138
	v_rcp_f32_e32 v138, v138
	s_nop 0
	v_mul_f32_e32 v34, v34, v138
	v_and_b32_e32 v138, 0xffff0000, v155
	v_mul_f32_e32 v138, 0xbfb8aa3b, v138
	v_exp_f32_e32 v138, v138
	s_nop 0
	v_add_f32_e32 v138, 1.0, v138
	v_rcp_f32_e32 v138, v138
	s_nop 0
	v_mul_f32_e32 v35, v35, v138
	v_mov_b32_e32 v152, v96
	s_nop 0
	v_ashrrev_i32_e32 v153, 31, v152
	v_lshlrev_b64 v[152:153], 13, v[152:153]
	v_lshl_add_u64 v[152:153], s[2:3], 0, v[152:153]
	v_lshl_add_u64 v[152:153], v[152:153], 0, v[64:65]
	s_waitcnt vmcnt(3)
; __device__ __forceinline__ float bf_lo(unsigned u) { return __uint_as_float(u << 16); }
; __device__ __forceinline__ float bf_hi(unsigned u) { return __uint_as_float(u & 0xffff0000u); }
; __device__ __forceinline__ float sigmoidf_(float x) { return frcp(1.0f + fexp2(-1.4426950408889634f * x)); }
; #define EPI_PIN(r) asm volatile("" : "+v"(r))
; #define EPI_FOR_BJ _Pragma("unroll") for (int bj = 0; bj < 2; ++bj)
; #define EPI_FOR_AM _Pragma("unroll") for (int ai = 0; ai < 2; ++ai) _Pragma("unroll") for (int m = 0; m < 4; ++m)
;     __device__ __forceinline__ void operator()(Acc& acc, const Unit& u, int wr, int wc, int fr, int fq) const {
;         EPI_FOR_BJ { const int c0 = EPI_COL(u, bj);
;             EPI_FOR_AM { int r = EPI_ROW(u, ai, m); EPI_PIN(r);
;                 const u32x4 ga = *(const u32x4*)(P + (size_t)r * INWP + OFF_GA + c0);
; #pragma unroll
;                 for (int e = 0; e < 8; ++e) acc[ai][bj][m][e >> 2][e & 3] *= sigmoidf_((e & 1) ? bf_hi(ga[e >> 1]) : bf_lo(ga[e >> 1]));
;                 __builtin_amdgcn_sched_barrier(0); } }
	v_mov_b32_e32 v152, v214
	v_mov_b32_e32 v153, v215
	v_mov_b32_e32 v154, v216
	v_mov_b32_e32 v155, v217
	v_lshlrev_b32_e32 v138, 16, v152
	v_mul_f32_e32 v138, 0xbfb8aa3b, v138
	v_exp_f32_e32 v138, v138
	s_nop 0
	v_add_f32_e32 v138, 1.0, v138
	v_rcp_f32_e32 v138, v138
	s_nop 0
	v_mul_f32_e32 v28, v28, v138
	v_and_b32_e32 v138, 0xffff0000, v152
	v_mul_f32_e32 v138, 0xbfb8aa3b, v138
	v_exp_f32_e32 v138, v138
	s_nop 0
	v_add_f32_e32 v138, 1.0, v138
	v_rcp_f32_e32 v138, v138
	s_nop 0
	v_mul_f32_e32 v29, v29, v138
	v_lshlrev_b32_e32 v138, 16, v153
	v_mul_f32_e32 v138, 0xbfb8aa3b, v138
	v_exp_f32_e32 v138, v138
	s_nop 0
	v_add_f32_e32 v138, 1.0, v138
	v_rcp_f32_e32 v138, v138
	s_nop 0
	v_mul_f32_e32 v30, v30, v138
	v_and_b32_e32 v138, 0xffff0000, v153
	v_mul_f32_e32 v138, 0xbfb8aa3b, v138
	v_exp_f32_e32 v138, v138
	s_nop 0
	v_add_f32_e32 v138, 1.0, v138
	v_rcp_f32_e32 v138, v138
	s_nop 0
	v_mul_f32_e32 v31, v31, v138
	v_lshlrev_b32_e32 v138, 16, v154
	v_mul_f32_e32 v138, 0xbfb8aa3b, v138
	v_exp_f32_e32 v138, v138
	s_nop 0
	v_add_f32_e32 v138, 1.0, v138
	v_rcp_f32_e32 v138, v138
	s_nop 0
	v_mul_f32_e32 v24, v24, v138
	v_and_b32_e32 v138, 0xffff0000, v154
	v_mul_f32_e32 v138, 0xbfb8aa3b, v138
	v_exp_f32_e32 v138, v138
	s_nop 0
	v_add_f32_e32 v138, 1.0, v138
	v_rcp_f32_e32 v138, v138
	s_nop 0
	v_mul_f32_e32 v25, v25, v138
	v_lshlrev_b32_e32 v138, 16, v155
	v_mul_f32_e32 v138, 0xbfb8aa3b, v138
	v_exp_f32_e32 v138, v138
	s_nop 0
	v_add_f32_e32 v138, 1.0, v138
	v_rcp_f32_e32 v138, v138
	s_nop 0
	v_mul_f32_e32 v26, v26, v138
	v_and_b32_e32 v138, 0xffff0000, v155
	v_mul_f32_e32 v138, 0xbfb8aa3b, v138
	v_exp_f32_e32 v138, v138
	s_nop 0
	v_add_f32_e32 v138, 1.0, v138
	v_rcp_f32_e32 v138, v138
	s_nop 0
	v_mul_f32_e32 v27, v27, v138
	v_mov_b32_e32 v152, v88
	s_nop 0
	v_ashrrev_i32_e32 v153, 31, v152
	v_lshlrev_b64 v[152:153], 13, v[152:153]
	v_lshl_add_u64 v[152:153], s[2:3], 0, v[152:153]
	v_lshl_add_u64 v[152:153], v[152:153], 0, v[64:65]
	s_waitcnt vmcnt(2)
	v_mov_b32_e32 v152, v218
	v_mov_b32_e32 v153, v219
	v_mov_b32_e32 v154, v220
	v_mov_b32_e32 v155, v221
	v_lshlrev_b32_e32 v138, 16, v152
	v_mul_f32_e32 v138, 0xbfb8aa3b, v138
	v_exp_f32_e32 v138, v138
	s_nop 0
	v_add_f32_e32 v138, 1.0, v138
	v_rcp_f32_e32 v138, v138
	s_nop 0
	v_mul_f32_e32 v20, v20, v138
	v_and_b32_e32 v138, 0xffff0000, v152
	v_mul_f32_e32 v138, 0xbfb8aa3b, v138
	v_exp_f32_e32 v138, v138
	s_nop 0
	v_add_f32_e32 v138, 1.0, v138
	v_rcp_f32_e32 v138, v138
	s_nop 0
	v_mul_f32_e32 v21, v21, v138
	v_lshlrev_b32_e32 v138, 16, v153
	v_mul_f32_e32 v138, 0xbfb8aa3b, v138
	v_exp_f32_e32 v138, v138
	s_nop 0
	v_add_f32_e32 v138, 1.0, v138
	v_rcp_f32_e32 v138, v138
	s_nop 0
	v_mul_f32_e32 v22, v22, v138
	v_and_b32_e32 v138, 0xffff0000, v153
	v_mul_f32_e32 v138, 0xbfb8aa3b, v138
	v_exp_f32_e32 v138, v138
	s_nop 0
	v_add_f32_e32 v138, 1.0, v138
	v_rcp_f32_e32 v138, v138
	s_nop 0
	v_mul_f32_e32 v23, v23, v138
	v_lshlrev_b32_e32 v138, 16, v154
	v_mul_f32_e32 v138, 0xbfb8aa3b, v138
	v_exp_f32_e32 v138, v138
	s_nop 0
	v_add_f32_e32 v138, 1.0, v138
	v_rcp_f32_e32 v138, v138
	s_nop 0
	v_mul_f32_e32 v16, v16, v138
	v_and_b32_e32 v138, 0xffff0000, v154
	v_mul_f32_e32 v138, 0xbfb8aa3b, v138
	v_exp_f32_e32 v138, v138
	s_nop 0
	v_add_f32_e32 v138, 1.0, v138
	v_rcp_f32_e32 v138, v138
	s_nop 0
	v_mul_f32_e32 v17, v17, v138
	v_lshlrev_b32_e32 v138, 16, v155
	v_mul_f32_e32 v138, 0xbfb8aa3b, v138
	v_exp_f32_e32 v138, v138
	s_nop 0
	v_add_f32_e32 v138, 1.0, v138
	v_rcp_f32_e32 v138, v138
	s_nop 0
	v_mul_f32_e32 v18, v18, v138
	v_and_b32_e32 v138, 0xffff0000, v155
	v_mul_f32_e32 v138, 0xbfb8aa3b, v138
	v_exp_f32_e32 v138, v138
	s_nop 0
	v_add_f32_e32 v138, 1.0, v138
	v_rcp_f32_e32 v138, v138
	s_nop 0
	v_mul_f32_e32 v19, v19, v138
	v_mov_b32_e32 v152, v80
	s_nop 0
	v_ashrrev_i32_e32 v153, 31, v152
	v_lshlrev_b64 v[152:153], 13, v[152:153]
	v_lshl_add_u64 v[152:153], s[2:3], 0, v[152:153]
	v_lshl_add_u64 v[152:153], v[152:153], 0, v[64:65]
	s_waitcnt vmcnt(1)
	v_mov_b32_e32 v152, v222
	v_mov_b32_e32 v153, v223
	v_mov_b32_e32 v154, v224
	v_mov_b32_e32 v155, v225
	v_lshlrev_b32_e32 v138, 16, v152
	v_mul_f32_e32 v138, 0xbfb8aa3b, v138
	v_exp_f32_e32 v138, v138
	s_nop 0
	v_add_f32_e32 v138, 1.0, v138
	v_rcp_f32_e32 v138, v138
	s_nop 0
	v_mul_f32_e32 v12, v12, v138
	v_and_b32_e32 v138, 0xffff0000, v152
	v_mul_f32_e32 v138, 0xbfb8aa3b, v138
	v_exp_f32_e32 v138, v138
	s_nop 0
	v_add_f32_e32 v138, 1.0, v138
	v_rcp_f32_e32 v138, v138
	s_nop 0
	v_mul_f32_e32 v13, v13, v138
	v_lshlrev_b32_e32 v138, 16, v153
	v_mul_f32_e32 v138, 0xbfb8aa3b, v138
	v_exp_f32_e32 v138, v138
	s_nop 0
	v_add_f32_e32 v138, 1.0, v138
	v_rcp_f32_e32 v138, v138
	s_nop 0
	v_mul_f32_e32 v14, v14, v138
	v_and_b32_e32 v138, 0xffff0000, v153
	v_mul_f32_e32 v138, 0xbfb8aa3b, v138
	v_exp_f32_e32 v138, v138
	s_nop 0
	v_add_f32_e32 v138, 1.0, v138
	v_rcp_f32_e32 v138, v138
	s_nop 0
	v_mul_f32_e32 v15, v15, v138
	v_lshlrev_b32_e32 v138, 16, v154
	v_mul_f32_e32 v138, 0xbfb8aa3b, v138
	v_exp_f32_e32 v138, v138
	s_nop 0
	v_add_f32_e32 v138, 1.0, v138
	v_rcp_f32_e32 v138, v138
	s_nop 0
	v_mul_f32_e32 v8, v8, v138
	v_and_b32_e32 v138, 0xffff0000, v154
	v_mul_f32_e32 v138, 0xbfb8aa3b, v138
	v_exp_f32_e32 v138, v138
	s_nop 0
	v_add_f32_e32 v138, 1.0, v138
	v_rcp_f32_e32 v138, v138
	s_nop 0
	v_mul_f32_e32 v9, v9, v138
	v_lshlrev_b32_e32 v138, 16, v155
	v_mul_f32_e32 v138, 0xbfb8aa3b, v138
	v_exp_f32_e32 v138, v138
	s_nop 0
	v_add_f32_e32 v138, 1.0, v138
	v_rcp_f32_e32 v138, v138
	s_nop 0
	v_mul_f32_e32 v10, v10, v138
	v_and_b32_e32 v138, 0xffff0000, v155
	v_mul_f32_e32 v138, 0xbfb8aa3b, v138
	v_exp_f32_e32 v138, v138
	s_nop 0
	v_add_f32_e32 v138, 1.0, v138
	v_rcp_f32_e32 v138, v138
	s_nop 0
	v_mul_f32_e32 v11, v11, v138
	v_mov_b32_e32 v152, v72
	s_nop 0
	v_ashrrev_i32_e32 v153, 31, v152
	v_lshlrev_b64 v[152:153], 13, v[152:153]
	v_lshl_add_u64 v[152:153], s[2:3], 0, v[152:153]
	v_lshl_add_u64 v[64:65], v[152:153], 0, v[64:65]
	s_waitcnt vmcnt(0)
; __device__ __forceinline__ float bf_lo(unsigned u) { return __uint_as_float(u << 16); }
; __device__ __forceinline__ float bf_hi(unsigned u) { return __uint_as_float(u & 0xffff0000u); }
; __device__ __forceinline__ float sigmoidf_(float x) { return frcp(1.0f + fexp2(-1.4426950408889634f * x)); }
; #define EPI_PIN(r) asm volatile("" : "+v"(r))
; #define EPI_FOR_BJ _Pragma("unroll") for (int bj = 0; bj < 2; ++bj)
; #define EPI_FOR_AM _Pragma("unroll") for (int ai = 0; ai < 2; ++ai) _Pragma("unroll") for (int m = 0; m < 4; ++m)
; __device__ __forceinline__ u32x4 pack8(const f32x4 a, const f32x4 b) { u32x4 o = {pk_bf16(a[0], a[1]), pk_bf16(a[2], a[3]), pk_bf16(b[0], b[1]), pk_bf16(b[2], b[3])}; return o; }
;     __device__ __forceinline__ void operator()(Acc& acc, const Unit& u, int wr, int wc, int fr, int fq) const {
;     ...
;                 for (int e = 0; e < 8; ++e) acc[ai][bj][m][e >> 2][e & 3] *= sigmoidf_((e & 1) ? bf_hi(ga[e >> 1]) : bf_lo(ga[e >> 1]));
;                 __builtin_amdgcn_sched_barrier(0); } }
;         EPI_FOR_BJ { const int c0 = EPI_COL(u, bj);
;             EPI_FOR_AM { int r = EPI_ROW(u, ai, m); EPI_PIN(r);
;                 *(u32x4*)(MG + (size_t)r * 1024 + c0) = pack8(acc[ai][bj][m][0], acc[ai][bj][m][1]);
;                 __builtin_amdgcn_sched_barrier(0); } }
	v_mov_b32_e32 v152, v226
	v_mov_b32_e32 v153, v227
	v_mov_b32_e32 v154, v228
	v_mov_b32_e32 v155, v229
	v_lshlrev_b32_e32 v64, 16, v152
	v_mul_f32_e32 v64, 0xbfb8aa3b, v64
	v_exp_f32_e32 v64, v64
	s_nop 0
	v_add_f32_e32 v64, 1.0, v64
	v_rcp_f32_e32 v64, v64
	s_nop 0
	v_mul_f32_e32 v4, v4, v64
	v_and_b32_e32 v64, 0xffff0000, v152
	v_mul_f32_e32 v64, 0xbfb8aa3b, v64
	v_exp_f32_e32 v64, v64
	s_nop 0
	v_add_f32_e32 v64, 1.0, v64
	v_rcp_f32_e32 v64, v64
	s_nop 0
	v_mul_f32_e32 v5, v5, v64
	v_lshlrev_b32_e32 v64, 16, v153
	v_mul_f32_e32 v64, 0xbfb8aa3b, v64
	v_exp_f32_e32 v64, v64
	s_nop 0
	v_add_f32_e32 v64, 1.0, v64
	v_rcp_f32_e32 v64, v64
	s_nop 0
	v_mul_f32_e32 v6, v6, v64
	v_and_b32_e32 v64, 0xffff0000, v153
	v_mul_f32_e32 v64, 0xbfb8aa3b, v64
	v_exp_f32_e32 v64, v64
	s_nop 0
	v_add_f32_e32 v64, 1.0, v64
	v_rcp_f32_e32 v64, v64
	s_nop 0
	v_mul_f32_e32 v7, v7, v64
	v_lshlrev_b32_e32 v64, 16, v154
	v_mul_f32_e32 v64, 0xbfb8aa3b, v64
	v_exp_f32_e32 v64, v64
	s_nop 0
	v_add_f32_e32 v64, 1.0, v64
	v_rcp_f32_e32 v64, v64
	s_nop 0
	v_mul_f32_e32 v138, v0, v64
	v_and_b32_e32 v0, 0xffff0000, v154
	v_mul_f32_e32 v0, 0xbfb8aa3b, v0
	v_exp_f32_e32 v0, v0
	s_nop 0
	v_add_f32_e32 v0, 1.0, v0
	v_rcp_f32_e32 v0, v0
	s_nop 0
	v_mul_f32_e32 v151, v1, v0
	v_lshlrev_b32_e32 v0, 16, v155
	v_mul_f32_e32 v0, 0xbfb8aa3b, v0
	v_exp_f32_e32 v0, v0
	s_nop 0
	v_add_f32_e32 v0, 1.0, v0
	v_rcp_f32_e32 v0, v0
	s_nop 0
	v_mul_f32_e32 v152, v2, v0
	v_and_b32_e32 v0, 0xffff0000, v155
	v_mul_f32_e32 v0, 0xbfb8aa3b, v0
	v_exp_f32_e32 v0, v0
	s_nop 0
	v_add_f32_e32 v0, 1.0, v0
	v_rcp_f32_e32 v0, v0
	s_nop 0
	v_mul_f32_e32 v153, v3, v0
	v_mov_b32_e32 v64, v136
	v_readlane_b32 s2, v248, 5
	v_ashrrev_i32_e32 v65, 31, v64
	v_lshlrev_b64 v[64:65], 11, v[64:65]
	v_readlane_b32 s3, v248, 6
	v_cvt_pk_bf16_f32 v0, v124, v125
	v_cvt_pk_bf16_f32 v1, v126, v127
	v_cvt_pk_bf16_f32 v2, v137, v121
	v_cvt_pk_bf16_f32 v3, v122, v123
	s_nop 1
	v_lshl_add_u64 v[64:65], s[2:3], 0, v[64:65]
	v_lshl_add_u64 v[64:65], v[64:65], 0, v[134:135]
	global_store_dwordx4 v[64:65], v[0:3], off
	v_mov_b32_e32 v64, v120
	s_nop 0
	v_cvt_pk_bf16_f32 v0, v116, v117
	v_cvt_pk_bf16_f32 v1, v118, v119
	v_cvt_pk_bf16_f32 v2, v139, v113
	v_cvt_pk_bf16_f32 v3, v114, v115
	v_ashrrev_i32_e32 v65, 31, v64
	v_lshlrev_b64 v[64:65], 11, v[64:65]
	v_lshl_add_u64 v[64:65], s[2:3], 0, v[64:65]
	v_lshl_add_u64 v[64:65], v[64:65], 0, v[134:135]
	global_store_dwordx4 v[64:65], v[0:3], off
	v_mov_b32_e32 v64, v112
	s_nop 0
	v_cvt_pk_bf16_f32 v0, v108, v109
	v_cvt_pk_bf16_f32 v1, v110, v111
	v_cvt_pk_bf16_f32 v2, v144, v105
	v_cvt_pk_bf16_f32 v3, v106, v107
	v_ashrrev_i32_e32 v65, 31, v64
	v_lshlrev_b64 v[64:65], 11, v[64:65]
	v_lshl_add_u64 v[64:65], s[2:3], 0, v[64:65]
	v_lshl_add_u64 v[64:65], v[64:65], 0, v[134:135]
	global_store_dwordx4 v[64:65], v[0:3], off
	v_mov_b32_e32 v64, v104
	s_nop 0
	v_cvt_pk_bf16_f32 v0, v100, v101
	v_cvt_pk_bf16_f32 v1, v102, v103
	v_cvt_pk_bf16_f32 v2, v145, v97
	v_cvt_pk_bf16_f32 v3, v98, v99
	v_ashrrev_i32_e32 v65, 31, v64
	v_lshlrev_b64 v[64:65], 11, v[64:65]
	v_lshl_add_u64 v[64:65], s[2:3], 0, v[64:65]
	v_lshl_add_u64 v[64:65], v[64:65], 0, v[134:135]
	global_store_dwordx4 v[64:65], v[0:3], off
	v_mov_b32_e32 v64, v96
	s_nop 0
	v_cvt_pk_bf16_f32 v0, v92, v93
	v_cvt_pk_bf16_f32 v1, v94, v95
	v_cvt_pk_bf16_f32 v2, v146, v89
	v_cvt_pk_bf16_f32 v3, v90, v91
	v_ashrrev_i32_e32 v65, 31, v64
	v_lshlrev_b64 v[64:65], 11, v[64:65]
	v_lshl_add_u64 v[64:65], s[2:3], 0, v[64:65]
	v_lshl_add_u64 v[64:65], v[64:65], 0, v[134:135]
	global_store_dwordx4 v[64:65], v[0:3], off
	v_mov_b32_e32 v64, v88
	s_nop 0
	v_cvt_pk_bf16_f32 v0, v84, v85
	v_cvt_pk_bf16_f32 v1, v86, v87
	v_cvt_pk_bf16_f32 v2, v147, v81
	v_cvt_pk_bf16_f32 v3, v82, v83
	v_ashrrev_i32_e32 v65, 31, v64
	v_lshlrev_b64 v[64:65], 11, v[64:65]
	v_lshl_add_u64 v[64:65], s[2:3], 0, v[64:65]
	v_lshl_add_u64 v[64:65], v[64:65], 0, v[134:135]
; #define PG8_WAIT_V(n) asm volatile("s_waitcnt vmcnt(" #n ")" ::: "memory")
; #define PG8_BAR __builtin_amdgcn_s_barrier()
; #define EPI_PIN(r) asm volatile("" : "+v"(r))
; #define EPI_FOR_BJ _Pragma("unroll") for (int bj = 0; bj < 2; ++bj)
; #define EPI_FOR_AM _Pragma("unroll") for (int ai = 0; ai < 2; ++ai) _Pragma("unroll") for (int m = 0; m < 4; ++m)
; __device__ __forceinline__ u32x4 pack8(const f32x4 a, const f32x4 b) { u32x4 o = {pk_bf16(a[0], a[1]), pk_bf16(a[2], a[3]), pk_bf16(b[0], b[1]), pk_bf16(b[2], b[3])}; return o; }
; template <class Epi, class Sched, bool GATHER = false>
; __device__ __forceinline__ void gemm_phase(LAS unsigned char* lds, const int K, const int lda, const Sched& S, const Epi& E, const int wid_s, const LAS int* rowoff = nullptr) {
;     ...
;         E(acc, cur, wr, wc, fr, fq);
;         if (!has_next) break;
; #pragma unroll
;         for (int a = 0; a < 2; ++a)
; #pragma unroll
;             for (int b = 0; b < 2; ++b)
; #pragma unroll
;                 for (int m = 0; m < 4; ++m)
; #pragma unroll
;                     for (int n = 0; n < 2; ++n) acc[a][b][m][n] = (f32x4){0.f, 0.f, 0.f, 0.f};
;         cur = nxt; cA = nA; cB = nB; ++ui;
;         if (GATHER) { _Pragma("unroll") for (int h_ = 0; h_ < 2; ++h_) _Pragma("unroll") for (int i_ = 0; i_ < 2; ++i_) gcur[h_][i_] = gnxt[h_][i_]; }
;     }
;     PG8_WAIT_V(0);
;     if (wr == 0) PG8_BAR;
;     PG8_BAR;
;     __device__ __forceinline__ void operator()(Acc& acc, const Unit& u, int wr, int wc, int fr, int fq) const {
;     ...
;         EPI_FOR_BJ { const int c0 = EPI_COL(u, bj);
;             EPI_FOR_AM { int r = EPI_ROW(u, ai, m); EPI_PIN(r);
;                 *(u32x4*)(MG + (size_t)r * 1024 + c0) = pack8(acc[ai][bj][m][0], acc[ai][bj][m][1]);
;                 __builtin_amdgcn_sched_barrier(0); } }
	global_store_dwordx4 v[64:65], v[0:3], off
	v_mov_b32_e32 v64, v80
	s_nop 0
	v_cvt_pk_bf16_f32 v0, v76, v77
	v_cvt_pk_bf16_f32 v1, v78, v79
	v_cvt_pk_bf16_f32 v2, v148, v73
	v_cvt_pk_bf16_f32 v3, v74, v75
	v_ashrrev_i32_e32 v65, 31, v64
	v_lshlrev_b64 v[64:65], 11, v[64:65]
	v_lshl_add_u64 v[64:65], s[2:3], 0, v[64:65]
	v_lshl_add_u64 v[64:65], v[64:65], 0, v[134:135]
	global_store_dwordx4 v[64:65], v[0:3], off
	v_mov_b32_e32 v64, v72
	s_nop 0
	v_cvt_pk_bf16_f32 v0, v68, v69
	v_cvt_pk_bf16_f32 v1, v70, v71
	v_cvt_pk_bf16_f32 v2, v149, v150
	v_cvt_pk_bf16_f32 v3, v66, v67
	v_ashrrev_i32_e32 v65, 31, v64
	v_lshlrev_b64 v[64:65], 11, v[64:65]
	v_lshl_add_u64 v[64:65], s[2:3], 0, v[64:65]
	v_lshl_add_u64 v[64:65], v[64:65], 0, v[134:135]
	global_store_dwordx4 v[64:65], v[0:3], off
	s_nop 1
	v_cvt_pk_bf16_f32 v2, v56, v57
	v_cvt_pk_bf16_f32 v0, v60, v61
	v_cvt_pk_bf16_f32 v1, v62, v63
	v_cvt_pk_bf16_f32 v3, v58, v59
	v_ashrrev_i32_e32 v137, 31, v136
	v_lshlrev_b64 v[56:57], 11, v[136:137]
	v_lshl_add_u64 v[56:57], s[2:3], 0, v[56:57]
	v_lshl_add_u64 v[56:57], v[56:57], 0, v[134:135]
	global_store_dwordx4 v[56:57], v[0:3], off offset:256
	s_nop 1
	v_cvt_pk_bf16_f32 v2, v48, v49
	v_cvt_pk_bf16_f32 v0, v52, v53
	v_cvt_pk_bf16_f32 v1, v54, v55
	v_cvt_pk_bf16_f32 v3, v50, v51
	v_ashrrev_i32_e32 v121, 31, v120
	v_lshlrev_b64 v[48:49], 11, v[120:121]
	v_lshl_add_u64 v[48:49], s[2:3], 0, v[48:49]
	v_lshl_add_u64 v[48:49], v[48:49], 0, v[134:135]
	global_store_dwordx4 v[48:49], v[0:3], off offset:256
	s_nop 1
	v_cvt_pk_bf16_f32 v2, v40, v41
	v_cvt_pk_bf16_f32 v0, v44, v45
	v_cvt_pk_bf16_f32 v1, v46, v47
	v_cvt_pk_bf16_f32 v3, v42, v43
	v_ashrrev_i32_e32 v113, 31, v112
	v_lshlrev_b64 v[40:41], 11, v[112:113]
	v_lshl_add_u64 v[40:41], s[2:3], 0, v[40:41]
	v_lshl_add_u64 v[40:41], v[40:41], 0, v[134:135]
	global_store_dwordx4 v[40:41], v[0:3], off offset:256
	s_nop 1
	v_cvt_pk_bf16_f32 v2, v32, v33
	v_cvt_pk_bf16_f32 v0, v36, v37
	v_cvt_pk_bf16_f32 v1, v38, v39
	v_cvt_pk_bf16_f32 v3, v34, v35
	v_ashrrev_i32_e32 v105, 31, v104
	v_lshlrev_b64 v[32:33], 11, v[104:105]
	v_lshl_add_u64 v[32:33], s[2:3], 0, v[32:33]
	v_lshl_add_u64 v[32:33], v[32:33], 0, v[134:135]
	global_store_dwordx4 v[32:33], v[0:3], off offset:256
	s_nop 1
	v_cvt_pk_bf16_f32 v2, v24, v25
	v_cvt_pk_bf16_f32 v0, v28, v29
	v_cvt_pk_bf16_f32 v1, v30, v31
	v_cvt_pk_bf16_f32 v3, v26, v27
	v_ashrrev_i32_e32 v97, 31, v96
	v_lshlrev_b64 v[24:25], 11, v[96:97]
	v_lshl_add_u64 v[24:25], s[2:3], 0, v[24:25]
	v_lshl_add_u64 v[24:25], v[24:25], 0, v[134:135]
	global_store_dwordx4 v[24:25], v[0:3], off offset:256
	s_nop 1
	v_cvt_pk_bf16_f32 v2, v16, v17
	v_cvt_pk_bf16_f32 v0, v20, v21
	v_cvt_pk_bf16_f32 v1, v22, v23
	v_cvt_pk_bf16_f32 v3, v18, v19
	v_ashrrev_i32_e32 v89, 31, v88
	v_lshlrev_b64 v[16:17], 11, v[88:89]
	v_lshl_add_u64 v[16:17], s[2:3], 0, v[16:17]
	v_lshl_add_u64 v[16:17], v[16:17], 0, v[134:135]
	global_store_dwordx4 v[16:17], v[0:3], off offset:256
	s_nop 1
	v_cvt_pk_bf16_f32 v2, v8, v9
	v_cvt_pk_bf16_f32 v0, v12, v13
	v_cvt_pk_bf16_f32 v1, v14, v15
	v_cvt_pk_bf16_f32 v3, v10, v11
	v_ashrrev_i32_e32 v81, 31, v80
	v_lshlrev_b64 v[8:9], 11, v[80:81]
	v_lshl_add_u64 v[8:9], s[2:3], 0, v[8:9]
	v_lshl_add_u64 v[8:9], v[8:9], 0, v[134:135]
	global_store_dwordx4 v[8:9], v[0:3], off offset:256
	s_nop 1
	v_cvt_pk_bf16_f32 v0, v4, v5
	v_cvt_pk_bf16_f32 v1, v6, v7
	v_cvt_pk_bf16_f32 v2, v138, v151
	v_cvt_pk_bf16_f32 v3, v152, v153
	v_ashrrev_i32_e32 v73, 31, v72
	v_lshlrev_b64 v[4:5], 11, v[72:73]
	v_lshl_add_u64 v[4:5], s[2:3], 0, v[4:5]
	v_lshl_add_u64 v[4:5], v[4:5], 0, v[134:135]
	global_store_dwordx4 v[4:5], v[0:3], off offset:256
	s_and_b64 vcc, exec, s[10:11]
	s_mov_b32 s16, s76
	s_mov_b32 s39, s6
	s_mov_b64 s[2:3], s[14:15]
	s_mov_b64 s[18:19], s[12:13]
	s_cbranch_vccz .LBB0_473
	v_readlane_b32 s2, v249, 43
	s_waitcnt vmcnt(0)
	v_readlane_b32 s3, v249, 44
	s_andn2_b64 vcc, exec, s[2:3]
	s_cbranch_vccnz .LBB0_484
	s_barrier

; #define PG8_STAGE(bufoff, gbase, voff) do { const char* _gb = (const char*)(gbase); asm volatile("" : "+s"(_gb)); _Pragma("unroll") for (int _i = 0; _i < 2; ++_i) \
;         __builtin_amdgcn_global_load_lds((const unsigned*)(_gb + (voff)[_i]), (LAS unsigned*)(lds + (bufoff) + ldsw + _i * 8192), 16, 0, 0); } while (0)
; #define PG8_STAGEA(bufoff, gbase, h_, usenext) do { if (GATHER) { unsigned go_[2] = {(usenext) ? gnxt[h_][0] : gcur[h_][0], (usenext) ? gnxt[h_][1] : gcur[h_][1]}; PG8_STAGE(bufoff, gbase, go_); } else PG8_STAGE(bufoff, (gbase) + (h_) * hstepA, voffA); } while (0)
; #define PG8_LDA(dst, b, h) do { _Pragma("unroll") for (int m = 0; m < 4; ++m) _Pragma("unroll") for (int k = 0; k < 2; ++k) dst[m][k] = *(const LAS bf16x8*)(lds + PG8_SA(b, h) + aoff + m * 2048 + k * 1024); } while (0)
; #define PG8_LDB(dst, b, h) do { _Pragma("unroll") for (int n = 0; n < 2; ++n) _Pragma("unroll") for (int k = 0; k < 2; ++k) dst[n][k] = *(const LAS bf16x8*)(lds + PG8_SB(b, h) + boff + n * 2048 + k * 1024); } while (0)
; #define PG8_WAIT_L(n) asm volatile("s_waitcnt lgkmcnt(" #n ")" ::: "memory")
; #define PG8_BAR __builtin_amdgcn_s_barrier()
; #define PG8_SCHED __builtin_amdgcn_sched_barrier(0)
; template <class Epi, class Sched, bool GATHER = false>
; __device__ __forceinline__ void gemm_phase(LAS unsigned char* lds, const int K, const int lda, const Sched& S, const Epi& E, const int wid_s, const LAS int* rowoff = nullptr) {
;     ...
;             const bool last = (t == nt - 2);
;             const char* a1 = cA + (size_t)(t + 1) * kstep;
;             const char* a2 = last ? nA : cA + (size_t)(t + 2) * kstep; const char* b2 = last ? nB : cB + (size_t)(t + 2) * kstep;
;             const char* a3 = a2 + kstep; const char* b3 = b2 + kstep;
;             PG8_LDB(B0, 0, 0); PG8_SCHED; PG8_LDA(At, 0, 0); PG8_STAGEA(PG8_SA(1, 1), a1, 1, false);
;             PG8_WAIT_L(8); PG8_BAR; PG8_WAIT_L(0); PG8_MMA(0, 0, At, B0); PG8_BAR; PG8_SCHED;
;             PG8_LDB(B1, 0, 1); PG8_STAGE(PG8_SB(0, 0), b2, voffB);
;             PG8_BAR; PG8_WAIT_L(0); PG8_MMA(0, 1, At, B1); PG8_BAR;
;             PG8_LDA(At, 0, 1); PG8_STAGEA(PG8_SA(0, 0), a2, 0, last);
;             PG8_BAR; PG8_WAIT_L(0); PG8_MMA(1, 0, At, B0); PG8_BAR; PG8_SCHED;
.LBB0_496:
	s_add_u32 s22, s20, 0x100
	s_addc_u32 s23, s21, 0
	s_cmp_eq_u32 s43, 4
	s_cselect_b32 s26, s14, s22
	s_cselect_b32 s27, s15, s23
	s_cselect_b32 s2, s16, s11
	s_cselect_b32 s3, s17, s42
	s_add_u32 s24, s26, 0x80
	s_addc_u32 s25, s27, 0
	s_add_i32 s44, 0, 0x10000
	v_add_u32_e32 v138, s44, v141
	ds_read_b128 v[134:137], v138
	ds_read_b128 v[144:147], v138 offset:1024
	ds_read_b128 v[148:151], v138 offset:2048
	ds_read_b128 v[152:155], v138 offset:3072
	s_add_u32 s20, s20, 0x40080
	s_addc_u32 s21, s21, 0
	ds_read_b128 v[156:159], v143
	ds_read_b128 v[160:163], v143 offset:1024
	ds_read_b128 v[164:167], v143 offset:2048
	ds_read_b128 v[168:171], v143 offset:3072
	ds_read_b128 v[172:175], v143 offset:4096
	ds_read_b128 v[176:179], v143 offset:5120
	ds_read_b128 v[180:183], v143 offset:6144
	ds_read_b128 v[184:187], v143 offset:7168
	s_add_i32 m0, s19, 0xc000
	v_lshl_add_u64 v[138:139], s[20:21], 0, v[132:133]
	global_load_lds_dwordx4 v[138:139], off
	v_lshl_add_u64 v[138:139], s[20:21], 0, v[130:131]
	s_add_i32 m0, s19, 0xe000
	s_nop 0
	global_load_lds_dwordx4 v[138:139], off
	s_waitcnt lgkmcnt(8)
	s_barrier
	s_waitcnt lgkmcnt(0)
	s_setprio 1
	s_waitcnt lgkmcnt(0)
	v_mfma_f32_16x16x32_bf16 v[124:127], v[134:137], v[156:159], v[124:127]
	v_mfma_f32_16x16x32_bf16 v[120:123], v[148:151], v[156:159], v[120:123]
	v_mfma_f32_16x16x32_bf16 v[116:119], v[134:137], v[164:167], v[116:119]
	v_mfma_f32_16x16x32_bf16 v[112:115], v[148:151], v[164:167], v[112:115]
	v_mfma_f32_16x16x32_bf16 v[108:111], v[134:137], v[172:175], v[108:111]
	v_mfma_f32_16x16x32_bf16 v[104:107], v[148:151], v[172:175], v[104:107]
	v_mfma_f32_16x16x32_bf16 v[100:103], v[134:137], v[180:183], v[100:103]
	v_mfma_f32_16x16x32_bf16 v[96:99], v[148:151], v[180:183], v[96:99]
	v_mfma_f32_16x16x32_bf16 v[124:127], v[144:147], v[160:163], v[124:127]
	v_mfma_f32_16x16x32_bf16 v[120:123], v[152:155], v[160:163], v[120:123]
	v_mfma_f32_16x16x32_bf16 v[116:119], v[144:147], v[168:171], v[116:119]
	v_mfma_f32_16x16x32_bf16 v[112:115], v[152:155], v[168:171], v[112:115]
	v_mfma_f32_16x16x32_bf16 v[108:111], v[144:147], v[176:179], v[108:111]
	v_mfma_f32_16x16x32_bf16 v[104:107], v[152:155], v[176:179], v[104:107]
	v_mfma_f32_16x16x32_bf16 v[100:103], v[144:147], v[184:187], v[100:103]
	v_mfma_f32_16x16x32_bf16 v[96:99], v[152:155], v[184:187], v[96:99]
	s_setprio 0
	s_barrier
	s_add_i32 s45, 0, 0x14000
	v_add_u32_e32 v138, s45, v141
	s_mov_b64 s[20:21], s[2:3]
	s_add_i32 s44, s44, s33
	ds_read_b128 v[188:191], v138
	ds_read_b128 v[192:195], v138 offset:1024
	ds_read_b128 v[196:199], v138 offset:2048
	ds_read_b128 v[206:209], v138 offset:3072
	s_mov_b32 m0, s44
	v_lshl_add_u64 v[138:139], s[20:21], 0, v[200:201]
	global_load_lds_dwordx4 v[138:139], off
	v_lshl_add_u64 v[138:139], s[20:21], 0, v[128:129]
	s_add_i32 m0, s44, 0x2000
	s_nop 0
	global_load_lds_dwordx4 v[138:139], off
	s_barrier
	s_waitcnt lgkmcnt(0)
	s_setprio 1
	s_waitcnt lgkmcnt(0)
	v_mfma_f32_16x16x32_bf16 v[60:63], v[188:191], v[156:159], v[60:63]
	v_mfma_f32_16x16x32_bf16 v[56:59], v[196:199], v[156:159], v[56:59]
	v_mfma_f32_16x16x32_bf16 v[52:55], v[188:191], v[164:167], v[52:55]
	v_mfma_f32_16x16x32_bf16 v[48:51], v[196:199], v[164:167], v[48:51]
	v_mfma_f32_16x16x32_bf16 v[44:47], v[188:191], v[172:175], v[44:47]
	v_mfma_f32_16x16x32_bf16 v[40:43], v[196:199], v[172:175], v[40:43]
	v_mfma_f32_16x16x32_bf16 v[36:39], v[188:191], v[180:183], v[36:39]
	v_mfma_f32_16x16x32_bf16 v[32:35], v[196:199], v[180:183], v[32:35]
	v_mfma_f32_16x16x32_bf16 v[60:63], v[192:195], v[160:163], v[60:63]
	v_mfma_f32_16x16x32_bf16 v[56:59], v[206:209], v[160:163], v[56:59]
	v_mfma_f32_16x16x32_bf16 v[52:55], v[192:195], v[168:171], v[52:55]
	v_mfma_f32_16x16x32_bf16 v[48:51], v[206:209], v[168:171], v[48:51]
	v_mfma_f32_16x16x32_bf16 v[44:47], v[192:195], v[176:179], v[44:47]
	v_mfma_f32_16x16x32_bf16 v[40:43], v[206:209], v[176:179], v[40:43]
	v_mfma_f32_16x16x32_bf16 v[36:39], v[192:195], v[184:187], v[36:39]
	v_mfma_f32_16x16x32_bf16 v[32:35], v[206:209], v[184:187], v[32:35]
	s_setprio 0
	s_mov_b64 s[20:21], s[26:27]
	s_mov_b32 m0, s19
	s_barrier
	ds_read_b128 v[156:159], v143 offset:16384
	ds_read_b128 v[160:163], v143 offset:17408
	ds_read_b128 v[164:167], v143 offset:18432
	ds_read_b128 v[168:171], v143 offset:19456
	ds_read_b128 v[172:175], v143 offset:20480
	ds_read_b128 v[176:179], v143 offset:21504
	ds_read_b128 v[180:183], v143 offset:22528
	ds_read_b128 v[184:187], v143 offset:23552
	s_nop 0
	v_lshl_add_u64 v[138:139], s[20:21], 0, v[132:133]
	global_load_lds_dwordx4 v[138:139], off
	v_lshl_add_u64 v[138:139], s[20:21], 0, v[130:131]
	s_mov_b32 m0, s35
	s_nop 0
	global_load_lds_dwordx4 v[138:139], off
	s_barrier
	s_waitcnt lgkmcnt(0)
	s_setprio 1
	s_waitcnt lgkmcnt(0)
	v_mfma_f32_16x16x32_bf16 v[92:95], v[134:137], v[156:159], v[92:95]
	v_mfma_f32_16x16x32_bf16 v[88:91], v[148:151], v[156:159], v[88:91]
	v_mfma_f32_16x16x32_bf16 v[84:87], v[134:137], v[164:167], v[84:87]
	v_mfma_f32_16x16x32_bf16 v[80:83], v[148:151], v[164:167], v[80:83]
	v_mfma_f32_16x16x32_bf16 v[76:79], v[134:137], v[172:175], v[76:79]
	v_mfma_f32_16x16x32_bf16 v[72:75], v[148:151], v[172:175], v[72:75]
	v_mfma_f32_16x16x32_bf16 v[68:71], v[134:137], v[180:183], v[68:71]
	v_mfma_f32_16x16x32_bf16 v[64:67], v[148:151], v[180:183], v[64:67]
	v_mfma_f32_16x16x32_bf16 v[92:95], v[144:147], v[160:163], v[92:95]
	v_mfma_f32_16x16x32_bf16 v[88:91], v[152:155], v[160:163], v[88:91]
	v_mfma_f32_16x16x32_bf16 v[84:87], v[144:147], v[168:171], v[84:87]
	v_mfma_f32_16x16x32_bf16 v[80:83], v[152:155], v[168:171], v[80:83]
	v_mfma_f32_16x16x32_bf16 v[76:79], v[144:147], v[176:179], v[76:79]
	v_mfma_f32_16x16x32_bf16 v[72:75], v[152:155], v[176:179], v[72:75]
	v_mfma_f32_16x16x32_bf16 v[68:71], v[144:147], v[184:187], v[68:71]
	v_mfma_f32_16x16x32_bf16 v[64:67], v[152:155], v[184:187], v[64:67]
	s_setprio 0
	s_barrier
; #define PG8_STAGE(bufoff, gbase, voff) do { const char* _gb = (const char*)(gbase); asm volatile("" : "+s"(_gb)); _Pragma("unroll") for (int _i = 0; _i < 2; ++_i) \
;         __builtin_amdgcn_global_load_lds((const unsigned*)(_gb + (voff)[_i]), (LAS unsigned*)(lds + (bufoff) + ldsw + _i * 8192), 16, 0, 0); } while (0)
; #define PG8_STAGEA(bufoff, gbase, h_, usenext) do { if (GATHER) { unsigned go_[2] = {(usenext) ? gnxt[h_][0] : gcur[h_][0], (usenext) ? gnxt[h_][1] : gcur[h_][1]}; PG8_STAGE(bufoff, gbase, go_); } else PG8_STAGE(bufoff, (gbase) + (h_) * hstepA, voffA); } while (0)
; #define PG8_LDA(dst, b, h) do { _Pragma("unroll") for (int m = 0; m < 4; ++m) _Pragma("unroll") for (int k = 0; k < 2; ++k) dst[m][k] = *(const LAS bf16x8*)(lds + PG8_SA(b, h) + aoff + m * 2048 + k * 1024); } while (0)
; #define PG8_LDB(dst, b, h) do { _Pragma("unroll") for (int n = 0; n < 2; ++n) _Pragma("unroll") for (int k = 0; k < 2; ++k) dst[n][k] = *(const LAS bf16x8*)(lds + PG8_SB(b, h) + boff + n * 2048 + k * 1024); } while (0)
; #define PG8_MMA(ai, bj, At, Bt) do { __builtin_amdgcn_s_setprio(1); _Pragma("unroll") for (int m = 0; m < 4; ++m) _Pragma("unroll") for (int n = 0; n < 2; ++n) _Pragma("unroll") for (int k = 0; k < 2; ++k) \
;         acc[ai][bj][m][n] = __builtin_amdgcn_mfma_f32_16x16x32_bf16(Bt[n][k], At[m][k], acc[ai][bj][m][n], 0, 0, 0); __builtin_amdgcn_s_setprio(0); } while (0)
; #define PG8_WAIT_V(n) asm volatile("s_waitcnt vmcnt(" #n ")" ::: "memory")
; #define PG8_WAIT_L(n) asm volatile("s_waitcnt lgkmcnt(" #n ")" ::: "memory")
; #define PG8_BAR __builtin_amdgcn_s_barrier()
; #define PG8_SCHED __builtin_amdgcn_sched_barrier(0)
; template <class Epi, class Sched, bool GATHER = false>
; __device__ __forceinline__ void gemm_phase(LAS unsigned char* lds, const int K, const int lda, const Sched& S, const Epi& E, const int wid_s, const LAS int* rowoff = nullptr) {
;     ...
;             PG8_STAGE(PG8_SB(0, 1), b2 + hstepB, voffB);
;             PG8_WAIT_V(6); PG8_BAR; PG8_MMA(1, 1, At, B1); PG8_BAR;
;             PG8_LDB(B0, 1, 0); PG8_SCHED; PG8_LDA(At, 1, 0); PG8_STAGEA(PG8_SA(0, 1), a2, 1, last);
;             PG8_WAIT_L(8); PG8_BAR; PG8_WAIT_L(0); PG8_MMA(0, 0, At, B0); PG8_BAR; PG8_SCHED;
;             PG8_LDB(B1, 1, 1); PG8_STAGE(PG8_SB(1, 0), b3, voffB);
;             PG8_BAR; PG8_WAIT_L(0); PG8_MMA(0, 1, At, B1); PG8_BAR;
	s_add_u32 s20, s2, 0x20000
	s_addc_u32 s21, s3, 0
	s_add_i32 s44, s45, s33
	s_mov_b32 m0, s44
	v_lshl_add_u64 v[134:135], s[20:21], 0, v[200:201]
	global_load_lds_dwordx4 v[134:135], off
	v_lshl_add_u64 v[134:135], s[20:21], 0, v[128:129]
	s_add_i32 m0, s44, 0x2000
	s_nop 0
	global_load_lds_dwordx4 v[134:135], off
	s_waitcnt vmcnt(6)
	s_barrier
	s_setprio 1
	v_mfma_f32_16x16x32_bf16 v[28:31], v[188:191], v[156:159], v[28:31]
	v_mfma_f32_16x16x32_bf16 v[24:27], v[196:199], v[156:159], v[24:27]
	v_mfma_f32_16x16x32_bf16 v[20:23], v[188:191], v[164:167], v[20:23]
	v_mfma_f32_16x16x32_bf16 v[16:19], v[196:199], v[164:167], v[16:19]
	v_mfma_f32_16x16x32_bf16 v[12:15], v[188:191], v[172:175], v[12:15]
	v_mfma_f32_16x16x32_bf16 v[8:11], v[196:199], v[172:175], v[8:11]
	v_mfma_f32_16x16x32_bf16 v[4:7], v[188:191], v[180:183], v[4:7]
	v_mfma_f32_16x16x32_bf16 v[0:3], v[196:199], v[180:183], v[0:3]
	v_mfma_f32_16x16x32_bf16 v[28:31], v[192:195], v[160:163], v[28:31]
	v_mfma_f32_16x16x32_bf16 v[24:27], v[206:209], v[160:163], v[24:27]
	v_mfma_f32_16x16x32_bf16 v[20:23], v[192:195], v[168:171], v[20:23]
	v_mfma_f32_16x16x32_bf16 v[16:19], v[206:209], v[168:171], v[16:19]
	v_mfma_f32_16x16x32_bf16 v[12:15], v[192:195], v[176:179], v[12:15]
	v_mfma_f32_16x16x32_bf16 v[8:11], v[206:209], v[176:179], v[8:11]
	v_mfma_f32_16x16x32_bf16 v[4:7], v[192:195], v[184:187], v[4:7]
	v_mfma_f32_16x16x32_bf16 v[0:3], v[206:209], v[184:187], v[0:3]
	s_setprio 0
	s_add_i32 s44, 0, 0x18000
	v_add_u32_e32 v138, s44, v141
	s_barrier
	ds_read_b128 v[134:137], v138
	ds_read_b128 v[144:147], v138 offset:1024
	ds_read_b128 v[148:151], v138 offset:2048
	ds_read_b128 v[152:155], v138 offset:3072
	s_add_u32 s20, s26, 0x40000
	s_addc_u32 s21, s27, 0
	s_mov_b32 m0, s36
	ds_read_b128 v[156:159], v143 offset:32768
	ds_read_b128 v[160:163], v143 offset:33792
	ds_read_b128 v[164:167], v143 offset:34816
	ds_read_b128 v[168:171], v143 offset:35840
	ds_read_b128 v[172:175], v143 offset:36864
	ds_read_b128 v[176:179], v143 offset:37888
	ds_read_b128 v[180:183], v143 offset:38912
	ds_read_b128 v[184:187], v143 offset:39936
	s_nop 0
	v_lshl_add_u64 v[138:139], s[20:21], 0, v[132:133]
	global_load_lds_dwordx4 v[138:139], off
	v_lshl_add_u64 v[138:139], s[20:21], 0, v[130:131]
	s_mov_b32 m0, s37
	s_nop 0
	global_load_lds_dwordx4 v[138:139], off
	s_waitcnt lgkmcnt(8)
	s_barrier
	s_waitcnt lgkmcnt(0)
	s_setprio 1
	s_waitcnt lgkmcnt(0)
	v_mfma_f32_16x16x32_bf16 v[124:127], v[134:137], v[156:159], v[124:127]
	v_mfma_f32_16x16x32_bf16 v[120:123], v[148:151], v[156:159], v[120:123]
	v_mfma_f32_16x16x32_bf16 v[116:119], v[134:137], v[164:167], v[116:119]
	v_mfma_f32_16x16x32_bf16 v[112:115], v[148:151], v[164:167], v[112:115]
	v_mfma_f32_16x16x32_bf16 v[108:111], v[134:137], v[172:175], v[108:111]
	v_mfma_f32_16x16x32_bf16 v[104:107], v[148:151], v[172:175], v[104:107]
	v_mfma_f32_16x16x32_bf16 v[100:103], v[134:137], v[180:183], v[100:103]
	v_mfma_f32_16x16x32_bf16 v[96:99], v[148:151], v[180:183], v[96:99]
	v_mfma_f32_16x16x32_bf16 v[124:127], v[144:147], v[160:163], v[124:127]
	v_mfma_f32_16x16x32_bf16 v[120:123], v[152:155], v[160:163], v[120:123]
	v_mfma_f32_16x16x32_bf16 v[116:119], v[144:147], v[168:171], v[116:119]
	v_mfma_f32_16x16x32_bf16 v[112:115], v[152:155], v[168:171], v[112:115]
	v_mfma_f32_16x16x32_bf16 v[108:111], v[144:147], v[176:179], v[108:111]
	v_mfma_f32_16x16x32_bf16 v[104:107], v[152:155], v[176:179], v[104:107]
	v_mfma_f32_16x16x32_bf16 v[100:103], v[144:147], v[184:187], v[100:103]
	v_mfma_f32_16x16x32_bf16 v[96:99], v[152:155], v[184:187], v[96:99]
	s_setprio 0
	s_barrier
	s_add_i32 s26, 0, 0x1c000
	s_add_u32 s20, s2, 0x80
	v_add_u32_e32 v138, s26, v141
	s_addc_u32 s21, s3, 0
	s_add_i32 s27, s44, s33
	ds_read_b128 v[188:191], v138
	ds_read_b128 v[192:195], v138 offset:1024
	ds_read_b128 v[196:199], v138 offset:2048
	ds_read_b128 v[206:209], v138 offset:3072
	s_mov_b32 m0, s27
	v_lshl_add_u64 v[138:139], s[20:21], 0, v[200:201]
	global_load_lds_dwordx4 v[138:139], off
	v_lshl_add_u64 v[138:139], s[20:21], 0, v[128:129]
	s_add_i32 m0, s27, 0x2000
	s_nop 0
	global_load_lds_dwordx4 v[138:139], off
	s_barrier
	s_waitcnt lgkmcnt(0)
	s_setprio 1
	s_waitcnt lgkmcnt(0)
	v_mfma_f32_16x16x32_bf16 v[60:63], v[188:191], v[156:159], v[60:63]
	v_mfma_f32_16x16x32_bf16 v[56:59], v[196:199], v[156:159], v[56:59]
	v_mfma_f32_16x16x32_bf16 v[52:55], v[188:191], v[164:167], v[52:55]
	v_mfma_f32_16x16x32_bf16 v[48:51], v[196:199], v[164:167], v[48:51]
	v_mfma_f32_16x16x32_bf16 v[44:47], v[188:191], v[172:175], v[44:47]
	v_mfma_f32_16x16x32_bf16 v[40:43], v[196:199], v[172:175], v[40:43]
	v_mfma_f32_16x16x32_bf16 v[36:39], v[188:191], v[180:183], v[36:39]
	v_mfma_f32_16x16x32_bf16 v[32:35], v[196:199], v[180:183], v[32:35]
	v_mfma_f32_16x16x32_bf16 v[60:63], v[192:195], v[160:163], v[60:63]
	v_mfma_f32_16x16x32_bf16 v[56:59], v[206:209], v[160:163], v[56:59]
	v_mfma_f32_16x16x32_bf16 v[52:55], v[192:195], v[168:171], v[52:55]
	v_mfma_f32_16x16x32_bf16 v[48:51], v[206:209], v[168:171], v[48:51]
	v_mfma_f32_16x16x32_bf16 v[44:47], v[192:195], v[176:179], v[44:47]
	v_mfma_f32_16x16x32_bf16 v[40:43], v[206:209], v[176:179], v[40:43]
	v_mfma_f32_16x16x32_bf16 v[36:39], v[192:195], v[184:187], v[36:39]
	v_mfma_f32_16x16x32_bf16 v[32:35], v[206:209], v[184:187], v[32:35]
	s_setprio 0
	s_mov_b32 m0, s38
	s_barrier
; __device__ __forceinline__ float bf_lo(unsigned u) { return __uint_as_float(u << 16); }
; __device__ __forceinline__ float bf_hi(unsigned u) { return __uint_as_float(u & 0xffff0000u); }
; __device__ __forceinline__ float sigmoidf_(float x) { return frcp(1.0f + fexp2(-1.4426950408889634f * x)); }
; #define PG8_STAGE(bufoff, gbase, voff) do { const char* _gb = (const char*)(gbase); asm volatile("" : "+s"(_gb)); _Pragma("unroll") for (int _i = 0; _i < 2; ++_i) \
;         __builtin_amdgcn_global_load_lds((const unsigned*)(_gb + (voff)[_i]), (LAS unsigned*)(lds + (bufoff) + ldsw + _i * 8192), 16, 0, 0); } while (0)
; #define PG8_STAGEA(bufoff, gbase, h_, usenext) do { if (GATHER) { unsigned go_[2] = {(usenext) ? gnxt[h_][0] : gcur[h_][0], (usenext) ? gnxt[h_][1] : gcur[h_][1]}; PG8_STAGE(bufoff, gbase, go_); } else PG8_STAGE(bufoff, (gbase) + (h_) * hstepA, voffA); } while (0)
; #define PG8_LDA(dst, b, h) do { _Pragma("unroll") for (int m = 0; m < 4; ++m) _Pragma("unroll") for (int k = 0; k < 2; ++k) dst[m][k] = *(const LAS bf16x8*)(lds + PG8_SA(b, h) + aoff + m * 2048 + k * 1024); } while (0)
; #define PG8_WAIT_V(n) asm volatile("s_waitcnt vmcnt(" #n ")" ::: "memory")
; #define PG8_BAR __builtin_amdgcn_s_barrier()
; template <class Epi, class Sched, bool GATHER = false>
; __device__ __forceinline__ void gemm_phase(LAS unsigned char* lds, const int K, const int lda, const Sched& S, const Epi& E, const int wid_s, const LAS int* rowoff = nullptr) {
;     ...
;             PG8_LDA(At, 1, 1); PG8_STAGEA(PG8_SA(1, 0), a3, 0, last);
;             PG8_BAR; PG8_WAIT_L(0); PG8_MMA(1, 0, At, B0); PG8_BAR; PG8_SCHED;
;             PG8_STAGE(PG8_SB(1, 1), b3 + hstepB, voffB);
;             PG8_WAIT_V(6); PG8_BAR; PG8_MMA(1, 1, At, B1); PG8_BAR;
;     __device__ __forceinline__ void operator()(Acc& acc, const Unit& u, int wr, int wc, int fr, int fq) const {
;         EPI_FOR_BJ { const int c0 = EPI_COL(u, bj);
;             EPI_FOR_AM { int r = EPI_ROW(u, ai, m); EPI_PIN(r);
;                 const u32x4 gb = *(const u32x4*)(P + (size_t)r * INWP + OFF_GB + c0);
;                 const u32x4 mo = *(const u32x4*)(MG + (size_t)r * 1024 + c0);
; #pragma unroll
;                 for (int e = 0; e < 8; ++e) {
;                     const float g = sigmoidf_((e & 1) ? bf_hi(gb[e >> 1]) : bf_lo(gb[e >> 1])), o = (e & 1) ? bf_hi(mo[e >> 1]) : bf_lo(mo[e >> 1]);
	ds_read_b128 v[156:159], v143 offset:49152
	ds_read_b128 v[160:163], v143 offset:50176
	ds_read_b128 v[164:167], v143 offset:51200
	ds_read_b128 v[168:171], v143 offset:52224
	ds_read_b128 v[172:175], v143 offset:53248
	ds_read_b128 v[176:179], v143 offset:54272
	ds_read_b128 v[180:183], v143 offset:55296
	ds_read_b128 v[184:187], v143 offset:56320
	s_nop 0
	v_lshl_add_u64 v[138:139], s[24:25], 0, v[132:133]
	global_load_lds_dwordx4 v[138:139], off
	v_lshl_add_u64 v[138:139], s[24:25], 0, v[130:131]
	s_mov_b32 m0, s39
	s_nop 0
	global_load_lds_dwordx4 v[138:139], off
	s_barrier
	s_waitcnt lgkmcnt(0)
	s_setprio 1
	s_waitcnt lgkmcnt(0)
	v_mfma_f32_16x16x32_bf16 v[92:95], v[134:137], v[156:159], v[92:95]
	v_mfma_f32_16x16x32_bf16 v[88:91], v[148:151], v[156:159], v[88:91]
	v_mfma_f32_16x16x32_bf16 v[84:87], v[134:137], v[164:167], v[84:87]
	v_mfma_f32_16x16x32_bf16 v[80:83], v[148:151], v[164:167], v[80:83]
	v_mfma_f32_16x16x32_bf16 v[76:79], v[134:137], v[172:175], v[76:79]
	v_mfma_f32_16x16x32_bf16 v[72:75], v[148:151], v[172:175], v[72:75]
	v_mfma_f32_16x16x32_bf16 v[68:71], v[134:137], v[180:183], v[68:71]
	v_mfma_f32_16x16x32_bf16 v[64:67], v[148:151], v[180:183], v[64:67]
	v_mfma_f32_16x16x32_bf16 v[92:95], v[144:147], v[160:163], v[92:95]
	v_mfma_f32_16x16x32_bf16 v[88:91], v[152:155], v[160:163], v[88:91]
	v_mfma_f32_16x16x32_bf16 v[84:87], v[144:147], v[168:171], v[84:87]
	v_mfma_f32_16x16x32_bf16 v[80:83], v[152:155], v[168:171], v[80:83]
	v_mfma_f32_16x16x32_bf16 v[76:79], v[144:147], v[176:179], v[76:79]
	v_mfma_f32_16x16x32_bf16 v[72:75], v[152:155], v[176:179], v[72:75]
	v_mfma_f32_16x16x32_bf16 v[68:71], v[144:147], v[184:187], v[68:71]
	v_mfma_f32_16x16x32_bf16 v[64:67], v[152:155], v[184:187], v[64:67]
	s_setprio 0
	s_barrier
	s_add_u32 s2, s2, 0x20080
	s_addc_u32 s3, s3, 0
	s_add_i32 s20, s26, s33
	s_mov_b32 m0, s20
	v_lshl_add_u64 v[134:135], s[2:3], 0, v[200:201]
	global_load_lds_dwordx4 v[134:135], off
	v_lshl_add_u64 v[134:135], s[2:3], 0, v[128:129]
	s_add_i32 m0, s20, 0x2000
	s_nop 0
	global_load_lds_dwordx4 v[134:135], off
	s_waitcnt vmcnt(6)
	s_barrier
	s_setprio 1
	v_mfma_f32_16x16x32_bf16 v[28:31], v[188:191], v[156:159], v[28:31]
	v_mfma_f32_16x16x32_bf16 v[24:27], v[196:199], v[156:159], v[24:27]
	v_mfma_f32_16x16x32_bf16 v[20:23], v[188:191], v[164:167], v[20:23]
	v_mfma_f32_16x16x32_bf16 v[16:19], v[196:199], v[164:167], v[16:19]
	v_mfma_f32_16x16x32_bf16 v[12:15], v[188:191], v[172:175], v[12:15]
	v_mfma_f32_16x16x32_bf16 v[8:11], v[196:199], v[172:175], v[8:11]
	v_mfma_f32_16x16x32_bf16 v[4:7], v[188:191], v[180:183], v[4:7]
	v_mfma_f32_16x16x32_bf16 v[0:3], v[196:199], v[180:183], v[0:3]
	v_mfma_f32_16x16x32_bf16 v[28:31], v[192:195], v[160:163], v[28:31]
	v_mfma_f32_16x16x32_bf16 v[24:27], v[206:209], v[160:163], v[24:27]
	v_mfma_f32_16x16x32_bf16 v[20:23], v[192:195], v[168:171], v[20:23]
	v_mfma_f32_16x16x32_bf16 v[16:19], v[206:209], v[168:171], v[16:19]
	v_mfma_f32_16x16x32_bf16 v[12:15], v[192:195], v[176:179], v[12:15]
	v_mfma_f32_16x16x32_bf16 v[8:11], v[206:209], v[176:179], v[8:11]
	v_mfma_f32_16x16x32_bf16 v[4:7], v[192:195], v[184:187], v[4:7]
	v_mfma_f32_16x16x32_bf16 v[0:3], v[206:209], v[184:187], v[0:3]
	s_setprio 0
	s_add_i32 s43, s43, 2
	s_add_u32 s11, s11, 0x100
	s_addc_u32 s42, s42, 0
	s_cmp_gt_u32 s43, 5
	s_mov_b64 s[20:21], s[22:23]
	s_barrier
	s_cbranch_scc0 .LBB0_496
	v_lshl_add_u32 v136, s18, 8, v140
	v_mov_b32_e32 v148, v136
	v_lshl_or_b32 v138, s41, 8, v142
	v_readlane_b32 s2, v249, 34
	v_ashrrev_i32_e32 v149, 31, v148
	v_ashrrev_i32_e32 v139, 31, v138
	v_lshlrev_b64 v[134:135], 13, v[148:149]
	v_readlane_b32 s3, v249, 35
	v_readlane_b32 s20, v248, 5
	v_lshlrev_b64 v[148:149], 11, v[148:149]
	v_lshl_add_u64 v[144:145], s[2:3], 0, v[134:135]
	v_lshlrev_b64 v[134:135], 1, v[138:139]
	v_lshl_add_u64 v[144:145], v[144:145], 0, v[134:135]
	v_add_co_u32_e32 v144, vcc, 0x1000, v144
	v_readlane_b32 s21, v248, 6
	s_nop 0
	v_addc_co_u32_e32 v145, vcc, 0, v145, vcc
	v_lshl_add_u64 v[148:149], s[20:21], 0, v[148:149]
	v_lshl_add_u64 v[148:149], v[148:149], 0, v[134:135]
	v_mov_b32_e32 v198, v144
	v_mov_b32_e32 v199, v145
	v_mov_b32_e32 v230, v148
	v_mov_b32_e32 v231, v149
	s_mov_b32 s87, 0
	s_mov_b32 s89, 0
	s_mov_b32 s86, 0x0
	v_lshl_add_u64 v[196:197], v[198:199], 0, s[86:87]
	global_load_dwordx4 v[160:163], v[196:197], off offset:1856
	s_mov_b32 s88, 0x0
	v_lshl_add_u64 v[196:197], v[230:231], 0, s[88:89]
	global_load_dwordx4 v[164:167], v[196:197], off
	s_mov_b32 s86, 0x20000
	v_lshl_add_u64 v[196:197], v[198:199], 0, s[86:87]
	global_load_dwordx4 v[168:171], v[196:197], off offset:1856
	s_mov_b32 s88, 0x8000
	v_lshl_add_u64 v[196:197], v[230:231], 0, s[88:89]
	global_load_dwordx4 v[172:175], v[196:197], off
	s_mov_b32 s86, 0x40000
	v_lshl_add_u64 v[196:197], v[198:199], 0, s[86:87]
	global_load_dwordx4 v[176:179], v[196:197], off offset:1856
	s_mov_b32 s88, 0x10000
	v_lshl_add_u64 v[196:197], v[230:231], 0, s[88:89]
	global_load_dwordx4 v[180:183], v[196:197], off
	s_mov_b32 s86, 0x60000
	v_lshl_add_u64 v[196:197], v[198:199], 0, s[86:87]
	global_load_dwordx4 v[184:187], v[196:197], off offset:1856
	s_mov_b32 s88, 0x18000
	v_lshl_add_u64 v[196:197], v[230:231], 0, s[88:89]
	global_load_dwordx4 v[188:191], v[196:197], off
	s_mov_b32 s86, 0x100000
	v_lshl_add_u64 v[196:197], v[198:199], 0, s[86:87]
	global_load_dwordx4 v[192:195], v[196:197], off offset:1856
	s_mov_b32 s88, 0x40000
	v_lshl_add_u64 v[196:197], v[230:231], 0, s[88:89]
	global_load_dwordx4 v[206:209], v[196:197], off
	s_mov_b32 s86, 0x120000
	v_lshl_add_u64 v[196:197], v[198:199], 0, s[86:87]
	global_load_dwordx4 v[210:213], v[196:197], off offset:1856
	s_mov_b32 s88, 0x48000
	v_lshl_add_u64 v[196:197], v[230:231], 0, s[88:89]
	global_load_dwordx4 v[214:217], v[196:197], off
	s_mov_b32 s86, 0x140000
	v_lshl_add_u64 v[196:197], v[198:199], 0, s[86:87]
	global_load_dwordx4 v[218:221], v[196:197], off offset:1856
	s_mov_b32 s88, 0x50000
	v_lshl_add_u64 v[196:197], v[230:231], 0, s[88:89]
	global_load_dwordx4 v[222:225], v[196:197], off
	s_waitcnt vmcnt(12)
; __device__ __forceinline__ float bf_lo(unsigned u) { return __uint_as_float(u << 16); }
; __device__ __forceinline__ float bf_hi(unsigned u) { return __uint_as_float(u & 0xffff0000u); }
; __device__ __forceinline__ float sigmoidf_(float x) { return frcp(1.0f + fexp2(-1.4426950408889634f * x)); }
; #define EPI_PIN(r) asm volatile("" : "+v"(r))
; #define EPI_FOR_BJ _Pragma("unroll") for (int bj = 0; bj < 2; ++bj)
; #define EPI_FOR_AM _Pragma("unroll") for (int ai = 0; ai < 2; ++ai) _Pragma("unroll") for (int m = 0; m < 4; ++m)
;     __device__ __forceinline__ void operator()(Acc& acc, const Unit& u, int wr, int wc, int fr, int fq) const {
;         EPI_FOR_BJ { const int c0 = EPI_COL(u, bj);
;             EPI_FOR_AM { int r = EPI_ROW(u, ai, m); EPI_PIN(r);
;                 const u32x4 gb = *(const u32x4*)(P + (size_t)r * INWP + OFF_GB + c0);
;                 const u32x4 mo = *(const u32x4*)(MG + (size_t)r * 1024 + c0);
; #pragma unroll
;                 for (int e = 0; e < 8; ++e) {
;                     const float g = sigmoidf_((e & 1) ? bf_hi(gb[e >> 1]) : bf_lo(gb[e >> 1])), o = (e & 1) ? bf_hi(mo[e >> 1]) : bf_lo(mo[e >> 1]);
;                     acc[ai][bj][m][e >> 2][e & 3] = o + acc[ai][bj][m][e >> 2][e & 3] * g;
;                 }
;                 __builtin_amdgcn_sched_barrier(0); } }
	v_mov_b32_e32 v144, v160
	v_mov_b32_e32 v145, v161
	v_mov_b32_e32 v146, v162
	v_mov_b32_e32 v147, v163
	v_mov_b32_e32 v148, v164
	v_mov_b32_e32 v149, v165
	v_mov_b32_e32 v150, v166
	v_mov_b32_e32 v151, v167
	v_lshlrev_b32_e32 v137, 16, v144
	v_mul_f32_e32 v137, 0xbfb8aa3b, v137
	v_exp_f32_e32 v137, v137
	s_nop 0
	v_add_f32_e32 v137, 1.0, v137
	v_rcp_f32_e32 v139, v137
	v_lshlrev_b32_e32 v137, 16, v148
	v_fmac_f32_e32 v137, v124, v139
	v_and_b32_e32 v124, 0xffff0000, v144
	v_mul_f32_e32 v124, 0xbfb8aa3b, v124
	v_exp_f32_e32 v124, v124
	s_nop 0
	v_add_f32_e32 v124, 1.0, v124
	v_rcp_f32_e32 v139, v124
	v_and_b32_e32 v124, 0xffff0000, v148
	v_fmac_f32_e32 v124, v125, v139
	v_lshlrev_b32_e32 v125, 16, v145
	v_mul_f32_e32 v125, 0xbfb8aa3b, v125
	v_exp_f32_e32 v125, v125
	s_nop 0
	v_add_f32_e32 v125, 1.0, v125
	v_rcp_f32_e32 v139, v125
	v_lshlrev_b32_e32 v125, 16, v149
	v_fmac_f32_e32 v125, v126, v139
	v_and_b32_e32 v126, 0xffff0000, v145
	v_mul_f32_e32 v126, 0xbfb8aa3b, v126
	v_exp_f32_e32 v126, v126
	s_nop 0
	v_add_f32_e32 v126, 1.0, v126
	v_rcp_f32_e32 v139, v126
	v_and_b32_e32 v126, 0xffff0000, v149
	v_fmac_f32_e32 v126, v127, v139
	v_lshlrev_b32_e32 v127, 16, v146
	v_mul_f32_e32 v127, 0xbfb8aa3b, v127
	v_exp_f32_e32 v127, v127
	s_nop 0
	v_add_f32_e32 v127, 1.0, v127
	v_rcp_f32_e32 v139, v127
	v_lshlrev_b32_e32 v127, 16, v150
	v_fmac_f32_e32 v127, v120, v139
	v_and_b32_e32 v120, 0xffff0000, v146
	v_mul_f32_e32 v120, 0xbfb8aa3b, v120
	v_exp_f32_e32 v120, v120
	v_and_b32_e32 v139, 0xffff0000, v150
	v_add_f32_e32 v120, 1.0, v120
	v_rcp_f32_e32 v120, v120
	s_nop 0
	v_fmac_f32_e32 v139, v121, v120
	v_lshlrev_b32_e32 v120, 16, v147
	v_mul_f32_e32 v120, 0xbfb8aa3b, v120
	v_exp_f32_e32 v120, v120
	v_lshlrev_b32_e32 v121, 16, v151
	v_add_f32_e32 v120, 1.0, v120
	v_rcp_f32_e32 v120, v120
	s_nop 0
	v_fmac_f32_e32 v121, v122, v120
	v_and_b32_e32 v120, 0xffff0000, v147
	v_mul_f32_e32 v120, 0xbfb8aa3b, v120
	v_exp_f32_e32 v120, v120
	v_and_b32_e32 v122, 0xffff0000, v151
	v_add_f32_e32 v120, 1.0, v120
	v_rcp_f32_e32 v120, v120
	s_nop 0
	v_fmac_f32_e32 v122, v123, v120
	v_or_b32_e32 v120, 16, v136
	v_mov_b32_e32 v148, v120
	s_movk_i32 s11, 0x1000
	v_ashrrev_i32_e32 v149, 31, v148
	v_lshlrev_b64 v[144:145], 13, v[148:149]
	v_lshl_add_u64 v[144:145], s[2:3], 0, v[144:145]
	v_lshl_add_u64 v[144:145], v[144:145], 0, v[134:135]
	v_add_co_u32_e32 v144, vcc, s11, v144
	v_lshlrev_b64 v[148:149], 11, v[148:149]
	s_nop 0
	v_addc_co_u32_e32 v145, vcc, 0, v145, vcc
	v_lshl_add_u64 v[148:149], s[20:21], 0, v[148:149]
	v_lshl_add_u64 v[148:149], v[148:149], 0, v[134:135]
	s_waitcnt vmcnt(10)
	v_mov_b32_e32 v144, v168
	v_mov_b32_e32 v145, v169
	v_mov_b32_e32 v146, v170
	v_mov_b32_e32 v147, v171
	v_mov_b32_e32 v148, v172
	v_mov_b32_e32 v149, v173
	v_mov_b32_e32 v150, v174
	v_mov_b32_e32 v151, v175
	v_lshlrev_b32_e32 v123, 16, v144
	v_mul_f32_e32 v123, 0xbfb8aa3b, v123
	v_exp_f32_e32 v123, v123
	s_nop 0
	v_add_f32_e32 v123, 1.0, v123
	v_rcp_f32_e32 v152, v123
	v_lshlrev_b32_e32 v123, 16, v148
	v_fmac_f32_e32 v123, v116, v152
	v_and_b32_e32 v116, 0xffff0000, v144
	v_mul_f32_e32 v116, 0xbfb8aa3b, v116
	v_exp_f32_e32 v116, v116
	s_nop 0
	v_add_f32_e32 v116, 1.0, v116
	v_rcp_f32_e32 v144, v116
	v_and_b32_e32 v116, 0xffff0000, v148
	v_fmac_f32_e32 v116, v117, v144
	v_lshlrev_b32_e32 v117, 16, v145
	v_mul_f32_e32 v117, 0xbfb8aa3b, v117
	v_exp_f32_e32 v117, v117
	s_nop 0
	v_add_f32_e32 v117, 1.0, v117
	v_rcp_f32_e32 v144, v117
	v_lshlrev_b32_e32 v117, 16, v149
	v_fmac_f32_e32 v117, v118, v144
	v_and_b32_e32 v118, 0xffff0000, v145
	v_mul_f32_e32 v118, 0xbfb8aa3b, v118
	v_exp_f32_e32 v118, v118
	s_nop 0
	v_add_f32_e32 v118, 1.0, v118
	v_rcp_f32_e32 v144, v118
	v_and_b32_e32 v118, 0xffff0000, v149
	v_fmac_f32_e32 v118, v119, v144
	v_lshlrev_b32_e32 v119, 16, v146
	v_mul_f32_e32 v119, 0xbfb8aa3b, v119
	v_exp_f32_e32 v119, v119
	s_nop 0
	v_add_f32_e32 v119, 1.0, v119
	v_rcp_f32_e32 v144, v119
	v_lshlrev_b32_e32 v119, 16, v150
	v_fmac_f32_e32 v119, v112, v144
	v_and_b32_e32 v112, 0xffff0000, v146
	v_mul_f32_e32 v112, 0xbfb8aa3b, v112
	v_exp_f32_e32 v112, v112
	v_and_b32_e32 v144, 0xffff0000, v150
	v_add_f32_e32 v112, 1.0, v112
	v_rcp_f32_e32 v112, v112
	s_nop 0
	v_fmac_f32_e32 v144, v113, v112
	v_lshlrev_b32_e32 v112, 16, v147
	v_mul_f32_e32 v112, 0xbfb8aa3b, v112
	v_exp_f32_e32 v112, v112
	v_lshlrev_b32_e32 v113, 16, v151
	v_add_f32_e32 v112, 1.0, v112
	v_rcp_f32_e32 v112, v112
	s_nop 0
	v_fmac_f32_e32 v113, v114, v112
	v_and_b32_e32 v112, 0xffff0000, v147
	v_mul_f32_e32 v112, 0xbfb8aa3b, v112
	v_exp_f32_e32 v112, v112
	v_and_b32_e32 v114, 0xffff0000, v151
	v_add_f32_e32 v112, 1.0, v112
	v_rcp_f32_e32 v112, v112
	s_nop 0
	v_fmac_f32_e32 v114, v115, v112
	v_or_b32_e32 v112, 32, v136
	v_mov_b32_e32 v150, v112
	s_nop 0
	v_ashrrev_i32_e32 v151, 31, v150
	v_lshlrev_b64 v[146:147], 13, v[150:151]
	v_lshl_add_u64 v[146:147], s[2:3], 0, v[146:147]
	v_lshl_add_u64 v[146:147], v[146:147], 0, v[134:135]
	v_add_co_u32_e32 v146, vcc, s11, v146
	v_lshlrev_b64 v[150:151], 11, v[150:151]
	s_nop 0
	v_addc_co_u32_e32 v147, vcc, 0, v147, vcc
	v_lshl_add_u64 v[150:151], s[20:21], 0, v[150:151]
	v_lshl_add_u64 v[150:151], v[150:151], 0, v[134:135]
	s_waitcnt vmcnt(8)
; __device__ __forceinline__ float bf_lo(unsigned u) { return __uint_as_float(u << 16); }
; __device__ __forceinline__ float bf_hi(unsigned u) { return __uint_as_float(u & 0xffff0000u); }
; __device__ __forceinline__ float sigmoidf_(float x) { return frcp(1.0f + fexp2(-1.4426950408889634f * x)); }
; #define EPI_PIN(r) asm volatile("" : "+v"(r))
; #define EPI_FOR_BJ _Pragma("unroll") for (int bj = 0; bj < 2; ++bj)
; #define EPI_FOR_AM _Pragma("unroll") for (int ai = 0; ai < 2; ++ai) _Pragma("unroll") for (int m = 0; m < 4; ++m)
;     __device__ __forceinline__ void operator()(Acc& acc, const Unit& u, int wr, int wc, int fr, int fq) const {
;         EPI_FOR_BJ { const int c0 = EPI_COL(u, bj);
;             EPI_FOR_AM { int r = EPI_ROW(u, ai, m); EPI_PIN(r);
;                 const u32x4 gb = *(const u32x4*)(P + (size_t)r * INWP + OFF_GB + c0);
;                 const u32x4 mo = *(const u32x4*)(MG + (size_t)r * 1024 + c0);
; #pragma unroll
;                 for (int e = 0; e < 8; ++e) {
;                     const float g = sigmoidf_((e & 1) ? bf_hi(gb[e >> 1]) : bf_lo(gb[e >> 1])), o = (e & 1) ? bf_hi(mo[e >> 1]) : bf_lo(mo[e >> 1]);
;                     acc[ai][bj][m][e >> 2][e & 3] = o + acc[ai][bj][m][e >> 2][e & 3] * g;
;                 }
;                 __builtin_amdgcn_sched_barrier(0); } }
	v_mov_b32_e32 v146, v176
	v_mov_b32_e32 v147, v177
	v_mov_b32_e32 v148, v178
	v_mov_b32_e32 v149, v179
	v_mov_b32_e32 v150, v180
	v_mov_b32_e32 v151, v181
	v_mov_b32_e32 v152, v182
	v_mov_b32_e32 v153, v183
	v_lshlrev_b32_e32 v115, 16, v146
	v_mul_f32_e32 v115, 0xbfb8aa3b, v115
	v_exp_f32_e32 v115, v115
	s_nop 0
	v_add_f32_e32 v115, 1.0, v115
	v_rcp_f32_e32 v145, v115
	v_lshlrev_b32_e32 v115, 16, v150
	v_fmac_f32_e32 v115, v108, v145
	v_and_b32_e32 v108, 0xffff0000, v146
	v_mul_f32_e32 v108, 0xbfb8aa3b, v108
	v_exp_f32_e32 v108, v108
	s_nop 0
	v_add_f32_e32 v108, 1.0, v108
	v_rcp_f32_e32 v145, v108
	v_and_b32_e32 v108, 0xffff0000, v150
	v_fmac_f32_e32 v108, v109, v145
	v_lshlrev_b32_e32 v109, 16, v147
	v_mul_f32_e32 v109, 0xbfb8aa3b, v109
	v_exp_f32_e32 v109, v109
	s_nop 0
	v_add_f32_e32 v109, 1.0, v109
	v_rcp_f32_e32 v145, v109
	v_lshlrev_b32_e32 v109, 16, v151
	v_fmac_f32_e32 v109, v110, v145
	v_and_b32_e32 v110, 0xffff0000, v147
	v_mul_f32_e32 v110, 0xbfb8aa3b, v110
	v_exp_f32_e32 v110, v110
	s_nop 0
	v_add_f32_e32 v110, 1.0, v110
	v_rcp_f32_e32 v145, v110
	v_and_b32_e32 v110, 0xffff0000, v151
	v_fmac_f32_e32 v110, v111, v145
	v_lshlrev_b32_e32 v111, 16, v148
	v_mul_f32_e32 v111, 0xbfb8aa3b, v111
	v_exp_f32_e32 v111, v111
	s_nop 0
	v_add_f32_e32 v111, 1.0, v111
	v_rcp_f32_e32 v145, v111
	v_lshlrev_b32_e32 v111, 16, v152
	v_fmac_f32_e32 v111, v104, v145
	v_and_b32_e32 v104, 0xffff0000, v148
	v_mul_f32_e32 v104, 0xbfb8aa3b, v104
	v_exp_f32_e32 v104, v104
	v_and_b32_e32 v145, 0xffff0000, v152
	v_add_f32_e32 v104, 1.0, v104
	v_rcp_f32_e32 v104, v104
	s_nop 0
	v_fmac_f32_e32 v145, v105, v104
	v_lshlrev_b32_e32 v104, 16, v149
	v_mul_f32_e32 v104, 0xbfb8aa3b, v104
	v_exp_f32_e32 v104, v104
	v_lshlrev_b32_e32 v105, 16, v153
	v_add_f32_e32 v104, 1.0, v104
	v_rcp_f32_e32 v104, v104
	s_nop 0
	v_fmac_f32_e32 v105, v106, v104
	v_and_b32_e32 v104, 0xffff0000, v149
	v_mul_f32_e32 v104, 0xbfb8aa3b, v104
	v_exp_f32_e32 v104, v104
	v_and_b32_e32 v106, 0xffff0000, v153
	v_add_f32_e32 v104, 1.0, v104
	v_rcp_f32_e32 v104, v104
	s_nop 0
	v_fmac_f32_e32 v106, v107, v104
	v_or_b32_e32 v104, 48, v136
	v_mov_b32_e32 v150, v104
	s_nop 0
	v_ashrrev_i32_e32 v151, 31, v150
	v_lshlrev_b64 v[146:147], 13, v[150:151]
	v_lshl_add_u64 v[146:147], s[2:3], 0, v[146:147]
	v_lshl_add_u64 v[146:147], v[146:147], 0, v[134:135]
	v_add_co_u32_e32 v146, vcc, s11, v146
	v_lshlrev_b64 v[150:151], 11, v[150:151]
	s_nop 0
	v_addc_co_u32_e32 v147, vcc, 0, v147, vcc
	v_lshl_add_u64 v[150:151], s[20:21], 0, v[150:151]
	v_lshl_add_u64 v[150:151], v[150:151], 0, v[134:135]
	s_waitcnt vmcnt(6)
	v_mov_b32_e32 v146, v184
	v_mov_b32_e32 v147, v185
	v_mov_b32_e32 v148, v186
	v_mov_b32_e32 v149, v187
	v_mov_b32_e32 v150, v188
	v_mov_b32_e32 v151, v189
	v_mov_b32_e32 v152, v190
	v_mov_b32_e32 v153, v191
	v_lshlrev_b32_e32 v107, 16, v146
	v_mul_f32_e32 v107, 0xbfb8aa3b, v107
	v_exp_f32_e32 v107, v107
	s_nop 0
	v_add_f32_e32 v107, 1.0, v107
	v_rcp_f32_e32 v154, v107
	v_lshlrev_b32_e32 v107, 16, v150
	v_fmac_f32_e32 v107, v100, v154
	v_and_b32_e32 v100, 0xffff0000, v146
	v_mul_f32_e32 v100, 0xbfb8aa3b, v100
	v_exp_f32_e32 v100, v100
	s_nop 0
	v_add_f32_e32 v100, 1.0, v100
	v_rcp_f32_e32 v146, v100
	v_and_b32_e32 v100, 0xffff0000, v150
	v_fmac_f32_e32 v100, v101, v146
	v_lshlrev_b32_e32 v101, 16, v147
	v_mul_f32_e32 v101, 0xbfb8aa3b, v101
	v_exp_f32_e32 v101, v101
	s_nop 0
	v_add_f32_e32 v101, 1.0, v101
	v_rcp_f32_e32 v146, v101
	v_lshlrev_b32_e32 v101, 16, v151
	v_fmac_f32_e32 v101, v102, v146
	v_and_b32_e32 v102, 0xffff0000, v147
	v_mul_f32_e32 v102, 0xbfb8aa3b, v102
	v_exp_f32_e32 v102, v102
	s_nop 0
	v_add_f32_e32 v102, 1.0, v102
	v_rcp_f32_e32 v146, v102
	v_and_b32_e32 v102, 0xffff0000, v151
	v_fmac_f32_e32 v102, v103, v146
	v_lshlrev_b32_e32 v103, 16, v148
	v_mul_f32_e32 v103, 0xbfb8aa3b, v103
	v_exp_f32_e32 v103, v103
	s_nop 0
	v_add_f32_e32 v103, 1.0, v103
	v_rcp_f32_e32 v146, v103
	v_lshlrev_b32_e32 v103, 16, v152
	v_fmac_f32_e32 v103, v96, v146
	v_and_b32_e32 v96, 0xffff0000, v148
	v_mul_f32_e32 v96, 0xbfb8aa3b, v96
	v_exp_f32_e32 v96, v96
	v_and_b32_e32 v146, 0xffff0000, v152
	v_add_f32_e32 v96, 1.0, v96
	v_rcp_f32_e32 v96, v96
	s_nop 0
	v_fmac_f32_e32 v146, v97, v96
	v_lshlrev_b32_e32 v96, 16, v149
	v_mul_f32_e32 v96, 0xbfb8aa3b, v96
	v_exp_f32_e32 v96, v96
	v_lshlrev_b32_e32 v97, 16, v153
	v_add_f32_e32 v96, 1.0, v96
	v_rcp_f32_e32 v96, v96
	s_nop 0
	v_fmac_f32_e32 v97, v98, v96
	v_and_b32_e32 v96, 0xffff0000, v149
	v_mul_f32_e32 v96, 0xbfb8aa3b, v96
	v_exp_f32_e32 v96, v96
	v_and_b32_e32 v98, 0xffff0000, v153
	v_add_f32_e32 v96, 1.0, v96
	v_rcp_f32_e32 v96, v96
	s_nop 0
	v_fmac_f32_e32 v98, v99, v96
	v_add_u32_e32 v96, 0x80, v136
	v_mov_b32_e32 v152, v96
	s_nop 0
	v_ashrrev_i32_e32 v153, 31, v152
	v_lshlrev_b64 v[148:149], 13, v[152:153]
	v_lshl_add_u64 v[148:149], s[2:3], 0, v[148:149]
	v_lshl_add_u64 v[148:149], v[148:149], 0, v[134:135]
	v_add_co_u32_e32 v148, vcc, s11, v148
	v_lshlrev_b64 v[152:153], 11, v[152:153]
	s_nop 0
	v_addc_co_u32_e32 v149, vcc, 0, v149, vcc
	v_lshl_add_u64 v[152:153], s[20:21], 0, v[152:153]
	v_lshl_add_u64 v[152:153], v[152:153], 0, v[134:135]
	s_waitcnt vmcnt(4)
; __device__ __forceinline__ float bf_lo(unsigned u) { return __uint_as_float(u << 16); }
; __device__ __forceinline__ float bf_hi(unsigned u) { return __uint_as_float(u & 0xffff0000u); }
; __device__ __forceinline__ float sigmoidf_(float x) { return frcp(1.0f + fexp2(-1.4426950408889634f * x)); }
; #define EPI_PIN(r) asm volatile("" : "+v"(r))
; #define EPI_FOR_BJ _Pragma("unroll") for (int bj = 0; bj < 2; ++bj)
; #define EPI_FOR_AM _Pragma("unroll") for (int ai = 0; ai < 2; ++ai) _Pragma("unroll") for (int m = 0; m < 4; ++m)
;     __device__ __forceinline__ void operator()(Acc& acc, const Unit& u, int wr, int wc, int fr, int fq) const {
;         EPI_FOR_BJ { const int c0 = EPI_COL(u, bj);
;             EPI_FOR_AM { int r = EPI_ROW(u, ai, m); EPI_PIN(r);
;                 const u32x4 gb = *(const u32x4*)(P + (size_t)r * INWP + OFF_GB + c0);
;                 const u32x4 mo = *(const u32x4*)(MG + (size_t)r * 1024 + c0);
; #pragma unroll
;                 for (int e = 0; e < 8; ++e) {
;                     const float g = sigmoidf_((e & 1) ? bf_hi(gb[e >> 1]) : bf_lo(gb[e >> 1])), o = (e & 1) ? bf_hi(mo[e >> 1]) : bf_lo(mo[e >> 1]);
;                     acc[ai][bj][m][e >> 2][e & 3] = o + acc[ai][bj][m][e >> 2][e & 3] * g;
;                 }
;                 __builtin_amdgcn_sched_barrier(0); } }
	v_mov_b32_e32 v148, v192
	v_mov_b32_e32 v149, v193
	v_mov_b32_e32 v150, v194
	v_mov_b32_e32 v151, v195
	v_mov_b32_e32 v152, v206
	v_mov_b32_e32 v153, v207
	v_mov_b32_e32 v154, v208
	v_mov_b32_e32 v155, v209
	v_lshlrev_b32_e32 v99, 16, v148
	v_mul_f32_e32 v99, 0xbfb8aa3b, v99
	v_exp_f32_e32 v99, v99
	s_nop 0
	v_add_f32_e32 v99, 1.0, v99
	v_rcp_f32_e32 v147, v99
	v_lshlrev_b32_e32 v99, 16, v152
	v_fmac_f32_e32 v99, v92, v147
	v_and_b32_e32 v92, 0xffff0000, v148
	v_mul_f32_e32 v92, 0xbfb8aa3b, v92
	v_exp_f32_e32 v92, v92
	s_nop 0
	v_add_f32_e32 v92, 1.0, v92
	v_rcp_f32_e32 v147, v92
	v_and_b32_e32 v92, 0xffff0000, v152
	v_fmac_f32_e32 v92, v93, v147
	v_lshlrev_b32_e32 v93, 16, v149
	v_mul_f32_e32 v93, 0xbfb8aa3b, v93
	v_exp_f32_e32 v93, v93
	s_nop 0
	v_add_f32_e32 v93, 1.0, v93
	v_rcp_f32_e32 v147, v93
	v_lshlrev_b32_e32 v93, 16, v153
	v_fmac_f32_e32 v93, v94, v147
	v_and_b32_e32 v94, 0xffff0000, v149
	v_mul_f32_e32 v94, 0xbfb8aa3b, v94
	v_exp_f32_e32 v94, v94
	s_nop 0
	v_add_f32_e32 v94, 1.0, v94
	v_rcp_f32_e32 v147, v94
	v_and_b32_e32 v94, 0xffff0000, v153
	v_fmac_f32_e32 v94, v95, v147
	v_lshlrev_b32_e32 v95, 16, v150
	v_mul_f32_e32 v95, 0xbfb8aa3b, v95
	v_exp_f32_e32 v95, v95
	s_nop 0
	v_add_f32_e32 v95, 1.0, v95
	v_rcp_f32_e32 v147, v95
	v_lshlrev_b32_e32 v95, 16, v154
	v_fmac_f32_e32 v95, v88, v147
	v_and_b32_e32 v88, 0xffff0000, v150
	v_mul_f32_e32 v88, 0xbfb8aa3b, v88
	v_exp_f32_e32 v88, v88
	v_and_b32_e32 v147, 0xffff0000, v154
	v_add_f32_e32 v88, 1.0, v88
	v_rcp_f32_e32 v88, v88
	s_nop 0
	v_fmac_f32_e32 v147, v89, v88
	v_lshlrev_b32_e32 v88, 16, v151
	v_mul_f32_e32 v88, 0xbfb8aa3b, v88
	v_exp_f32_e32 v88, v88
	v_lshlrev_b32_e32 v89, 16, v155
	v_add_f32_e32 v88, 1.0, v88
	v_rcp_f32_e32 v88, v88
	s_nop 0
	v_fmac_f32_e32 v89, v90, v88
	v_and_b32_e32 v88, 0xffff0000, v151
	v_mul_f32_e32 v88, 0xbfb8aa3b, v88
	v_exp_f32_e32 v88, v88
	v_and_b32_e32 v90, 0xffff0000, v155
	v_add_f32_e32 v88, 1.0, v88
	v_rcp_f32_e32 v88, v88
	s_nop 0
	v_fmac_f32_e32 v90, v91, v88
	v_add_u32_e32 v88, 0x90, v136
	v_mov_b32_e32 v152, v88
	s_nop 0
	v_ashrrev_i32_e32 v153, 31, v152
	v_lshlrev_b64 v[148:149], 13, v[152:153]
	v_lshl_add_u64 v[148:149], s[2:3], 0, v[148:149]
	v_lshl_add_u64 v[148:149], v[148:149], 0, v[134:135]
	v_add_co_u32_e32 v148, vcc, s11, v148
	v_lshlrev_b64 v[152:153], 11, v[152:153]
	s_nop 0
	v_addc_co_u32_e32 v149, vcc, 0, v149, vcc
	v_lshl_add_u64 v[152:153], s[20:21], 0, v[152:153]
	v_lshl_add_u64 v[152:153], v[152:153], 0, v[134:135]
	s_waitcnt vmcnt(2)
	v_mov_b32_e32 v148, v210
	v_mov_b32_e32 v149, v211
	v_mov_b32_e32 v150, v212
	v_mov_b32_e32 v151, v213
	v_mov_b32_e32 v152, v214
	v_mov_b32_e32 v153, v215
	v_mov_b32_e32 v154, v216
	v_mov_b32_e32 v155, v217
	v_lshlrev_b32_e32 v91, 16, v148
	v_mul_f32_e32 v91, 0xbfb8aa3b, v91
	v_exp_f32_e32 v91, v91
	s_nop 0
	v_add_f32_e32 v91, 1.0, v91
	v_rcp_f32_e32 v156, v91
	v_lshlrev_b32_e32 v91, 16, v152
	v_fmac_f32_e32 v91, v84, v156
	v_and_b32_e32 v84, 0xffff0000, v148
	v_mul_f32_e32 v84, 0xbfb8aa3b, v84
	v_exp_f32_e32 v84, v84
	s_nop 0
	v_add_f32_e32 v84, 1.0, v84
	v_rcp_f32_e32 v148, v84
	v_and_b32_e32 v84, 0xffff0000, v152
	v_fmac_f32_e32 v84, v85, v148
	v_lshlrev_b32_e32 v85, 16, v149
	v_mul_f32_e32 v85, 0xbfb8aa3b, v85
	v_exp_f32_e32 v85, v85
	s_nop 0
	v_add_f32_e32 v85, 1.0, v85
	v_rcp_f32_e32 v148, v85
	v_lshlrev_b32_e32 v85, 16, v153
	v_fmac_f32_e32 v85, v86, v148
	v_and_b32_e32 v86, 0xffff0000, v149
	v_mul_f32_e32 v86, 0xbfb8aa3b, v86
	v_exp_f32_e32 v86, v86
	s_nop 0
	v_add_f32_e32 v86, 1.0, v86
	v_rcp_f32_e32 v148, v86
	v_and_b32_e32 v86, 0xffff0000, v153
	v_fmac_f32_e32 v86, v87, v148
	v_lshlrev_b32_e32 v87, 16, v150
	v_mul_f32_e32 v87, 0xbfb8aa3b, v87
	v_exp_f32_e32 v87, v87
	s_nop 0
	v_add_f32_e32 v87, 1.0, v87
	v_rcp_f32_e32 v148, v87
	v_lshlrev_b32_e32 v87, 16, v154
	v_fmac_f32_e32 v87, v80, v148
	v_and_b32_e32 v80, 0xffff0000, v150
	v_mul_f32_e32 v80, 0xbfb8aa3b, v80
	v_exp_f32_e32 v80, v80
	v_and_b32_e32 v148, 0xffff0000, v154
	v_add_f32_e32 v80, 1.0, v80
	v_rcp_f32_e32 v80, v80
	s_nop 0
	v_fmac_f32_e32 v148, v81, v80
	v_lshlrev_b32_e32 v80, 16, v151
	v_mul_f32_e32 v80, 0xbfb8aa3b, v80
	v_exp_f32_e32 v80, v80
	v_lshlrev_b32_e32 v81, 16, v155
	v_add_f32_e32 v80, 1.0, v80
	v_rcp_f32_e32 v80, v80
	s_nop 0
	v_fmac_f32_e32 v81, v82, v80
	v_and_b32_e32 v80, 0xffff0000, v151
	v_mul_f32_e32 v80, 0xbfb8aa3b, v80
	v_exp_f32_e32 v80, v80
	v_and_b32_e32 v82, 0xffff0000, v155
	v_add_f32_e32 v80, 1.0, v80
	v_rcp_f32_e32 v80, v80
	s_nop 0
	v_fmac_f32_e32 v82, v83, v80
	v_add_u32_e32 v80, 0xa0, v136
	v_mov_b32_e32 v154, v80
	s_nop 0
	v_ashrrev_i32_e32 v155, 31, v154
	v_lshlrev_b64 v[150:151], 13, v[154:155]
	v_lshl_add_u64 v[150:151], s[2:3], 0, v[150:151]
	v_lshl_add_u64 v[150:151], v[150:151], 0, v[134:135]
	v_add_co_u32_e32 v150, vcc, s11, v150
	v_lshlrev_b64 v[154:155], 11, v[154:155]
	s_nop 0
	v_addc_co_u32_e32 v151, vcc, 0, v151, vcc
	v_lshl_add_u64 v[154:155], s[20:21], 0, v[154:155]
	v_lshl_add_u64 v[154:155], v[154:155], 0, v[134:135]
	s_waitcnt vmcnt(0)
; __device__ __forceinline__ float bf_lo(unsigned u) { return __uint_as_float(u << 16); }
; __device__ __forceinline__ float bf_hi(unsigned u) { return __uint_as_float(u & 0xffff0000u); }
; __device__ __forceinline__ float sigmoidf_(float x) { return frcp(1.0f + fexp2(-1.4426950408889634f * x)); }
; #define EPI_PIN(r) asm volatile("" : "+v"(r))
; #define EPI_FOR_BJ _Pragma("unroll") for (int bj = 0; bj < 2; ++bj)
; #define EPI_FOR_AM _Pragma("unroll") for (int ai = 0; ai < 2; ++ai) _Pragma("unroll") for (int m = 0; m < 4; ++m)
;     __device__ __forceinline__ void operator()(Acc& acc, const Unit& u, int wr, int wc, int fr, int fq) const {
;         EPI_FOR_BJ { const int c0 = EPI_COL(u, bj);
;             EPI_FOR_AM { int r = EPI_ROW(u, ai, m); EPI_PIN(r);
;                 const u32x4 gb = *(const u32x4*)(P + (size_t)r * INWP + OFF_GB + c0);
;                 const u32x4 mo = *(const u32x4*)(MG + (size_t)r * 1024 + c0);
; #pragma unroll
;                 for (int e = 0; e < 8; ++e) {
;                     const float g = sigmoidf_((e & 1) ? bf_hi(gb[e >> 1]) : bf_lo(gb[e >> 1])), o = (e & 1) ? bf_hi(mo[e >> 1]) : bf_lo(mo[e >> 1]);
;                     acc[ai][bj][m][e >> 2][e & 3] = o + acc[ai][bj][m][e >> 2][e & 3] * g;
;                 }
;                 __builtin_amdgcn_sched_barrier(0); } }
	v_mov_b32_e32 v150, v218
	v_mov_b32_e32 v151, v219
	v_mov_b32_e32 v152, v220
	v_mov_b32_e32 v153, v221
	v_mov_b32_e32 v154, v222
	v_mov_b32_e32 v155, v223
	v_mov_b32_e32 v156, v224
	v_mov_b32_e32 v157, v225
	s_mov_b32 s86, 0x160000
	v_lshl_add_u64 v[196:197], v[198:199], 0, s[86:87]
	global_load_dwordx4 v[160:163], v[196:197], off offset:1856
	s_mov_b32 s88, 0x58000
	v_lshl_add_u64 v[196:197], v[230:231], 0, s[88:89]
	global_load_dwordx4 v[164:167], v[196:197], off
	s_mov_b32 s86, 0x100
	v_lshl_add_u64 v[196:197], v[198:199], 0, s[86:87]
	global_load_dwordx4 v[168:171], v[196:197], off offset:1856
	s_mov_b32 s88, 0x100
	v_lshl_add_u64 v[196:197], v[230:231], 0, s[88:89]
	global_load_dwordx4 v[172:175], v[196:197], off
	s_mov_b32 s86, 0x20100
	v_lshl_add_u64 v[196:197], v[198:199], 0, s[86:87]
	global_load_dwordx4 v[176:179], v[196:197], off offset:1856
	s_mov_b32 s88, 0x8100
	v_lshl_add_u64 v[196:197], v[230:231], 0, s[88:89]
	global_load_dwordx4 v[180:183], v[196:197], off
	s_mov_b32 s86, 0x40100
	v_lshl_add_u64 v[196:197], v[198:199], 0, s[86:87]
	global_load_dwordx4 v[184:187], v[196:197], off offset:1856
	s_mov_b32 s88, 0x10100
	v_lshl_add_u64 v[196:197], v[230:231], 0, s[88:89]
	global_load_dwordx4 v[188:191], v[196:197], off
	s_mov_b32 s86, 0x60100
	v_lshl_add_u64 v[196:197], v[198:199], 0, s[86:87]
	global_load_dwordx4 v[192:195], v[196:197], off offset:1856
	s_mov_b32 s88, 0x18100
	v_lshl_add_u64 v[196:197], v[230:231], 0, s[88:89]
	global_load_dwordx4 v[206:209], v[196:197], off
	s_mov_b32 s86, 0x100100
	v_lshl_add_u64 v[196:197], v[198:199], 0, s[86:87]
	global_load_dwordx4 v[210:213], v[196:197], off offset:1856
	s_mov_b32 s88, 0x40100
	v_lshl_add_u64 v[196:197], v[230:231], 0, s[88:89]
	global_load_dwordx4 v[214:217], v[196:197], off
	s_mov_b32 s86, 0x120100
	v_lshl_add_u64 v[196:197], v[198:199], 0, s[86:87]
	global_load_dwordx4 v[218:221], v[196:197], off offset:1856
	s_mov_b32 s88, 0x48100
	v_lshl_add_u64 v[196:197], v[230:231], 0, s[88:89]
	global_load_dwordx4 v[222:225], v[196:197], off
	v_lshlrev_b32_e32 v83, 16, v150
	v_mul_f32_e32 v83, 0xbfb8aa3b, v83
	v_exp_f32_e32 v83, v83
	s_nop 0
	v_add_f32_e32 v83, 1.0, v83
	v_rcp_f32_e32 v149, v83
	v_lshlrev_b32_e32 v83, 16, v154
	v_fmac_f32_e32 v83, v76, v149
	v_and_b32_e32 v76, 0xffff0000, v150
	v_mul_f32_e32 v76, 0xbfb8aa3b, v76
	v_exp_f32_e32 v76, v76
	s_nop 0
	v_add_f32_e32 v76, 1.0, v76
	v_rcp_f32_e32 v149, v76
	v_and_b32_e32 v76, 0xffff0000, v154
	v_fmac_f32_e32 v76, v77, v149
	v_lshlrev_b32_e32 v77, 16, v151
	v_mul_f32_e32 v77, 0xbfb8aa3b, v77
	v_exp_f32_e32 v77, v77
	s_nop 0
	v_add_f32_e32 v77, 1.0, v77
	v_rcp_f32_e32 v149, v77
	v_lshlrev_b32_e32 v77, 16, v155
	v_fmac_f32_e32 v77, v78, v149
	v_and_b32_e32 v78, 0xffff0000, v151
	v_mul_f32_e32 v78, 0xbfb8aa3b, v78
	v_exp_f32_e32 v78, v78
	s_nop 0
	v_add_f32_e32 v78, 1.0, v78
	v_rcp_f32_e32 v149, v78
	v_and_b32_e32 v78, 0xffff0000, v155
	v_fmac_f32_e32 v78, v79, v149
	v_lshlrev_b32_e32 v79, 16, v152
	v_mul_f32_e32 v79, 0xbfb8aa3b, v79
	v_exp_f32_e32 v79, v79
	s_nop 0
	v_add_f32_e32 v79, 1.0, v79
	v_rcp_f32_e32 v149, v79
	v_lshlrev_b32_e32 v79, 16, v156
	v_fmac_f32_e32 v79, v72, v149
	v_and_b32_e32 v72, 0xffff0000, v152
	v_mul_f32_e32 v72, 0xbfb8aa3b, v72
	v_exp_f32_e32 v72, v72
	v_and_b32_e32 v149, 0xffff0000, v156
	v_add_f32_e32 v72, 1.0, v72
	v_rcp_f32_e32 v72, v72
	s_nop 0
	v_fmac_f32_e32 v149, v73, v72
	v_lshlrev_b32_e32 v72, 16, v153
	v_mul_f32_e32 v72, 0xbfb8aa3b, v72
	v_exp_f32_e32 v72, v72
	v_lshlrev_b32_e32 v73, 16, v157
	v_add_f32_e32 v72, 1.0, v72
	v_rcp_f32_e32 v72, v72
	s_nop 0
	v_fmac_f32_e32 v73, v74, v72
	v_and_b32_e32 v72, 0xffff0000, v153
	v_mul_f32_e32 v72, 0xbfb8aa3b, v72
	v_exp_f32_e32 v72, v72
	v_and_b32_e32 v74, 0xffff0000, v157
	v_add_f32_e32 v72, 1.0, v72
	v_rcp_f32_e32 v72, v72
	s_nop 0
	v_fmac_f32_e32 v74, v75, v72
	v_add_u32_e32 v72, 0xb0, v136
	v_mov_b32_e32 v154, v72
	s_nop 0
	v_ashrrev_i32_e32 v155, 31, v154
	v_lshlrev_b64 v[150:151], 13, v[154:155]
	v_lshl_add_u64 v[150:151], s[2:3], 0, v[150:151]
	v_lshl_add_u64 v[150:151], v[150:151], 0, v[134:135]
	v_add_co_u32_e32 v150, vcc, s11, v150
	v_lshlrev_b64 v[154:155], 11, v[154:155]
	s_nop 0
	v_addc_co_u32_e32 v151, vcc, 0, v151, vcc
	v_lshl_add_u64 v[154:155], s[20:21], 0, v[154:155]
	v_lshl_add_u64 v[154:155], v[154:155], 0, v[134:135]
	s_waitcnt vmcnt(12)
	v_mov_b32_e32 v150, v160
	v_mov_b32_e32 v151, v161
	v_mov_b32_e32 v152, v162
	v_mov_b32_e32 v153, v163
	v_mov_b32_e32 v154, v164
	v_mov_b32_e32 v155, v165
	v_mov_b32_e32 v156, v166
	v_mov_b32_e32 v157, v167
	v_lshlrev_b32_e32 v75, 16, v150
	v_mul_f32_e32 v75, 0xbfb8aa3b, v75
	v_exp_f32_e32 v75, v75
	s_nop 0
	v_add_f32_e32 v75, 1.0, v75
	v_rcp_f32_e32 v158, v75
	v_lshlrev_b32_e32 v75, 16, v154
	v_fmac_f32_e32 v75, v68, v158
	v_and_b32_e32 v68, 0xffff0000, v150
	v_mul_f32_e32 v68, 0xbfb8aa3b, v68
	v_exp_f32_e32 v68, v68
	s_nop 0
	v_add_f32_e32 v68, 1.0, v68
	v_rcp_f32_e32 v150, v68
	v_and_b32_e32 v68, 0xffff0000, v154
	v_fmac_f32_e32 v68, v69, v150
	v_lshlrev_b32_e32 v69, 16, v151
	v_mul_f32_e32 v69, 0xbfb8aa3b, v69
	v_exp_f32_e32 v69, v69
	s_nop 0
	v_add_f32_e32 v69, 1.0, v69
	v_rcp_f32_e32 v150, v69
	v_lshlrev_b32_e32 v69, 16, v155
	v_fmac_f32_e32 v69, v70, v150
	v_and_b32_e32 v70, 0xffff0000, v151
	v_mul_f32_e32 v70, 0xbfb8aa3b, v70
	v_exp_f32_e32 v70, v70
	v_lshlrev_b32_e32 v151, 16, v157
	v_add_f32_e32 v70, 1.0, v70
	v_rcp_f32_e32 v150, v70
	v_and_b32_e32 v70, 0xffff0000, v155
	v_fmac_f32_e32 v70, v71, v150
	v_lshlrev_b32_e32 v71, 16, v152
	v_mul_f32_e32 v71, 0xbfb8aa3b, v71
	v_exp_f32_e32 v71, v71
	s_nop 0
	v_add_f32_e32 v71, 1.0, v71
	v_rcp_f32_e32 v150, v71
	v_lshlrev_b32_e32 v71, 16, v156
	v_fmac_f32_e32 v71, v64, v150
	v_and_b32_e32 v64, 0xffff0000, v152
	v_mul_f32_e32 v64, 0xbfb8aa3b, v64
	v_exp_f32_e32 v64, v64
	v_and_b32_e32 v150, 0xffff0000, v156
	v_add_f32_e32 v64, 1.0, v64
	v_rcp_f32_e32 v64, v64
	s_nop 0
	v_fmac_f32_e32 v150, v65, v64
	v_lshlrev_b32_e32 v64, 16, v153
	v_mul_f32_e32 v64, 0xbfb8aa3b, v64
	v_exp_f32_e32 v64, v64
	s_nop 0
	v_add_f32_e32 v64, 1.0, v64
	v_rcp_f32_e32 v64, v64
	s_nop 0
	v_fmac_f32_e32 v151, v66, v64
	v_and_b32_e32 v64, 0xffff0000, v153
	v_mul_f32_e32 v64, 0xbfb8aa3b, v64
	v_exp_f32_e32 v64, v64
	v_and_b32_e32 v66, 0xffff0000, v157
	v_add_f32_e32 v64, 1.0, v64
	v_rcp_f32_e32 v64, v64
	s_nop 0
	v_fmac_f32_e32 v66, v67, v64
	v_mov_b32_e32 v156, v136
	v_or_b32_e32 v64, 0x80, v138
	v_ashrrev_i32_e32 v65, 31, v64
	v_ashrrev_i32_e32 v157, 31, v156
	v_lshlrev_b64 v[152:153], 13, v[156:157]
	v_lshl_add_u64 v[152:153], s[2:3], 0, v[152:153]
	v_lshlrev_b64 v[64:65], 1, v[64:65]
	v_lshl_add_u64 v[152:153], v[152:153], 0, v[64:65]
	v_add_co_u32_e32 v152, vcc, s11, v152
	v_lshlrev_b64 v[156:157], 11, v[156:157]
	s_nop 0
	v_addc_co_u32_e32 v153, vcc, 0, v153, vcc
	v_lshl_add_u64 v[156:157], s[20:21], 0, v[156:157]
	v_lshl_add_u64 v[156:157], v[156:157], 0, v[134:135]
	s_waitcnt vmcnt(10)
; __device__ __forceinline__ float bf_lo(unsigned u) { return __uint_as_float(u << 16); }
; __device__ __forceinline__ float bf_hi(unsigned u) { return __uint_as_float(u & 0xffff0000u); }
; __device__ __forceinline__ float sigmoidf_(float x) { return frcp(1.0f + fexp2(-1.4426950408889634f * x)); }
; #define EPI_PIN(r) asm volatile("" : "+v"(r))
; #define EPI_FOR_BJ _Pragma("unroll") for (int bj = 0; bj < 2; ++bj)
; #define EPI_FOR_AM _Pragma("unroll") for (int ai = 0; ai < 2; ++ai) _Pragma("unroll") for (int m = 0; m < 4; ++m)
;     __device__ __forceinline__ void operator()(Acc& acc, const Unit& u, int wr, int wc, int fr, int fq) const {
;         EPI_FOR_BJ { const int c0 = EPI_COL(u, bj);
;             EPI_FOR_AM { int r = EPI_ROW(u, ai, m); EPI_PIN(r);
;                 const u32x4 gb = *(const u32x4*)(P + (size_t)r * INWP + OFF_GB + c0);
;                 const u32x4 mo = *(const u32x4*)(MG + (size_t)r * 1024 + c0);
; #pragma unroll
;                 for (int e = 0; e < 8; ++e) {
;                     const float g = sigmoidf_((e & 1) ? bf_hi(gb[e >> 1]) : bf_lo(gb[e >> 1])), o = (e & 1) ? bf_hi(mo[e >> 1]) : bf_lo(mo[e >> 1]);
;                     acc[ai][bj][m][e >> 2][e & 3] = o + acc[ai][bj][m][e >> 2][e & 3] * g;
;                 }
;                 __builtin_amdgcn_sched_barrier(0); } }
	v_mov_b32_e32 v152, v168
	v_mov_b32_e32 v153, v169
	v_mov_b32_e32 v154, v170
	v_mov_b32_e32 v155, v171
	v_mov_b32_e32 v156, v172
	v_mov_b32_e32 v157, v173
	v_mov_b32_e32 v158, v174
	v_mov_b32_e32 v159, v175
	v_lshlrev_b32_e32 v67, 16, v152
	v_mul_f32_e32 v67, 0xbfb8aa3b, v67
	v_exp_f32_e32 v67, v67
	s_nop 0
	v_add_f32_e32 v67, 1.0, v67
	v_rcp_f32_e32 v138, v67
	v_lshlrev_b32_e32 v67, 16, v156
	v_fmac_f32_e32 v67, v60, v138
	v_and_b32_e32 v60, 0xffff0000, v152
	v_mul_f32_e32 v60, 0xbfb8aa3b, v60
	v_exp_f32_e32 v60, v60
	s_nop 0
	v_add_f32_e32 v60, 1.0, v60
	v_rcp_f32_e32 v138, v60
	v_and_b32_e32 v60, 0xffff0000, v156
	v_fmac_f32_e32 v60, v61, v138
	v_lshlrev_b32_e32 v61, 16, v153
	v_mul_f32_e32 v61, 0xbfb8aa3b, v61
	v_exp_f32_e32 v61, v61
	s_nop 0
	v_add_f32_e32 v61, 1.0, v61
	v_rcp_f32_e32 v138, v61
	v_lshlrev_b32_e32 v61, 16, v157
	v_fmac_f32_e32 v61, v62, v138
	v_and_b32_e32 v62, 0xffff0000, v153
	v_mul_f32_e32 v62, 0xbfb8aa3b, v62
	v_exp_f32_e32 v62, v62
	s_nop 0
	v_add_f32_e32 v62, 1.0, v62
	v_rcp_f32_e32 v138, v62
	v_and_b32_e32 v62, 0xffff0000, v157
	v_fmac_f32_e32 v62, v63, v138
	v_lshlrev_b32_e32 v63, 16, v154
	v_mul_f32_e32 v63, 0xbfb8aa3b, v63
	v_exp_f32_e32 v63, v63
	s_nop 0
	v_add_f32_e32 v63, 1.0, v63
	v_rcp_f32_e32 v138, v63
	v_lshlrev_b32_e32 v63, 16, v158
	v_fmac_f32_e32 v63, v56, v138
	v_and_b32_e32 v56, 0xffff0000, v154
	v_mul_f32_e32 v56, 0xbfb8aa3b, v56
	v_exp_f32_e32 v56, v56
	s_nop 0
	v_add_f32_e32 v56, 1.0, v56
	v_rcp_f32_e32 v138, v56
	v_and_b32_e32 v56, 0xffff0000, v158
	v_fmac_f32_e32 v56, v57, v138
	v_lshlrev_b32_e32 v57, 16, v155
	v_mul_f32_e32 v57, 0xbfb8aa3b, v57
	v_exp_f32_e32 v57, v57
	s_nop 0
	v_add_f32_e32 v57, 1.0, v57
	v_rcp_f32_e32 v138, v57
	v_lshlrev_b32_e32 v57, 16, v159
	v_fmac_f32_e32 v57, v58, v138
	v_and_b32_e32 v58, 0xffff0000, v155
	v_mul_f32_e32 v58, 0xbfb8aa3b, v58
	v_exp_f32_e32 v58, v58
	s_nop 0
	v_add_f32_e32 v58, 1.0, v58
	v_rcp_f32_e32 v138, v58
	v_and_b32_e32 v58, 0xffff0000, v159
	v_fmac_f32_e32 v58, v59, v138
	v_mov_b32_e32 v156, v120
	s_nop 0
	v_ashrrev_i32_e32 v157, 31, v156
	v_lshlrev_b64 v[152:153], 13, v[156:157]
	v_lshl_add_u64 v[152:153], s[2:3], 0, v[152:153]
	v_lshl_add_u64 v[152:153], v[152:153], 0, v[64:65]
	v_add_co_u32_e32 v152, vcc, s11, v152
	v_lshlrev_b64 v[156:157], 11, v[156:157]
	s_nop 0
	v_addc_co_u32_e32 v153, vcc, 0, v153, vcc
	v_lshl_add_u64 v[156:157], s[20:21], 0, v[156:157]
	v_lshl_add_u64 v[156:157], v[156:157], 0, v[134:135]
	s_waitcnt vmcnt(8)
	v_mov_b32_e32 v152, v176
	v_mov_b32_e32 v153, v177
	v_mov_b32_e32 v154, v178
	v_mov_b32_e32 v155, v179
	v_mov_b32_e32 v156, v180
	v_mov_b32_e32 v157, v181
	v_mov_b32_e32 v158, v182
	v_mov_b32_e32 v159, v183
	v_lshlrev_b32_e32 v59, 16, v152
	v_mul_f32_e32 v59, 0xbfb8aa3b, v59
	v_exp_f32_e32 v59, v59
	s_nop 0
	v_add_f32_e32 v59, 1.0, v59
	v_rcp_f32_e32 v138, v59
	v_lshlrev_b32_e32 v59, 16, v156
	v_fmac_f32_e32 v59, v52, v138
	v_and_b32_e32 v52, 0xffff0000, v152
	v_mul_f32_e32 v52, 0xbfb8aa3b, v52
	v_exp_f32_e32 v52, v52
	s_nop 0
	v_add_f32_e32 v52, 1.0, v52
	v_rcp_f32_e32 v138, v52
	v_and_b32_e32 v52, 0xffff0000, v156
	v_fmac_f32_e32 v52, v53, v138
	v_lshlrev_b32_e32 v53, 16, v153
	v_mul_f32_e32 v53, 0xbfb8aa3b, v53
	v_exp_f32_e32 v53, v53
	s_nop 0
	v_add_f32_e32 v53, 1.0, v53
	v_rcp_f32_e32 v138, v53
	v_lshlrev_b32_e32 v53, 16, v157
	v_fmac_f32_e32 v53, v54, v138
	v_and_b32_e32 v54, 0xffff0000, v153
	v_mul_f32_e32 v54, 0xbfb8aa3b, v54
	v_exp_f32_e32 v54, v54
	s_nop 0
	v_add_f32_e32 v54, 1.0, v54
	v_rcp_f32_e32 v138, v54
	v_and_b32_e32 v54, 0xffff0000, v157
	v_fmac_f32_e32 v54, v55, v138
	v_lshlrev_b32_e32 v55, 16, v154
	v_mul_f32_e32 v55, 0xbfb8aa3b, v55
	v_exp_f32_e32 v55, v55
	s_nop 0
	v_add_f32_e32 v55, 1.0, v55
	v_rcp_f32_e32 v138, v55
	v_lshlrev_b32_e32 v55, 16, v158
	v_fmac_f32_e32 v55, v48, v138
	v_and_b32_e32 v48, 0xffff0000, v154
	v_mul_f32_e32 v48, 0xbfb8aa3b, v48
	v_exp_f32_e32 v48, v48
	s_nop 0
	v_add_f32_e32 v48, 1.0, v48
	v_rcp_f32_e32 v138, v48
	v_and_b32_e32 v48, 0xffff0000, v158
	v_fmac_f32_e32 v48, v49, v138
	v_lshlrev_b32_e32 v49, 16, v155
	v_mul_f32_e32 v49, 0xbfb8aa3b, v49
	v_exp_f32_e32 v49, v49
	s_nop 0
	v_add_f32_e32 v49, 1.0, v49
	v_rcp_f32_e32 v138, v49
	v_lshlrev_b32_e32 v49, 16, v159
	v_fmac_f32_e32 v49, v50, v138
	v_and_b32_e32 v50, 0xffff0000, v155
	v_mul_f32_e32 v50, 0xbfb8aa3b, v50
	v_exp_f32_e32 v50, v50
	s_nop 0
	v_add_f32_e32 v50, 1.0, v50
	v_rcp_f32_e32 v138, v50
	v_and_b32_e32 v50, 0xffff0000, v159
	v_fmac_f32_e32 v50, v51, v138
	v_mov_b32_e32 v156, v112
	s_nop 0
	v_ashrrev_i32_e32 v157, 31, v156
	v_lshlrev_b64 v[152:153], 13, v[156:157]
	v_lshl_add_u64 v[152:153], s[2:3], 0, v[152:153]
	v_lshl_add_u64 v[152:153], v[152:153], 0, v[64:65]
	v_add_co_u32_e32 v152, vcc, s11, v152
	v_lshlrev_b64 v[156:157], 11, v[156:157]
	s_nop 0
	v_addc_co_u32_e32 v153, vcc, 0, v153, vcc
	v_lshl_add_u64 v[156:157], s[20:21], 0, v[156:157]
	v_lshl_add_u64 v[156:157], v[156:157], 0, v[134:135]
	s_waitcnt vmcnt(6)
; __device__ __forceinline__ float bf_lo(unsigned u) { return __uint_as_float(u << 16); }
; __device__ __forceinline__ float bf_hi(unsigned u) { return __uint_as_float(u & 0xffff0000u); }
; __device__ __forceinline__ float sigmoidf_(float x) { return frcp(1.0f + fexp2(-1.4426950408889634f * x)); }
; #define EPI_PIN(r) asm volatile("" : "+v"(r))
; #define EPI_FOR_BJ _Pragma("unroll") for (int bj = 0; bj < 2; ++bj)
; #define EPI_FOR_AM _Pragma("unroll") for (int ai = 0; ai < 2; ++ai) _Pragma("unroll") for (int m = 0; m < 4; ++m)
;     __device__ __forceinline__ void operator()(Acc& acc, const Unit& u, int wr, int wc, int fr, int fq) const {
;         EPI_FOR_BJ { const int c0 = EPI_COL(u, bj);
;             EPI_FOR_AM { int r = EPI_ROW(u, ai, m); EPI_PIN(r);
;                 const u32x4 gb = *(const u32x4*)(P + (size_t)r * INWP + OFF_GB + c0);
;                 const u32x4 mo = *(const u32x4*)(MG + (size_t)r * 1024 + c0);
; #pragma unroll
;                 for (int e = 0; e < 8; ++e) {
;                     const float g = sigmoidf_((e & 1) ? bf_hi(gb[e >> 1]) : bf_lo(gb[e >> 1])), o = (e & 1) ? bf_hi(mo[e >> 1]) : bf_lo(mo[e >> 1]);
;                     acc[ai][bj][m][e >> 2][e & 3] = o + acc[ai][bj][m][e >> 2][e & 3] * g;
;                 }
;                 __builtin_amdgcn_sched_barrier(0); } }
	v_mov_b32_e32 v152, v184
	v_mov_b32_e32 v153, v185
	v_mov_b32_e32 v154, v186
	v_mov_b32_e32 v155, v187
	v_mov_b32_e32 v156, v188
	v_mov_b32_e32 v157, v189
	v_mov_b32_e32 v158, v190
	v_mov_b32_e32 v159, v191
	v_lshlrev_b32_e32 v51, 16, v152
	v_mul_f32_e32 v51, 0xbfb8aa3b, v51
	v_exp_f32_e32 v51, v51
	s_nop 0
	v_add_f32_e32 v51, 1.0, v51
	v_rcp_f32_e32 v138, v51
	v_lshlrev_b32_e32 v51, 16, v156
	v_fmac_f32_e32 v51, v44, v138
	v_and_b32_e32 v44, 0xffff0000, v152
	v_mul_f32_e32 v44, 0xbfb8aa3b, v44
	v_exp_f32_e32 v44, v44
	s_nop 0
	v_add_f32_e32 v44, 1.0, v44
	v_rcp_f32_e32 v138, v44
	v_and_b32_e32 v44, 0xffff0000, v156
	v_fmac_f32_e32 v44, v45, v138
	v_lshlrev_b32_e32 v45, 16, v153
	v_mul_f32_e32 v45, 0xbfb8aa3b, v45
	v_exp_f32_e32 v45, v45
	s_nop 0
	v_add_f32_e32 v45, 1.0, v45
	v_rcp_f32_e32 v138, v45
	v_lshlrev_b32_e32 v45, 16, v157
	v_fmac_f32_e32 v45, v46, v138
	v_and_b32_e32 v46, 0xffff0000, v153
	v_mul_f32_e32 v46, 0xbfb8aa3b, v46
	v_exp_f32_e32 v46, v46
	s_nop 0
	v_add_f32_e32 v46, 1.0, v46
	v_rcp_f32_e32 v138, v46
	v_and_b32_e32 v46, 0xffff0000, v157
	v_fmac_f32_e32 v46, v47, v138
	v_lshlrev_b32_e32 v47, 16, v154
	v_mul_f32_e32 v47, 0xbfb8aa3b, v47
	v_exp_f32_e32 v47, v47
	s_nop 0
	v_add_f32_e32 v47, 1.0, v47
	v_rcp_f32_e32 v138, v47
	v_lshlrev_b32_e32 v47, 16, v158
	v_fmac_f32_e32 v47, v40, v138
	v_and_b32_e32 v40, 0xffff0000, v154
	v_mul_f32_e32 v40, 0xbfb8aa3b, v40
	v_exp_f32_e32 v40, v40
	s_nop 0
	v_add_f32_e32 v40, 1.0, v40
	v_rcp_f32_e32 v138, v40
	v_and_b32_e32 v40, 0xffff0000, v158
	v_fmac_f32_e32 v40, v41, v138
	v_lshlrev_b32_e32 v41, 16, v155
	v_mul_f32_e32 v41, 0xbfb8aa3b, v41
	v_exp_f32_e32 v41, v41
	s_nop 0
	v_add_f32_e32 v41, 1.0, v41
	v_rcp_f32_e32 v138, v41
	v_lshlrev_b32_e32 v41, 16, v159
	v_fmac_f32_e32 v41, v42, v138
	v_and_b32_e32 v42, 0xffff0000, v155
	v_mul_f32_e32 v42, 0xbfb8aa3b, v42
	v_exp_f32_e32 v42, v42
	s_nop 0
	v_add_f32_e32 v42, 1.0, v42
	v_rcp_f32_e32 v138, v42
	v_and_b32_e32 v42, 0xffff0000, v159
	v_fmac_f32_e32 v42, v43, v138
	v_mov_b32_e32 v156, v104
	s_nop 0
	v_ashrrev_i32_e32 v157, 31, v156
	v_lshlrev_b64 v[152:153], 13, v[156:157]
	v_lshl_add_u64 v[152:153], s[2:3], 0, v[152:153]
	v_lshl_add_u64 v[152:153], v[152:153], 0, v[64:65]
	v_add_co_u32_e32 v152, vcc, s11, v152
	v_lshlrev_b64 v[156:157], 11, v[156:157]
	s_nop 0
	v_addc_co_u32_e32 v153, vcc, 0, v153, vcc
	v_lshl_add_u64 v[156:157], s[20:21], 0, v[156:157]
	v_lshl_add_u64 v[156:157], v[156:157], 0, v[134:135]
	s_waitcnt vmcnt(4)
	v_mov_b32_e32 v152, v192
	v_mov_b32_e32 v153, v193
	v_mov_b32_e32 v154, v194
	v_mov_b32_e32 v155, v195
	v_mov_b32_e32 v156, v206
	v_mov_b32_e32 v157, v207
	v_mov_b32_e32 v158, v208
	v_mov_b32_e32 v159, v209
	v_lshlrev_b32_e32 v43, 16, v152
	v_mul_f32_e32 v43, 0xbfb8aa3b, v43
	v_exp_f32_e32 v43, v43
	s_nop 0
	v_add_f32_e32 v43, 1.0, v43
	v_rcp_f32_e32 v138, v43
	v_lshlrev_b32_e32 v43, 16, v156
	v_fmac_f32_e32 v43, v36, v138
	v_and_b32_e32 v36, 0xffff0000, v152
	v_mul_f32_e32 v36, 0xbfb8aa3b, v36
	v_exp_f32_e32 v36, v36
	s_nop 0
	v_add_f32_e32 v36, 1.0, v36
	v_rcp_f32_e32 v138, v36
	v_and_b32_e32 v36, 0xffff0000, v156
	v_fmac_f32_e32 v36, v37, v138
	v_lshlrev_b32_e32 v37, 16, v153
	v_mul_f32_e32 v37, 0xbfb8aa3b, v37
	v_exp_f32_e32 v37, v37
	s_nop 0
	v_add_f32_e32 v37, 1.0, v37
	v_rcp_f32_e32 v138, v37
	v_lshlrev_b32_e32 v37, 16, v157
	v_fmac_f32_e32 v37, v38, v138
	v_and_b32_e32 v38, 0xffff0000, v153
	v_mul_f32_e32 v38, 0xbfb8aa3b, v38
	v_exp_f32_e32 v38, v38
	s_nop 0
	v_add_f32_e32 v38, 1.0, v38
	v_rcp_f32_e32 v138, v38
	v_and_b32_e32 v38, 0xffff0000, v157
	v_fmac_f32_e32 v38, v39, v138
	v_lshlrev_b32_e32 v39, 16, v154
	v_mul_f32_e32 v39, 0xbfb8aa3b, v39
	v_exp_f32_e32 v39, v39
	s_nop 0
	v_add_f32_e32 v39, 1.0, v39
	v_rcp_f32_e32 v138, v39
	v_lshlrev_b32_e32 v39, 16, v158
	v_fmac_f32_e32 v39, v32, v138
	v_and_b32_e32 v32, 0xffff0000, v154
	v_mul_f32_e32 v32, 0xbfb8aa3b, v32
	v_exp_f32_e32 v32, v32
	s_nop 0
	v_add_f32_e32 v32, 1.0, v32
	v_rcp_f32_e32 v138, v32
	v_and_b32_e32 v32, 0xffff0000, v158
	v_fmac_f32_e32 v32, v33, v138
	v_lshlrev_b32_e32 v33, 16, v155
	v_mul_f32_e32 v33, 0xbfb8aa3b, v33
	v_exp_f32_e32 v33, v33
	s_nop 0
	v_add_f32_e32 v33, 1.0, v33
	v_rcp_f32_e32 v138, v33
	v_lshlrev_b32_e32 v33, 16, v159
	v_fmac_f32_e32 v33, v34, v138
	v_and_b32_e32 v34, 0xffff0000, v155
	v_mul_f32_e32 v34, 0xbfb8aa3b, v34
	v_exp_f32_e32 v34, v34
	s_nop 0
	v_add_f32_e32 v34, 1.0, v34
	v_rcp_f32_e32 v138, v34
	v_and_b32_e32 v34, 0xffff0000, v159
	v_fmac_f32_e32 v34, v35, v138
	v_mov_b32_e32 v156, v96
	s_nop 0
	v_ashrrev_i32_e32 v157, 31, v156
	v_lshlrev_b64 v[152:153], 13, v[156:157]
	v_lshl_add_u64 v[152:153], s[2:3], 0, v[152:153]
	v_lshl_add_u64 v[152:153], v[152:153], 0, v[64:65]
	v_add_co_u32_e32 v152, vcc, s11, v152
	v_lshlrev_b64 v[156:157], 11, v[156:157]
	s_nop 0
	v_addc_co_u32_e32 v153, vcc, 0, v153, vcc
	v_lshl_add_u64 v[156:157], s[20:21], 0, v[156:157]
	v_lshl_add_u64 v[156:157], v[156:157], 0, v[134:135]
	s_waitcnt vmcnt(2)
; __device__ __forceinline__ float bf_lo(unsigned u) { return __uint_as_float(u << 16); }
; __device__ __forceinline__ float bf_hi(unsigned u) { return __uint_as_float(u & 0xffff0000u); }
; __device__ __forceinline__ float sigmoidf_(float x) { return frcp(1.0f + fexp2(-1.4426950408889634f * x)); }
; #define EPI_PIN(r) asm volatile("" : "+v"(r))
; #define EPI_FOR_BJ _Pragma("unroll") for (int bj = 0; bj < 2; ++bj)
; #define EPI_FOR_AM _Pragma("unroll") for (int ai = 0; ai < 2; ++ai) _Pragma("unroll") for (int m = 0; m < 4; ++m)
;     __device__ __forceinline__ void operator()(Acc& acc, const Unit& u, int wr, int wc, int fr, int fq) const {
;         EPI_FOR_BJ { const int c0 = EPI_COL(u, bj);
;             EPI_FOR_AM { int r = EPI_ROW(u, ai, m); EPI_PIN(r);
;                 const u32x4 gb = *(const u32x4*)(P + (size_t)r * INWP + OFF_GB + c0);
;                 const u32x4 mo = *(const u32x4*)(MG + (size_t)r * 1024 + c0);
; #pragma unroll
;                 for (int e = 0; e < 8; ++e) {
;                     const float g = sigmoidf_((e & 1) ? bf_hi(gb[e >> 1]) : bf_lo(gb[e >> 1])), o = (e & 1) ? bf_hi(mo[e >> 1]) : bf_lo(mo[e >> 1]);
;                     acc[ai][bj][m][e >> 2][e & 3] = o + acc[ai][bj][m][e >> 2][e & 3] * g;
;                 }
;                 __builtin_amdgcn_sched_barrier(0); } }
	v_mov_b32_e32 v152, v210
	v_mov_b32_e32 v153, v211
	v_mov_b32_e32 v154, v212
	v_mov_b32_e32 v155, v213
	v_mov_b32_e32 v156, v214
	v_mov_b32_e32 v157, v215
	v_mov_b32_e32 v158, v216
	v_mov_b32_e32 v159, v217
	v_lshlrev_b32_e32 v35, 16, v152
	v_mul_f32_e32 v35, 0xbfb8aa3b, v35
	v_exp_f32_e32 v35, v35
	s_nop 0
	v_add_f32_e32 v35, 1.0, v35
	v_rcp_f32_e32 v138, v35
	v_lshlrev_b32_e32 v35, 16, v156
	v_fmac_f32_e32 v35, v28, v138
	v_and_b32_e32 v28, 0xffff0000, v152
	v_mul_f32_e32 v28, 0xbfb8aa3b, v28
	v_exp_f32_e32 v28, v28
	s_nop 0
	v_add_f32_e32 v28, 1.0, v28
	v_rcp_f32_e32 v138, v28
	v_and_b32_e32 v28, 0xffff0000, v156
	v_fmac_f32_e32 v28, v29, v138
	v_lshlrev_b32_e32 v29, 16, v153
	v_mul_f32_e32 v29, 0xbfb8aa3b, v29
	v_exp_f32_e32 v29, v29
	s_nop 0
	v_add_f32_e32 v29, 1.0, v29
	v_rcp_f32_e32 v138, v29
	v_lshlrev_b32_e32 v29, 16, v157
	v_fmac_f32_e32 v29, v30, v138
	v_and_b32_e32 v30, 0xffff0000, v153
	v_mul_f32_e32 v30, 0xbfb8aa3b, v30
	v_exp_f32_e32 v30, v30
	s_nop 0
	v_add_f32_e32 v30, 1.0, v30
	v_rcp_f32_e32 v138, v30
	v_and_b32_e32 v30, 0xffff0000, v157
	v_fmac_f32_e32 v30, v31, v138
	v_lshlrev_b32_e32 v31, 16, v154
	v_mul_f32_e32 v31, 0xbfb8aa3b, v31
	v_exp_f32_e32 v31, v31
	s_nop 0
	v_add_f32_e32 v31, 1.0, v31
	v_rcp_f32_e32 v138, v31
	v_lshlrev_b32_e32 v31, 16, v158
	v_fmac_f32_e32 v31, v24, v138
	v_and_b32_e32 v24, 0xffff0000, v154
	v_mul_f32_e32 v24, 0xbfb8aa3b, v24
	v_exp_f32_e32 v24, v24
	s_nop 0
	v_add_f32_e32 v24, 1.0, v24
	v_rcp_f32_e32 v138, v24
	v_and_b32_e32 v24, 0xffff0000, v158
	v_fmac_f32_e32 v24, v25, v138
	v_lshlrev_b32_e32 v25, 16, v155
	v_mul_f32_e32 v25, 0xbfb8aa3b, v25
	v_exp_f32_e32 v25, v25
	s_nop 0
	v_add_f32_e32 v25, 1.0, v25
	v_rcp_f32_e32 v138, v25
	v_lshlrev_b32_e32 v25, 16, v159
	v_fmac_f32_e32 v25, v26, v138
	v_and_b32_e32 v26, 0xffff0000, v155
	v_mul_f32_e32 v26, 0xbfb8aa3b, v26
	v_exp_f32_e32 v26, v26
	s_nop 0
	v_add_f32_e32 v26, 1.0, v26
	v_rcp_f32_e32 v138, v26
	v_and_b32_e32 v26, 0xffff0000, v159
	v_fmac_f32_e32 v26, v27, v138
	v_mov_b32_e32 v156, v88
	s_nop 0
	v_ashrrev_i32_e32 v157, 31, v156
	v_lshlrev_b64 v[152:153], 13, v[156:157]
	v_lshl_add_u64 v[152:153], s[2:3], 0, v[152:153]
	v_lshl_add_u64 v[152:153], v[152:153], 0, v[64:65]
	v_add_co_u32_e32 v152, vcc, s11, v152
	v_lshlrev_b64 v[156:157], 11, v[156:157]
	s_nop 0
	v_addc_co_u32_e32 v153, vcc, 0, v153, vcc
	v_lshl_add_u64 v[156:157], s[20:21], 0, v[156:157]
	v_lshl_add_u64 v[156:157], v[156:157], 0, v[134:135]
	s_waitcnt vmcnt(0)
	v_mov_b32_e32 v152, v218
	v_mov_b32_e32 v153, v219
	v_mov_b32_e32 v154, v220
	v_mov_b32_e32 v155, v221
	v_mov_b32_e32 v156, v222
	v_mov_b32_e32 v157, v223
	v_mov_b32_e32 v158, v224
	v_mov_b32_e32 v159, v225
	s_mov_b32 s86, 0x140100
	v_lshl_add_u64 v[196:197], v[198:199], 0, s[86:87]
	global_load_dwordx4 v[160:163], v[196:197], off offset:1856
	s_mov_b32 s88, 0x50100
	v_lshl_add_u64 v[196:197], v[230:231], 0, s[88:89]
	global_load_dwordx4 v[164:167], v[196:197], off
	s_mov_b32 s86, 0x160100
	v_lshl_add_u64 v[196:197], v[198:199], 0, s[86:87]
	global_load_dwordx4 v[168:171], v[196:197], off offset:1856
	s_mov_b32 s88, 0x58100
	v_lshl_add_u64 v[196:197], v[230:231], 0, s[88:89]
	global_load_dwordx4 v[172:175], v[196:197], off
	v_lshlrev_b32_e32 v27, 16, v152
	v_mul_f32_e32 v27, 0xbfb8aa3b, v27
	v_exp_f32_e32 v27, v27
	s_nop 0
	v_add_f32_e32 v27, 1.0, v27
	v_rcp_f32_e32 v138, v27
	v_lshlrev_b32_e32 v27, 16, v156
	v_fmac_f32_e32 v27, v20, v138
	v_and_b32_e32 v20, 0xffff0000, v152
	v_mul_f32_e32 v20, 0xbfb8aa3b, v20
	v_exp_f32_e32 v20, v20
	s_nop 0
	v_add_f32_e32 v20, 1.0, v20
	v_rcp_f32_e32 v138, v20
	v_and_b32_e32 v20, 0xffff0000, v156
	v_fmac_f32_e32 v20, v21, v138
	v_lshlrev_b32_e32 v21, 16, v153
	v_mul_f32_e32 v21, 0xbfb8aa3b, v21
	v_exp_f32_e32 v21, v21
	s_nop 0
	v_add_f32_e32 v21, 1.0, v21
	v_rcp_f32_e32 v138, v21
	v_lshlrev_b32_e32 v21, 16, v157
	v_fmac_f32_e32 v21, v22, v138
	v_and_b32_e32 v22, 0xffff0000, v153
	v_mul_f32_e32 v22, 0xbfb8aa3b, v22
	v_exp_f32_e32 v22, v22
	s_nop 0
	v_add_f32_e32 v22, 1.0, v22
	v_rcp_f32_e32 v138, v22
	v_and_b32_e32 v22, 0xffff0000, v157
	v_fmac_f32_e32 v22, v23, v138
	v_lshlrev_b32_e32 v23, 16, v154
	v_mul_f32_e32 v23, 0xbfb8aa3b, v23
	v_exp_f32_e32 v23, v23
	s_nop 0
	v_add_f32_e32 v23, 1.0, v23
	v_rcp_f32_e32 v138, v23
	v_lshlrev_b32_e32 v23, 16, v158
	v_fmac_f32_e32 v23, v16, v138
	v_and_b32_e32 v16, 0xffff0000, v154
	v_mul_f32_e32 v16, 0xbfb8aa3b, v16
	v_exp_f32_e32 v16, v16
	s_nop 0
	v_add_f32_e32 v16, 1.0, v16
	v_rcp_f32_e32 v138, v16
	v_and_b32_e32 v16, 0xffff0000, v158
	v_fmac_f32_e32 v16, v17, v138
	v_lshlrev_b32_e32 v17, 16, v155
	v_mul_f32_e32 v17, 0xbfb8aa3b, v17
	v_exp_f32_e32 v17, v17
	s_nop 0
	v_add_f32_e32 v17, 1.0, v17
	v_rcp_f32_e32 v138, v17
	v_lshlrev_b32_e32 v17, 16, v159
	v_fmac_f32_e32 v17, v18, v138
	v_and_b32_e32 v18, 0xffff0000, v155
	v_mul_f32_e32 v18, 0xbfb8aa3b, v18
	v_exp_f32_e32 v18, v18
	s_nop 0
	v_add_f32_e32 v18, 1.0, v18
	v_rcp_f32_e32 v138, v18
	v_and_b32_e32 v18, 0xffff0000, v159
	v_fmac_f32_e32 v18, v19, v138
	v_mov_b32_e32 v156, v80
	s_nop 0
	v_ashrrev_i32_e32 v157, 31, v156
	v_lshlrev_b64 v[152:153], 13, v[156:157]
	v_lshl_add_u64 v[152:153], s[2:3], 0, v[152:153]
	v_lshl_add_u64 v[152:153], v[152:153], 0, v[64:65]
	v_add_co_u32_e32 v152, vcc, s11, v152
	v_lshlrev_b64 v[156:157], 11, v[156:157]
	s_nop 0
	v_addc_co_u32_e32 v153, vcc, 0, v153, vcc
	v_lshl_add_u64 v[156:157], s[20:21], 0, v[156:157]
	v_lshl_add_u64 v[156:157], v[156:157], 0, v[134:135]
	s_waitcnt vmcnt(2)
; __device__ __forceinline__ float bf_lo(unsigned u) { return __uint_as_float(u << 16); }
; __device__ __forceinline__ float bf_hi(unsigned u) { return __uint_as_float(u & 0xffff0000u); }
; __device__ __forceinline__ float sigmoidf_(float x) { return frcp(1.0f + fexp2(-1.4426950408889634f * x)); }
; #define EPI_PIN(r) asm volatile("" : "+v"(r))
; #define EPI_FOR_BJ _Pragma("unroll") for (int bj = 0; bj < 2; ++bj)
; #define EPI_FOR_AM _Pragma("unroll") for (int ai = 0; ai < 2; ++ai) _Pragma("unroll") for (int m = 0; m < 4; ++m)
; __device__ __forceinline__ u32x4 pack8(const f32x4 a, const f32x4 b) { u32x4 o = {pk_bf16(a[0], a[1]), pk_bf16(a[2], a[3]), pk_bf16(b[0], b[1]), pk_bf16(b[2], b[3])}; return o; }
;     __device__ __forceinline__ void operator()(Acc& acc, const Unit& u, int wr, int wc, int fr, int fq) const {
;         EPI_FOR_BJ { const int c0 = EPI_COL(u, bj);
;             EPI_FOR_AM { int r = EPI_ROW(u, ai, m); EPI_PIN(r);
;                 const u32x4 gb = *(const u32x4*)(P + (size_t)r * INWP + OFF_GB + c0);
;                 const u32x4 mo = *(const u32x4*)(MG + (size_t)r * 1024 + c0);
; #pragma unroll
;                 for (int e = 0; e < 8; ++e) {
;                     const float g = sigmoidf_((e & 1) ? bf_hi(gb[e >> 1]) : bf_lo(gb[e >> 1])), o = (e & 1) ? bf_hi(mo[e >> 1]) : bf_lo(mo[e >> 1]);
;                     acc[ai][bj][m][e >> 2][e & 3] = o + acc[ai][bj][m][e >> 2][e & 3] * g;
;                 }
;                 __builtin_amdgcn_sched_barrier(0); } }
;         EPI_FOR_BJ { const int c0 = EPI_COL(u, bj);
;             EPI_FOR_AM { int r = EPI_ROW(u, ai, m); EPI_PIN(r);
;                 *(u32x4*)(MG + (size_t)r * 1024 + c0) = pack8(acc[ai][bj][m][0], acc[ai][bj][m][1]);
	v_mov_b32_e32 v152, v160
	v_mov_b32_e32 v153, v161
	v_mov_b32_e32 v154, v162
	v_mov_b32_e32 v155, v163
	v_mov_b32_e32 v156, v164
	v_mov_b32_e32 v157, v165
	v_mov_b32_e32 v158, v166
	v_mov_b32_e32 v159, v167
	v_lshlrev_b32_e32 v19, 16, v152
	v_mul_f32_e32 v19, 0xbfb8aa3b, v19
	v_exp_f32_e32 v19, v19
	s_nop 0
	v_add_f32_e32 v19, 1.0, v19
	v_rcp_f32_e32 v138, v19
	v_lshlrev_b32_e32 v19, 16, v156
	v_fmac_f32_e32 v19, v12, v138
	v_and_b32_e32 v12, 0xffff0000, v152
	v_mul_f32_e32 v12, 0xbfb8aa3b, v12
	v_exp_f32_e32 v12, v12
	s_nop 0
	v_add_f32_e32 v12, 1.0, v12
	v_rcp_f32_e32 v138, v12
	v_and_b32_e32 v12, 0xffff0000, v156
	v_fmac_f32_e32 v12, v13, v138
	v_lshlrev_b32_e32 v13, 16, v153
	v_mul_f32_e32 v13, 0xbfb8aa3b, v13
	v_exp_f32_e32 v13, v13
	s_nop 0
	v_add_f32_e32 v13, 1.0, v13
	v_rcp_f32_e32 v138, v13
	v_lshlrev_b32_e32 v13, 16, v157
	v_fmac_f32_e32 v13, v14, v138
	v_and_b32_e32 v14, 0xffff0000, v153
	v_mul_f32_e32 v14, 0xbfb8aa3b, v14
	v_exp_f32_e32 v14, v14
	s_nop 0
	v_add_f32_e32 v14, 1.0, v14
	v_rcp_f32_e32 v138, v14
	v_and_b32_e32 v14, 0xffff0000, v157
	v_fmac_f32_e32 v14, v15, v138
	v_lshlrev_b32_e32 v15, 16, v154
	v_mul_f32_e32 v15, 0xbfb8aa3b, v15
	v_exp_f32_e32 v15, v15
	s_nop 0
	v_add_f32_e32 v15, 1.0, v15
	v_rcp_f32_e32 v138, v15
	v_lshlrev_b32_e32 v15, 16, v158
	v_fmac_f32_e32 v15, v8, v138
	v_and_b32_e32 v8, 0xffff0000, v154
	v_mul_f32_e32 v8, 0xbfb8aa3b, v8
	v_exp_f32_e32 v8, v8
	s_nop 0
	v_add_f32_e32 v8, 1.0, v8
	v_rcp_f32_e32 v138, v8
	v_and_b32_e32 v8, 0xffff0000, v158
	v_fmac_f32_e32 v8, v9, v138
	v_lshlrev_b32_e32 v9, 16, v155
	v_mul_f32_e32 v9, 0xbfb8aa3b, v9
	v_exp_f32_e32 v9, v9
	s_nop 0
	v_add_f32_e32 v9, 1.0, v9
	v_rcp_f32_e32 v138, v9
	v_lshlrev_b32_e32 v9, 16, v159
	v_fmac_f32_e32 v9, v10, v138
	v_and_b32_e32 v10, 0xffff0000, v155
	v_mul_f32_e32 v10, 0xbfb8aa3b, v10
	v_exp_f32_e32 v10, v10
	s_nop 0
	v_add_f32_e32 v10, 1.0, v10
	v_rcp_f32_e32 v138, v10
	v_and_b32_e32 v10, 0xffff0000, v159
	v_fmac_f32_e32 v10, v11, v138
	v_mov_b32_e32 v156, v72
	s_nop 0
	v_ashrrev_i32_e32 v157, 31, v156
	v_lshlrev_b64 v[152:153], 13, v[156:157]
	v_lshl_add_u64 v[152:153], s[2:3], 0, v[152:153]
	v_lshl_add_u64 v[64:65], v[152:153], 0, v[64:65]
	v_add_co_u32_e32 v64, vcc, s11, v64
	s_nop 1
	v_addc_co_u32_e32 v65, vcc, 0, v65, vcc
	v_lshlrev_b64 v[64:65], 11, v[156:157]
	v_lshl_add_u64 v[64:65], s[20:21], 0, v[64:65]
	v_lshl_add_u64 v[64:65], v[64:65], 0, v[134:135]
	s_waitcnt vmcnt(0)
	v_mov_b32_e32 v152, v168
	v_mov_b32_e32 v153, v169
	v_mov_b32_e32 v154, v170
	v_mov_b32_e32 v155, v171
	v_mov_b32_e32 v156, v172
	v_mov_b32_e32 v157, v173
	v_mov_b32_e32 v158, v174
	v_mov_b32_e32 v159, v175
	v_lshlrev_b32_e32 v11, 16, v152
	v_mul_f32_e32 v11, 0xbfb8aa3b, v11
	v_exp_f32_e32 v11, v11
	v_lshlrev_b32_e32 v138, 16, v158
	v_add_f32_e32 v11, 1.0, v11
	v_rcp_f32_e32 v64, v11
	v_lshlrev_b32_e32 v11, 16, v156
	v_fmac_f32_e32 v11, v4, v64
	v_and_b32_e32 v4, 0xffff0000, v152
	v_mul_f32_e32 v4, 0xbfb8aa3b, v4
	v_exp_f32_e32 v4, v4
	v_lshlrev_b32_e32 v152, 16, v159
	v_add_f32_e32 v4, 1.0, v4
	v_rcp_f32_e32 v64, v4
	v_and_b32_e32 v4, 0xffff0000, v156
	v_fmac_f32_e32 v4, v5, v64
	v_lshlrev_b32_e32 v5, 16, v153
	v_mul_f32_e32 v5, 0xbfb8aa3b, v5
	v_exp_f32_e32 v5, v5
	s_nop 0
	v_add_f32_e32 v5, 1.0, v5
	v_rcp_f32_e32 v64, v5
	v_lshlrev_b32_e32 v5, 16, v157
	v_fmac_f32_e32 v5, v6, v64
	v_and_b32_e32 v6, 0xffff0000, v153
	v_mul_f32_e32 v6, 0xbfb8aa3b, v6
	v_exp_f32_e32 v6, v6
	v_and_b32_e32 v153, 0xffff0000, v159
	v_add_f32_e32 v6, 1.0, v6
	v_rcp_f32_e32 v64, v6
	v_and_b32_e32 v6, 0xffff0000, v157
	v_fmac_f32_e32 v6, v7, v64
	v_lshlrev_b32_e32 v7, 16, v154
	v_mul_f32_e32 v7, 0xbfb8aa3b, v7
	v_exp_f32_e32 v7, v7
	s_nop 0
	v_add_f32_e32 v7, 1.0, v7
	v_rcp_f32_e32 v7, v7
	s_nop 0
	v_fmac_f32_e32 v138, v0, v7
	v_and_b32_e32 v0, 0xffff0000, v154
	v_mul_f32_e32 v0, 0xbfb8aa3b, v0
	v_exp_f32_e32 v0, v0
	v_and_b32_e32 v7, 0xffff0000, v158
	v_add_f32_e32 v0, 1.0, v0
	v_rcp_f32_e32 v0, v0
	s_nop 0
	v_fmac_f32_e32 v7, v1, v0
	v_lshlrev_b32_e32 v0, 16, v155
	v_mul_f32_e32 v0, 0xbfb8aa3b, v0
	v_exp_f32_e32 v0, v0
	s_nop 0
	v_add_f32_e32 v0, 1.0, v0
	v_rcp_f32_e32 v0, v0
	s_nop 0
	v_fmac_f32_e32 v152, v2, v0
	v_and_b32_e32 v0, 0xffff0000, v155
	v_mul_f32_e32 v0, 0xbfb8aa3b, v0
	v_exp_f32_e32 v0, v0
	s_nop 0
	v_add_f32_e32 v0, 1.0, v0
	v_rcp_f32_e32 v0, v0
	s_nop 0
	v_fmac_f32_e32 v153, v3, v0
	v_mov_b32_e32 v64, v136
	v_cvt_pk_bf16_f32 v0, v137, v124
	v_cvt_pk_bf16_f32 v1, v125, v126
	v_cvt_pk_bf16_f32 v2, v127, v139
	v_cvt_pk_bf16_f32 v3, v121, v122
	s_nop 0
	v_ashrrev_i32_e32 v65, 31, v64
	v_lshlrev_b64 v[64:65], 11, v[64:65]
	v_lshl_add_u64 v[64:65], s[20:21], 0, v[64:65]
	v_lshl_add_u64 v[64:65], v[64:65], 0, v[134:135]
	global_store_dwordx4 v[64:65], v[0:3], off
	v_mov_b32_e32 v64, v120
	s_nop 0
	v_cvt_pk_bf16_f32 v0, v123, v116
	v_cvt_pk_bf16_f32 v1, v117, v118
	v_cvt_pk_bf16_f32 v2, v119, v144
	v_cvt_pk_bf16_f32 v3, v113, v114
	v_ashrrev_i32_e32 v65, 31, v64
	v_lshlrev_b64 v[64:65], 11, v[64:65]
	v_lshl_add_u64 v[64:65], s[20:21], 0, v[64:65]
	v_lshl_add_u64 v[64:65], v[64:65], 0, v[134:135]
	global_store_dwordx4 v[64:65], v[0:3], off
	v_mov_b32_e32 v64, v112
	s_nop 0
	v_cvt_pk_bf16_f32 v0, v115, v108
	v_cvt_pk_bf16_f32 v1, v109, v110
	v_cvt_pk_bf16_f32 v2, v111, v145
	v_cvt_pk_bf16_f32 v3, v105, v106
; #define PG8_WAIT_V(n) asm volatile("s_waitcnt vmcnt(" #n ")" ::: "memory")
; #define PG8_BAR __builtin_amdgcn_s_barrier()
; #define EPI_PIN(r) asm volatile("" : "+v"(r))
; #define EPI_FOR_BJ _Pragma("unroll") for (int bj = 0; bj < 2; ++bj)
; #define EPI_FOR_AM _Pragma("unroll") for (int ai = 0; ai < 2; ++ai) _Pragma("unroll") for (int m = 0; m < 4; ++m)
; __device__ __forceinline__ u32x4 pack8(const f32x4 a, const f32x4 b) { u32x4 o = {pk_bf16(a[0], a[1]), pk_bf16(a[2], a[3]), pk_bf16(b[0], b[1]), pk_bf16(b[2], b[3])}; return o; }
; template <class Epi, class Sched, bool GATHER = false>
; __device__ __forceinline__ void gemm_phase(LAS unsigned char* lds, const int K, const int lda, const Sched& S, const Epi& E, const int wid_s, const LAS int* rowoff = nullptr) {
;     ...
;         if (!has_next) break;
; #pragma unroll
;         for (int a = 0; a < 2; ++a)
; #pragma unroll
;             for (int b = 0; b < 2; ++b)
; #pragma unroll
;                 for (int m = 0; m < 4; ++m)
; #pragma unroll
;                     for (int n = 0; n < 2; ++n) acc[a][b][m][n] = (f32x4){0.f, 0.f, 0.f, 0.f};
;         cur = nxt; cA = nA; cB = nB; ++ui;
;         if (GATHER) { _Pragma("unroll") for (int h_ = 0; h_ < 2; ++h_) _Pragma("unroll") for (int i_ = 0; i_ < 2; ++i_) gcur[h_][i_] = gnxt[h_][i_]; }
;     }
;     PG8_WAIT_V(0);
;     if (wr == 0) PG8_BAR;
;     PG8_BAR;
;     __device__ __forceinline__ void operator()(Acc& acc, const Unit& u, int wr, int wc, int fr, int fq) const {
;     ...
;         EPI_FOR_BJ { const int c0 = EPI_COL(u, bj);
;             EPI_FOR_AM { int r = EPI_ROW(u, ai, m); EPI_PIN(r);
;                 *(u32x4*)(MG + (size_t)r * 1024 + c0) = pack8(acc[ai][bj][m][0], acc[ai][bj][m][1]);
;                 __builtin_amdgcn_sched_barrier(0); } }
	v_ashrrev_i32_e32 v65, 31, v64
	v_lshlrev_b64 v[64:65], 11, v[64:65]
	v_lshl_add_u64 v[64:65], s[20:21], 0, v[64:65]
	v_lshl_add_u64 v[64:65], v[64:65], 0, v[134:135]
	global_store_dwordx4 v[64:65], v[0:3], off
	v_mov_b32_e32 v64, v104
	s_nop 0
	v_cvt_pk_bf16_f32 v0, v107, v100
	v_cvt_pk_bf16_f32 v1, v101, v102
	v_cvt_pk_bf16_f32 v2, v103, v146
	v_cvt_pk_bf16_f32 v3, v97, v98
	v_ashrrev_i32_e32 v65, 31, v64
	v_lshlrev_b64 v[64:65], 11, v[64:65]
	v_lshl_add_u64 v[64:65], s[20:21], 0, v[64:65]
	v_lshl_add_u64 v[64:65], v[64:65], 0, v[134:135]
	global_store_dwordx4 v[64:65], v[0:3], off
	v_mov_b32_e32 v64, v96
	s_nop 0
	v_cvt_pk_bf16_f32 v0, v99, v92
	v_cvt_pk_bf16_f32 v1, v93, v94
	v_cvt_pk_bf16_f32 v2, v95, v147
	v_cvt_pk_bf16_f32 v3, v89, v90
	v_ashrrev_i32_e32 v65, 31, v64
	v_lshlrev_b64 v[64:65], 11, v[64:65]
	v_lshl_add_u64 v[64:65], s[20:21], 0, v[64:65]
	v_lshl_add_u64 v[64:65], v[64:65], 0, v[134:135]
	global_store_dwordx4 v[64:65], v[0:3], off
	v_mov_b32_e32 v64, v88
	s_nop 0
	v_cvt_pk_bf16_f32 v0, v91, v84
	v_cvt_pk_bf16_f32 v1, v85, v86
	v_cvt_pk_bf16_f32 v2, v87, v148
	v_cvt_pk_bf16_f32 v3, v81, v82
	v_ashrrev_i32_e32 v65, 31, v64
	v_lshlrev_b64 v[64:65], 11, v[64:65]
	v_lshl_add_u64 v[64:65], s[20:21], 0, v[64:65]
	v_lshl_add_u64 v[64:65], v[64:65], 0, v[134:135]
	global_store_dwordx4 v[64:65], v[0:3], off
	v_mov_b32_e32 v64, v80
	s_nop 0
	v_cvt_pk_bf16_f32 v0, v83, v76
	v_cvt_pk_bf16_f32 v1, v77, v78
	v_cvt_pk_bf16_f32 v2, v79, v149
	v_cvt_pk_bf16_f32 v3, v73, v74
	v_ashrrev_i32_e32 v65, 31, v64
	v_lshlrev_b64 v[64:65], 11, v[64:65]
	v_lshl_add_u64 v[64:65], s[20:21], 0, v[64:65]
	v_lshl_add_u64 v[64:65], v[64:65], 0, v[134:135]
	global_store_dwordx4 v[64:65], v[0:3], off
	v_mov_b32_e32 v64, v72
	s_nop 0
	v_cvt_pk_bf16_f32 v0, v75, v68
	v_cvt_pk_bf16_f32 v1, v69, v70
	v_cvt_pk_bf16_f32 v2, v71, v150
	v_cvt_pk_bf16_f32 v3, v151, v66
	v_ashrrev_i32_e32 v65, 31, v64
	v_lshlrev_b64 v[64:65], 11, v[64:65]
	v_lshl_add_u64 v[64:65], s[20:21], 0, v[64:65]
	v_lshl_add_u64 v[64:65], v[64:65], 0, v[134:135]
	global_store_dwordx4 v[64:65], v[0:3], off
	s_nop 1
	v_cvt_pk_bf16_f32 v2, v63, v56
	v_cvt_pk_bf16_f32 v3, v57, v58
	v_cvt_pk_bf16_f32 v0, v67, v60
	v_cvt_pk_bf16_f32 v1, v61, v62
	v_ashrrev_i32_e32 v137, 31, v136
	v_lshlrev_b64 v[56:57], 11, v[136:137]
	v_lshl_add_u64 v[56:57], s[20:21], 0, v[56:57]
	v_lshl_add_u64 v[56:57], v[56:57], 0, v[134:135]
	global_store_dwordx4 v[56:57], v[0:3], off offset:256
	s_nop 1
	v_cvt_pk_bf16_f32 v2, v55, v48
	v_cvt_pk_bf16_f32 v3, v49, v50
	v_cvt_pk_bf16_f32 v0, v59, v52
	v_cvt_pk_bf16_f32 v1, v53, v54
	v_ashrrev_i32_e32 v121, 31, v120
	v_lshlrev_b64 v[48:49], 11, v[120:121]
	v_lshl_add_u64 v[48:49], s[20:21], 0, v[48:49]
	v_lshl_add_u64 v[48:49], v[48:49], 0, v[134:135]
	global_store_dwordx4 v[48:49], v[0:3], off offset:256
	s_nop 1
	v_cvt_pk_bf16_f32 v2, v47, v40
	v_cvt_pk_bf16_f32 v3, v41, v42
	v_cvt_pk_bf16_f32 v0, v51, v44
	v_cvt_pk_bf16_f32 v1, v45, v46
	v_ashrrev_i32_e32 v113, 31, v112
	v_lshlrev_b64 v[40:41], 11, v[112:113]
	v_lshl_add_u64 v[40:41], s[20:21], 0, v[40:41]
	v_lshl_add_u64 v[40:41], v[40:41], 0, v[134:135]
	global_store_dwordx4 v[40:41], v[0:3], off offset:256
	s_nop 1
	v_cvt_pk_bf16_f32 v2, v39, v32
	v_cvt_pk_bf16_f32 v3, v33, v34
	v_cvt_pk_bf16_f32 v0, v43, v36
	v_cvt_pk_bf16_f32 v1, v37, v38
	v_ashrrev_i32_e32 v105, 31, v104
	v_lshlrev_b64 v[32:33], 11, v[104:105]
	v_lshl_add_u64 v[32:33], s[20:21], 0, v[32:33]
	v_lshl_add_u64 v[32:33], v[32:33], 0, v[134:135]
	global_store_dwordx4 v[32:33], v[0:3], off offset:256
	s_nop 1
	v_cvt_pk_bf16_f32 v2, v31, v24
	v_cvt_pk_bf16_f32 v3, v25, v26
	v_cvt_pk_bf16_f32 v0, v35, v28
	v_cvt_pk_bf16_f32 v1, v29, v30
	v_ashrrev_i32_e32 v97, 31, v96
	v_lshlrev_b64 v[24:25], 11, v[96:97]
	v_lshl_add_u64 v[24:25], s[20:21], 0, v[24:25]
	v_lshl_add_u64 v[24:25], v[24:25], 0, v[134:135]
	global_store_dwordx4 v[24:25], v[0:3], off offset:256
	s_nop 1
	v_cvt_pk_bf16_f32 v2, v23, v16
	v_cvt_pk_bf16_f32 v3, v17, v18
	v_cvt_pk_bf16_f32 v0, v27, v20
	v_cvt_pk_bf16_f32 v1, v21, v22
	v_ashrrev_i32_e32 v89, 31, v88
	v_lshlrev_b64 v[16:17], 11, v[88:89]
	v_lshl_add_u64 v[16:17], s[20:21], 0, v[16:17]
	v_lshl_add_u64 v[16:17], v[16:17], 0, v[134:135]
	global_store_dwordx4 v[16:17], v[0:3], off offset:256
	s_nop 1
	v_cvt_pk_bf16_f32 v2, v15, v8
	v_cvt_pk_bf16_f32 v3, v9, v10
	v_cvt_pk_bf16_f32 v0, v19, v12
	v_cvt_pk_bf16_f32 v1, v13, v14
	v_ashrrev_i32_e32 v81, 31, v80
	v_lshlrev_b64 v[8:9], 11, v[80:81]
	v_lshl_add_u64 v[8:9], s[20:21], 0, v[8:9]
	v_lshl_add_u64 v[8:9], v[8:9], 0, v[134:135]
	global_store_dwordx4 v[8:9], v[0:3], off offset:256
	s_nop 1
	v_cvt_pk_bf16_f32 v0, v11, v4
	v_cvt_pk_bf16_f32 v1, v5, v6
	v_cvt_pk_bf16_f32 v2, v138, v7
	v_cvt_pk_bf16_f32 v3, v152, v153
	v_ashrrev_i32_e32 v73, 31, v72
	v_lshlrev_b64 v[4:5], 11, v[72:73]
	v_lshl_add_u64 v[4:5], s[20:21], 0, v[4:5]
	v_lshl_add_u64 v[4:5], v[4:5], 0, v[134:135]
	global_store_dwordx4 v[4:5], v[0:3], off offset:256
	s_and_b64 vcc, exec, s[12:13]
	s_mov_b32 s18, s76
	s_mov_b32 s41, s10
	s_mov_b64 s[2:3], s[16:17]
	s_mov_b64 s[20:21], s[14:15]
	s_cbranch_vccz .LBB0_489
	v_readlane_b32 s2, v249, 43
	s_waitcnt vmcnt(0)
	v_readlane_b32 s3, v249, 44
	s_andn2_b64 vcc, exec, s[2:3]
	s_cbranch_vccnz .LBB0_500
	s_barrier
